# spv1 priority + removed redundant v_max canonicalisations in attention softmax max-trees
# speedup vs baseline: 1.0290x; 1.0050x over previous
.LBB0_723:
	s_andn2_b64 vcc, exec, s[0:1]
	s_cbranch_vccnz .LBB0_729
	s_nop 8
	v_max_f32_e32 v142, v50, v51
	v_max3_f32 v142, v142, v52, v53
	v_max3_f32 v142, v142, v54, v55
	v_max3_f32 v142, v142, v56, v57
	v_max3_f32 v142, v142, v58, v59
	v_max3_f32 v142, v142, v60, v61
	v_max3_f32 v142, v142, v62, v63
	v_max3_f32 v142, v142, v64, v65
	v_mov_b32_e32 v143, v142
	s_nop 1
	v_permlane32_swap_b32_e32 v142, v143
	v_max_f32_e32 v142, v142, v143
	s_cmp_eq_u32 s91, 0
	s_cselect_b64 s[0:1], -1, 0
	v_cmp_lt_f32_e32 vcc, s8, v142
	s_or_b64 vcc, s[0:1], vcc
	s_cbranch_vccz .LBB0_726
	v_max_f32_e32 v143, v142, v142
	v_max_f32_e32 v143, 0, v143
	v_cndmask_b32_e64 v142, v143, v142, s[0:1]
	v_exp_f32_e64 v143, -v142
	v_add_f32_e32 v137, v137, v142
	v_sub_f32_e32 v81, v81, v142
	v_sub_f32_e32 v80, v80, v142
	v_cndmask_b32_e64 v144, v143, 1.0, s[0:1]
	v_pk_add_f32 v[50:51], v[50:51], v[142:143] op_sel_hi:[1,0] neg_lo:[0,1] neg_hi:[0,1]
	v_pk_add_f32 v[52:53], v[52:53], v[142:143] op_sel_hi:[1,0] neg_lo:[0,1] neg_hi:[0,1]
	v_mul_f32_e32 v34, v34, v144
	v_pk_add_f32 v[54:55], v[54:55], v[142:143] op_sel_hi:[1,0] neg_lo:[0,1] neg_hi:[0,1]
	v_pk_add_f32 v[56:57], v[56:57], v[142:143] op_sel_hi:[1,0] neg_lo:[0,1] neg_hi:[0,1]
	v_pk_add_f32 v[58:59], v[58:59], v[142:143] op_sel_hi:[1,0] neg_lo:[0,1] neg_hi:[0,1]
	v_pk_add_f32 v[60:61], v[60:61], v[142:143] op_sel_hi:[1,0] neg_lo:[0,1] neg_hi:[0,1]
	v_pk_add_f32 v[62:63], v[62:63], v[142:143] op_sel_hi:[1,0] neg_lo:[0,1] neg_hi:[0,1]
	v_pk_add_f32 v[64:65], v[64:65], v[142:143] op_sel_hi:[1,0] neg_lo:[0,1] neg_hi:[0,1]
	v_sub_f32_e32 v79, v79, v142
	v_sub_f32_e32 v78, v78, v142
	v_sub_f32_e32 v77, v77, v142
	v_sub_f32_e32 v76, v76, v142
	v_sub_f32_e32 v75, v75, v142
	v_sub_f32_e32 v74, v74, v142
	v_sub_f32_e32 v73, v73, v142
	v_sub_f32_e32 v72, v72, v142
	v_sub_f32_e32 v71, v71, v142
	v_sub_f32_e32 v70, v70, v142
	v_sub_f32_e32 v69, v69, v142
	v_sub_f32_e32 v68, v68, v142
	v_sub_f32_e32 v67, v67, v142
	v_sub_f32_e32 v66, v66, v142
	v_pk_mul_f32 v[32:33], v[32:33], v[144:145] op_sel_hi:[1,0]
	v_pk_mul_f32 v[30:31], v[30:31], v[144:145] op_sel_hi:[1,0]
	v_pk_mul_f32 v[28:29], v[28:29], v[144:145] op_sel_hi:[1,0]
	v_pk_mul_f32 v[26:27], v[26:27], v[144:145] op_sel_hi:[1,0]
	v_pk_mul_f32 v[24:25], v[24:25], v[144:145] op_sel_hi:[1,0]
	v_pk_mul_f32 v[22:23], v[22:23], v[144:145] op_sel_hi:[1,0]
	v_pk_mul_f32 v[20:21], v[20:21], v[144:145] op_sel_hi:[1,0]
	v_pk_mul_f32 v[18:19], v[18:19], v[144:145] op_sel_hi:[1,0]
	v_pk_mul_f32 v[16:17], v[16:17], v[144:145] op_sel_hi:[1,0]
	v_pk_mul_f32 v[14:15], v[14:15], v[144:145] op_sel_hi:[1,0]
	v_pk_mul_f32 v[12:13], v[12:13], v[144:145] op_sel_hi:[1,0]
	v_pk_mul_f32 v[10:11], v[10:11], v[144:145] op_sel_hi:[1,0]
	v_pk_mul_f32 v[8:9], v[8:9], v[144:145] op_sel_hi:[1,0]
	v_pk_mul_f32 v[6:7], v[6:7], v[144:145] op_sel_hi:[1,0]
	v_pk_mul_f32 v[4:5], v[4:5], v[144:145] op_sel_hi:[1,0]
	v_pk_mul_f32 v[2:3], v[2:3], v[144:145] op_sel_hi:[1,0]
.LBB0_726:
	v_add_u32_e32 v142, s11, v127
	v_add_u32_e32 v143, v142, v128
	v_exp_f32_e32 v50, v50
	v_exp_f32_e32 v51, v51
	v_exp_f32_e32 v52, v52
	v_exp_f32_e32 v53, v53
	ds_read_b64_tr_b16 v[144:145], v143 offset:16384
	ds_read_b64_tr_b16 v[146:147], v143 offset:17408
	v_exp_f32_e32 v54, v54
	v_exp_f32_e32 v55, v55
	v_exp_f32_e32 v56, v56
	v_exp_f32_e32 v57, v57
	v_cvt_pk_bf16_f32 v148, v50, v51
	v_cvt_pk_bf16_f32 v149, v52, v53
	v_cvt_pk_bf16_f32 v150, v54, v55
	v_cvt_pk_bf16_f32 v151, v56, v57
	v_add_u32_e32 v142, v142, v129
	v_exp_f32_e32 v58, v58
	s_waitcnt lgkmcnt(0)
	v_mfma_f32_32x32x16_bf16 v[2:17], v[144:147], v[148:151], v[2:17]
	ds_read_b64_tr_b16 v[144:145], v142 offset:16384
	ds_read_b64_tr_b16 v[146:147], v142 offset:17408
	v_exp_f32_e32 v59, v59
	v_exp_f32_e32 v60, v60
	v_exp_f32_e32 v61, v61
	v_exp_f32_e32 v62, v62
	v_exp_f32_e32 v63, v63
	v_exp_f32_e32 v64, v64
	s_waitcnt lgkmcnt(0)
	v_mfma_f32_32x32x16_bf16 v[18:33], v[144:147], v[148:151], v[18:33]
	ds_read_b64_tr_b16 v[144:145], v143 offset:18432
	ds_read_b64_tr_b16 v[146:147], v143 offset:19456
	v_exp_f32_e32 v65, v65
	v_mfma_f32_32x32x16_bf16 v[34:49], v[82:85], v[148:151], v[34:49]
	v_cvt_pk_bf16_f32 v148, v58, v59
	v_cvt_pk_bf16_f32 v149, v60, v61
	v_cvt_pk_bf16_f32 v150, v62, v63
	v_cvt_pk_bf16_f32 v151, v64, v65
	s_waitcnt lgkmcnt(0)
	s_nop 0
	v_mfma_f32_32x32x16_bf16 v[2:17], v[144:147], v[148:151], v[2:17]
	ds_read_b64_tr_b16 v[144:145], v142 offset:18432
	ds_read_b64_tr_b16 v[146:147], v142 offset:19456
	s_waitcnt lgkmcnt(0)
	v_mfma_f32_32x32x16_bf16 v[18:33], v[144:147], v[148:151], v[18:33]
	v_max_f32_e32 v144, v66, v67
	v_max3_f32 v144, v144, v68, v69
	v_max3_f32 v144, v144, v70, v71
	v_max3_f32 v144, v144, v72, v73
	v_max3_f32 v144, v144, v74, v75
	v_max3_f32 v144, v144, v76, v77
	v_mfma_f32_32x32x16_bf16 v[34:49], v[82:85], v[148:151], v[34:49]
	v_max3_f32 v144, v144, v78, v79
	v_max3_f32 v144, v144, v80, v81
	v_mov_b32_e32 v145, v144
	s_nop 1
	v_permlane32_swap_b32_e32 v144, v145
	v_max_f32_e32 v144, v144, v145
	v_cmp_lt_f32_e32 vcc, s8, v144
	s_cbranch_vccz .LBB0_728
	v_max_f32_e32 v144, v144, v144
	v_max_f32_e32 v144, 0, v144
	v_exp_f32_e64 v146, -v144
	v_add_f32_e32 v137, v137, v144
	v_pk_add_f32 v[66:67], v[66:67], v[144:145] op_sel_hi:[1,0] neg_lo:[0,1] neg_hi:[0,1]
	v_pk_add_f32 v[68:69], v[68:69], v[144:145] op_sel_hi:[1,0] neg_lo:[0,1] neg_hi:[0,1]
	v_mul_f32_e32 v34, v34, v146
	v_pk_add_f32 v[70:71], v[70:71], v[144:145] op_sel_hi:[1,0] neg_lo:[0,1] neg_hi:[0,1]
	v_pk_add_f32 v[72:73], v[72:73], v[144:145] op_sel_hi:[1,0] neg_lo:[0,1] neg_hi:[0,1]
	v_pk_add_f32 v[74:75], v[74:75], v[144:145] op_sel_hi:[1,0] neg_lo:[0,1] neg_hi:[0,1]
	v_pk_add_f32 v[76:77], v[76:77], v[144:145] op_sel_hi:[1,0] neg_lo:[0,1] neg_hi:[0,1]
	v_pk_add_f32 v[78:79], v[78:79], v[144:145] op_sel_hi:[1,0] neg_lo:[0,1] neg_hi:[0,1]
	v_pk_add_f32 v[80:81], v[80:81], v[144:145] op_sel_hi:[1,0] neg_lo:[0,1] neg_hi:[0,1]
	v_pk_mul_f32 v[32:33], v[32:33], v[146:147] op_sel_hi:[1,0]
	v_pk_mul_f32 v[30:31], v[30:31], v[146:147] op_sel_hi:[1,0]
	v_pk_mul_f32 v[28:29], v[28:29], v[146:147] op_sel_hi:[1,0]
	v_pk_mul_f32 v[26:27], v[26:27], v[146:147] op_sel_hi:[1,0]
	v_pk_mul_f32 v[24:25], v[24:25], v[146:147] op_sel_hi:[1,0]
	v_pk_mul_f32 v[22:23], v[22:23], v[146:147] op_sel_hi:[1,0]
	v_pk_mul_f32 v[20:21], v[20:21], v[146:147] op_sel_hi:[1,0]
	v_pk_mul_f32 v[18:19], v[18:19], v[146:147] op_sel_hi:[1,0]
	v_pk_mul_f32 v[16:17], v[16:17], v[146:147] op_sel_hi:[1,0]
	v_pk_mul_f32 v[14:15], v[14:15], v[146:147] op_sel_hi:[1,0]
	v_pk_mul_f32 v[12:13], v[12:13], v[146:147] op_sel_hi:[1,0]
	v_pk_mul_f32 v[10:11], v[10:11], v[146:147] op_sel_hi:[1,0]
	v_pk_mul_f32 v[8:9], v[8:9], v[146:147] op_sel_hi:[1,0]
	v_pk_mul_f32 v[6:7], v[6:7], v[146:147] op_sel_hi:[1,0]
	v_pk_mul_f32 v[4:5], v[4:5], v[146:147] op_sel_hi:[1,0]
	v_pk_mul_f32 v[2:3], v[2:3], v[146:147] op_sel_hi:[1,0]

.LBB0_732:
	s_andn2_b64 vcc, exec, s[0:1]
	s_cbranch_vccnz .LBB0_738
	s_nop 8
	v_max_f32_e32 v0, v50, v51
	v_max3_f32 v0, v0, v52, v53
	v_max3_f32 v0, v0, v54, v55
	v_max3_f32 v0, v0, v56, v57
	v_max3_f32 v0, v0, v58, v59
	v_max3_f32 v0, v0, v60, v61
	v_max3_f32 v0, v0, v62, v63
	v_max3_f32 v0, v0, v64, v65
	v_mov_b32_e32 v138, v0
	s_nop 1
	v_permlane32_swap_b32_e32 v0, v138
	v_max_f32_e32 v0, v0, v138
	v_cmp_lt_f32_e32 vcc, s8, v0
	s_cbranch_vccz .LBB0_735
	v_max_f32_e32 v0, v0, v0
	v_max_f32_e32 v0, 0, v0
	v_exp_f32_e64 v138, -v0
	v_add_f32_e32 v137, v137, v0
	v_pk_add_f32 v[50:51], v[50:51], v[0:1] op_sel_hi:[1,0] neg_lo:[0,1] neg_hi:[0,1]
	v_pk_add_f32 v[52:53], v[52:53], v[0:1] op_sel_hi:[1,0] neg_lo:[0,1] neg_hi:[0,1]
	v_mul_f32_e32 v34, v34, v138
	v_pk_add_f32 v[54:55], v[54:55], v[0:1] op_sel_hi:[1,0] neg_lo:[0,1] neg_hi:[0,1]
	v_pk_add_f32 v[56:57], v[56:57], v[0:1] op_sel_hi:[1,0] neg_lo:[0,1] neg_hi:[0,1]
	v_pk_add_f32 v[58:59], v[58:59], v[0:1] op_sel_hi:[1,0] neg_lo:[0,1] neg_hi:[0,1]
	v_pk_add_f32 v[60:61], v[60:61], v[0:1] op_sel_hi:[1,0] neg_lo:[0,1] neg_hi:[0,1]
	v_pk_add_f32 v[62:63], v[62:63], v[0:1] op_sel_hi:[1,0] neg_lo:[0,1] neg_hi:[0,1]
	v_pk_add_f32 v[64:65], v[64:65], v[0:1] op_sel_hi:[1,0] neg_lo:[0,1] neg_hi:[0,1]
	v_sub_f32_e32 v81, v81, v0
	v_sub_f32_e32 v80, v80, v0
	v_sub_f32_e32 v79, v79, v0
	v_sub_f32_e32 v78, v78, v0
	v_sub_f32_e32 v77, v77, v0
	v_sub_f32_e32 v76, v76, v0
	v_sub_f32_e32 v75, v75, v0
	v_sub_f32_e32 v74, v74, v0
	v_sub_f32_e32 v73, v73, v0
	v_sub_f32_e32 v72, v72, v0
	v_sub_f32_e32 v71, v71, v0
	v_sub_f32_e32 v70, v70, v0
	v_sub_f32_e32 v69, v69, v0
	v_sub_f32_e32 v68, v68, v0
	v_sub_f32_e32 v67, v67, v0
	v_sub_f32_e32 v66, v66, v0
	v_pk_mul_f32 v[32:33], v[32:33], v[138:139] op_sel_hi:[1,0]
	v_pk_mul_f32 v[30:31], v[30:31], v[138:139] op_sel_hi:[1,0]
	v_pk_mul_f32 v[28:29], v[28:29], v[138:139] op_sel_hi:[1,0]
	v_pk_mul_f32 v[26:27], v[26:27], v[138:139] op_sel_hi:[1,0]
	v_pk_mul_f32 v[24:25], v[24:25], v[138:139] op_sel_hi:[1,0]
	v_pk_mul_f32 v[22:23], v[22:23], v[138:139] op_sel_hi:[1,0]
	v_pk_mul_f32 v[20:21], v[20:21], v[138:139] op_sel_hi:[1,0]
	v_pk_mul_f32 v[18:19], v[18:19], v[138:139] op_sel_hi:[1,0]
	v_pk_mul_f32 v[16:17], v[16:17], v[138:139] op_sel_hi:[1,0]
	v_pk_mul_f32 v[14:15], v[14:15], v[138:139] op_sel_hi:[1,0]
	v_pk_mul_f32 v[12:13], v[12:13], v[138:139] op_sel_hi:[1,0]
	v_pk_mul_f32 v[10:11], v[10:11], v[138:139] op_sel_hi:[1,0]
	v_pk_mul_f32 v[8:9], v[8:9], v[138:139] op_sel_hi:[1,0]
	v_pk_mul_f32 v[6:7], v[6:7], v[138:139] op_sel_hi:[1,0]
	v_pk_mul_f32 v[4:5], v[4:5], v[138:139] op_sel_hi:[1,0]
	v_pk_mul_f32 v[2:3], v[2:3], v[138:139] op_sel_hi:[1,0]
.LBB0_735:
	v_add_u32_e32 v0, s11, v127
	v_add_u32_e32 v138, v0, v128
	v_exp_f32_e32 v50, v50
	v_exp_f32_e32 v51, v51
	v_exp_f32_e32 v52, v52
	v_exp_f32_e32 v53, v53
	ds_read_b64_tr_b16 v[140:141], v138 offset:24576
	ds_read_b64_tr_b16 v[142:143], v138 offset:25600
	v_exp_f32_e32 v54, v54
	v_exp_f32_e32 v55, v55
	v_exp_f32_e32 v56, v56
	v_exp_f32_e32 v57, v57
	v_cvt_pk_bf16_f32 v144, v50, v51
	v_cvt_pk_bf16_f32 v145, v52, v53
	v_cvt_pk_bf16_f32 v146, v54, v55
	v_cvt_pk_bf16_f32 v147, v56, v57
	v_add_u32_e32 v0, v0, v129
	v_exp_f32_e32 v58, v58
	s_waitcnt lgkmcnt(0)
	v_mfma_f32_32x32x16_bf16 v[2:17], v[140:143], v[144:147], v[2:17]
	ds_read_b64_tr_b16 v[140:141], v0 offset:24576
	ds_read_b64_tr_b16 v[142:143], v0 offset:25600
	v_exp_f32_e32 v59, v59
	v_exp_f32_e32 v60, v60
	v_exp_f32_e32 v61, v61
	v_exp_f32_e32 v62, v62
	v_exp_f32_e32 v63, v63
	v_exp_f32_e32 v64, v64
	s_waitcnt lgkmcnt(0)
	v_mfma_f32_32x32x16_bf16 v[18:33], v[140:143], v[144:147], v[18:33]
	ds_read_b64_tr_b16 v[140:141], v138 offset:26624
	ds_read_b64_tr_b16 v[142:143], v138 offset:27648
	v_exp_f32_e32 v65, v65
	v_max_f32_e32 v139, v67, v67
	v_mfma_f32_32x32x16_bf16 v[34:49], v[82:85], v[144:147], v[34:49]
	v_cvt_pk_bf16_f32 v144, v58, v59
	v_cvt_pk_bf16_f32 v145, v60, v61
	v_cvt_pk_bf16_f32 v146, v62, v63
	v_cvt_pk_bf16_f32 v147, v64, v65
	s_waitcnt lgkmcnt(0)
	s_nop 0
	v_mfma_f32_32x32x16_bf16 v[2:17], v[140:143], v[144:147], v[2:17]
	ds_read_b64_tr_b16 v[140:141], v0 offset:26624
	ds_read_b64_tr_b16 v[142:143], v0 offset:27648
	s_waitcnt lgkmcnt(0)
	v_mfma_f32_32x32x16_bf16 v[18:33], v[140:143], v[144:147], v[18:33]
	v_max_f32_e32 v140, v66, v66
	v_max_f32_e32 v139, v140, v139
	v_max3_f32 v139, v139, v68, v69
	v_max3_f32 v139, v139, v70, v71
	v_max3_f32 v139, v139, v72, v73
	v_max3_f32 v139, v139, v74, v75
	v_max3_f32 v139, v139, v76, v77
	v_mfma_f32_32x32x16_bf16 v[34:49], v[82:85], v[144:147], v[34:49]
	v_max3_f32 v139, v139, v78, v79
	v_max3_f32 v139, v139, v80, v81
	v_mov_b32_e32 v140, v139
	s_nop 1
	v_permlane32_swap_b32_e32 v139, v140
	v_max_f32_e32 v139, v139, v140
	v_cmp_lt_f32_e32 vcc, s8, v139
	s_cbranch_vccz .LBB0_737
	v_max_f32_e32 v139, v139, v139
	v_max_f32_e32 v140, 0, v139
	v_exp_f32_e64 v142, -v140
	v_add_f32_e32 v137, v137, v140
	v_pk_add_f32 v[66:67], v[66:67], v[140:141] op_sel_hi:[1,0] neg_lo:[0,1] neg_hi:[0,1]
	v_pk_add_f32 v[68:69], v[68:69], v[140:141] op_sel_hi:[1,0] neg_lo:[0,1] neg_hi:[0,1]
	v_mul_f32_e32 v34, v34, v142
	v_pk_add_f32 v[70:71], v[70:71], v[140:141] op_sel_hi:[1,0] neg_lo:[0,1] neg_hi:[0,1]
	v_pk_add_f32 v[72:73], v[72:73], v[140:141] op_sel_hi:[1,0] neg_lo:[0,1] neg_hi:[0,1]
	v_pk_add_f32 v[74:75], v[74:75], v[140:141] op_sel_hi:[1,0] neg_lo:[0,1] neg_hi:[0,1]
	v_pk_add_f32 v[76:77], v[76:77], v[140:141] op_sel_hi:[1,0] neg_lo:[0,1] neg_hi:[0,1]
	v_pk_add_f32 v[78:79], v[78:79], v[140:141] op_sel_hi:[1,0] neg_lo:[0,1] neg_hi:[0,1]
	v_pk_add_f32 v[80:81], v[80:81], v[140:141] op_sel_hi:[1,0] neg_lo:[0,1] neg_hi:[0,1]
	v_pk_mul_f32 v[32:33], v[32:33], v[142:143] op_sel_hi:[1,0]
	v_pk_mul_f32 v[30:31], v[30:31], v[142:143] op_sel_hi:[1,0]
	v_pk_mul_f32 v[28:29], v[28:29], v[142:143] op_sel_hi:[1,0]
	v_pk_mul_f32 v[26:27], v[26:27], v[142:143] op_sel_hi:[1,0]
	v_pk_mul_f32 v[24:25], v[24:25], v[142:143] op_sel_hi:[1,0]
	v_pk_mul_f32 v[22:23], v[22:23], v[142:143] op_sel_hi:[1,0]
	v_pk_mul_f32 v[20:21], v[20:21], v[142:143] op_sel_hi:[1,0]
	v_pk_mul_f32 v[18:19], v[18:19], v[142:143] op_sel_hi:[1,0]
	v_pk_mul_f32 v[16:17], v[16:17], v[142:143] op_sel_hi:[1,0]
	v_pk_mul_f32 v[14:15], v[14:15], v[142:143] op_sel_hi:[1,0]
	v_pk_mul_f32 v[12:13], v[12:13], v[142:143] op_sel_hi:[1,0]
	v_pk_mul_f32 v[10:11], v[10:11], v[142:143] op_sel_hi:[1,0]
	v_pk_mul_f32 v[8:9], v[8:9], v[142:143] op_sel_hi:[1,0]
	v_pk_mul_f32 v[6:7], v[6:7], v[142:143] op_sel_hi:[1,0]
	v_pk_mul_f32 v[4:5], v[4:5], v[142:143] op_sel_hi:[1,0]
	v_pk_mul_f32 v[2:3], v[2:3], v[142:143] op_sel_hi:[1,0]

.LBB0_753:
	s_andn2_b64 vcc, exec, s[0:1]
	s_cbranch_vccnz .LBB0_759
	s_nop 8
	v_max_f32_e32 v121, v50, v51
	v_max3_f32 v121, v121, v52, v53
	v_max3_f32 v121, v121, v54, v55
	v_max3_f32 v121, v121, v56, v57
	v_max3_f32 v121, v121, v58, v59
	v_max3_f32 v121, v121, v60, v61
	v_max3_f32 v121, v121, v62, v63
	v_max3_f32 v121, v121, v64, v65
	v_mov_b32_e32 v122, v121
	s_nop 1
	v_permlane32_swap_b32_e32 v121, v122
	v_max_f32_e32 v121, v121, v122
	s_cmp_eq_u32 s70, 0
	s_cselect_b64 s[0:1], -1, 0
	v_cmp_lt_f32_e32 vcc, s95, v121
	s_or_b64 vcc, s[0:1], vcc
	s_cbranch_vccz .LBB0_756
	v_max_f32_e32 v122, v121, v121
	v_max_f32_e32 v122, 0, v122
	v_cndmask_b32_e64 v122, v122, v121, s[0:1]
	v_exp_f32_e64 v121, -v122
	v_add_f32_e32 v116, v116, v122
	v_pk_add_f32 v[50:51], v[50:51], v[122:123] op_sel_hi:[1,0] neg_lo:[0,1] neg_hi:[0,1]
	v_pk_add_f32 v[52:53], v[52:53], v[122:123] op_sel_hi:[1,0] neg_lo:[0,1] neg_hi:[0,1]
	v_cndmask_b32_e64 v136, v121, 1.0, s[0:1]
	v_mul_f32_e32 v34, v34, v136
	v_pk_add_f32 v[54:55], v[54:55], v[122:123] op_sel_hi:[1,0] neg_lo:[0,1] neg_hi:[0,1]
	v_pk_add_f32 v[56:57], v[56:57], v[122:123] op_sel_hi:[1,0] neg_lo:[0,1] neg_hi:[0,1]
	v_pk_add_f32 v[58:59], v[58:59], v[122:123] op_sel_hi:[1,0] neg_lo:[0,1] neg_hi:[0,1]
	v_pk_add_f32 v[60:61], v[60:61], v[122:123] op_sel_hi:[1,0] neg_lo:[0,1] neg_hi:[0,1]
	v_pk_add_f32 v[62:63], v[62:63], v[122:123] op_sel_hi:[1,0] neg_lo:[0,1] neg_hi:[0,1]
	v_pk_add_f32 v[64:65], v[64:65], v[122:123] op_sel_hi:[1,0] neg_lo:[0,1] neg_hi:[0,1]
	v_sub_f32_e32 v81, v81, v122
	v_sub_f32_e32 v80, v80, v122
	v_sub_f32_e32 v79, v79, v122
	v_sub_f32_e32 v78, v78, v122
	v_sub_f32_e32 v77, v77, v122
	v_sub_f32_e32 v76, v76, v122
	v_sub_f32_e32 v75, v75, v122
	v_sub_f32_e32 v74, v74, v122
	v_sub_f32_e32 v73, v73, v122
	v_sub_f32_e32 v72, v72, v122
	v_sub_f32_e32 v71, v71, v122
	v_sub_f32_e32 v70, v70, v122
	v_sub_f32_e32 v69, v69, v122
	v_sub_f32_e32 v68, v68, v122
	v_sub_f32_e32 v67, v67, v122
	v_sub_f32_e32 v66, v66, v122
	v_pk_mul_f32 v[32:33], v[32:33], v[136:137] op_sel_hi:[1,0]
	v_pk_mul_f32 v[30:31], v[30:31], v[136:137] op_sel_hi:[1,0]
	v_pk_mul_f32 v[28:29], v[28:29], v[136:137] op_sel_hi:[1,0]
	v_pk_mul_f32 v[26:27], v[26:27], v[136:137] op_sel_hi:[1,0]
	v_pk_mul_f32 v[24:25], v[24:25], v[136:137] op_sel_hi:[1,0]
	v_pk_mul_f32 v[22:23], v[22:23], v[136:137] op_sel_hi:[1,0]
	v_pk_mul_f32 v[20:21], v[20:21], v[136:137] op_sel_hi:[1,0]
	v_pk_mul_f32 v[18:19], v[18:19], v[136:137] op_sel_hi:[1,0]
	v_pk_mul_f32 v[16:17], v[16:17], v[136:137] op_sel_hi:[1,0]
	v_pk_mul_f32 v[14:15], v[14:15], v[136:137] op_sel_hi:[1,0]
	v_pk_mul_f32 v[12:13], v[12:13], v[136:137] op_sel_hi:[1,0]
	v_pk_mul_f32 v[10:11], v[10:11], v[136:137] op_sel_hi:[1,0]
	v_pk_mul_f32 v[8:9], v[8:9], v[136:137] op_sel_hi:[1,0]
	v_pk_mul_f32 v[6:7], v[6:7], v[136:137] op_sel_hi:[1,0]
	v_pk_mul_f32 v[4:5], v[4:5], v[136:137] op_sel_hi:[1,0]
	v_pk_mul_f32 v[2:3], v[2:3], v[136:137] op_sel_hi:[1,0]
.LBB0_756:
	v_add_u32_e32 v121, s91, v129
	v_add_u32_e32 v122, v121, v130
	v_exp_f32_e32 v50, v50
	v_exp_f32_e32 v51, v51
	v_exp_f32_e32 v52, v52
	v_exp_f32_e32 v53, v53
	ds_read_b64_tr_b16 v[136:137], v122 offset:16384
	ds_read_b64_tr_b16 v[138:139], v122 offset:17408
	v_exp_f32_e32 v54, v54
	v_exp_f32_e32 v55, v55
	v_exp_f32_e32 v56, v56
	v_exp_f32_e32 v57, v57
	v_cvt_pk_bf16_f32 v140, v50, v51
	v_cvt_pk_bf16_f32 v141, v52, v53
	v_cvt_pk_bf16_f32 v142, v54, v55
	v_cvt_pk_bf16_f32 v143, v56, v57
	v_add_u32_e32 v121, v121, v131
	v_exp_f32_e32 v58, v58
	s_waitcnt lgkmcnt(0)
	v_mfma_f32_32x32x16_bf16 v[2:17], v[136:139], v[140:143], v[2:17]
	ds_read_b64_tr_b16 v[136:137], v121 offset:16384
	ds_read_b64_tr_b16 v[138:139], v121 offset:17408
	v_exp_f32_e32 v59, v59
	v_exp_f32_e32 v60, v60
	v_exp_f32_e32 v61, v61
	v_exp_f32_e32 v62, v62
	v_exp_f32_e32 v63, v63
	v_exp_f32_e32 v64, v64
	s_waitcnt lgkmcnt(0)
	v_mfma_f32_32x32x16_bf16 v[18:33], v[136:139], v[140:143], v[18:33]
	ds_read_b64_tr_b16 v[136:137], v122 offset:18432
	ds_read_b64_tr_b16 v[138:139], v122 offset:19456
	v_exp_f32_e32 v65, v65
	v_max_f32_e32 v123, v67, v67
	v_mfma_f32_32x32x16_bf16 v[34:49], v[84:87], v[140:143], v[34:49]
	v_cvt_pk_bf16_f32 v140, v58, v59
	v_cvt_pk_bf16_f32 v141, v60, v61
	v_cvt_pk_bf16_f32 v142, v62, v63
	v_cvt_pk_bf16_f32 v143, v64, v65
	s_waitcnt lgkmcnt(0)
	s_nop 0
	v_mfma_f32_32x32x16_bf16 v[2:17], v[136:139], v[140:143], v[2:17]
	ds_read_b64_tr_b16 v[136:137], v121 offset:18432
	ds_read_b64_tr_b16 v[138:139], v121 offset:19456
	s_waitcnt lgkmcnt(0)
	v_mfma_f32_32x32x16_bf16 v[18:33], v[136:139], v[140:143], v[18:33]
	v_max_f32_e32 v136, v66, v66
	v_max_f32_e32 v123, v136, v123
	v_max3_f32 v123, v123, v68, v69
	v_max3_f32 v123, v123, v70, v71
	v_max3_f32 v123, v123, v72, v73
	v_max3_f32 v123, v123, v74, v75
	v_max3_f32 v123, v123, v76, v77
	v_mfma_f32_32x32x16_bf16 v[34:49], v[84:87], v[140:143], v[34:49]
	v_max3_f32 v123, v123, v78, v79
	v_max3_f32 v123, v123, v80, v81
	v_mov_b32_e32 v136, v123
	s_nop 1
	v_permlane32_swap_b32_e32 v123, v136
	v_max_f32_e32 v123, v123, v136
	v_cmp_lt_f32_e32 vcc, s95, v123
	s_cbranch_vccz .LBB0_758
	v_max_f32_e32 v123, v123, v123
	v_max_f32_e32 v136, 0, v123
	v_exp_f32_e64 v138, -v136
	v_add_f32_e32 v116, v116, v136
	v_pk_add_f32 v[66:67], v[66:67], v[136:137] op_sel_hi:[1,0] neg_lo:[0,1] neg_hi:[0,1]
	v_pk_add_f32 v[68:69], v[68:69], v[136:137] op_sel_hi:[1,0] neg_lo:[0,1] neg_hi:[0,1]
	v_mul_f32_e32 v34, v34, v138
	v_pk_add_f32 v[70:71], v[70:71], v[136:137] op_sel_hi:[1,0] neg_lo:[0,1] neg_hi:[0,1]
	v_pk_add_f32 v[72:73], v[72:73], v[136:137] op_sel_hi:[1,0] neg_lo:[0,1] neg_hi:[0,1]
	v_pk_add_f32 v[74:75], v[74:75], v[136:137] op_sel_hi:[1,0] neg_lo:[0,1] neg_hi:[0,1]
	v_pk_add_f32 v[76:77], v[76:77], v[136:137] op_sel_hi:[1,0] neg_lo:[0,1] neg_hi:[0,1]
	v_pk_add_f32 v[78:79], v[78:79], v[136:137] op_sel_hi:[1,0] neg_lo:[0,1] neg_hi:[0,1]
	v_pk_add_f32 v[80:81], v[80:81], v[136:137] op_sel_hi:[1,0] neg_lo:[0,1] neg_hi:[0,1]
	v_pk_mul_f32 v[32:33], v[32:33], v[138:139] op_sel_hi:[1,0]
	v_pk_mul_f32 v[30:31], v[30:31], v[138:139] op_sel_hi:[1,0]
	v_pk_mul_f32 v[28:29], v[28:29], v[138:139] op_sel_hi:[1,0]
	v_pk_mul_f32 v[26:27], v[26:27], v[138:139] op_sel_hi:[1,0]
	v_pk_mul_f32 v[24:25], v[24:25], v[138:139] op_sel_hi:[1,0]
	v_pk_mul_f32 v[22:23], v[22:23], v[138:139] op_sel_hi:[1,0]
	v_pk_mul_f32 v[20:21], v[20:21], v[138:139] op_sel_hi:[1,0]
	v_pk_mul_f32 v[18:19], v[18:19], v[138:139] op_sel_hi:[1,0]
	v_pk_mul_f32 v[16:17], v[16:17], v[138:139] op_sel_hi:[1,0]
	v_pk_mul_f32 v[14:15], v[14:15], v[138:139] op_sel_hi:[1,0]
	v_pk_mul_f32 v[12:13], v[12:13], v[138:139] op_sel_hi:[1,0]
	v_pk_mul_f32 v[10:11], v[10:11], v[138:139] op_sel_hi:[1,0]
	v_pk_mul_f32 v[8:9], v[8:9], v[138:139] op_sel_hi:[1,0]
	v_pk_mul_f32 v[6:7], v[6:7], v[138:139] op_sel_hi:[1,0]
	v_pk_mul_f32 v[4:5], v[4:5], v[138:139] op_sel_hi:[1,0]
	v_pk_mul_f32 v[2:3], v[2:3], v[138:139] op_sel_hi:[1,0]

.LBB0_762:
	s_andn2_b64 vcc, exec, s[0:1]
	s_cbranch_vccnz .LBB0_768
	s_nop 8
	v_max_f32_e32 v0, v50, v51
	v_max3_f32 v0, v0, v52, v53
	v_max3_f32 v0, v0, v54, v55
	v_max3_f32 v0, v0, v56, v57
	v_max3_f32 v0, v0, v58, v59
	v_max3_f32 v0, v0, v60, v61
	v_max3_f32 v0, v0, v62, v63
	v_max3_f32 v0, v0, v64, v65
	v_mov_b32_e32 v117, v0
	s_nop 1
	v_permlane32_swap_b32_e32 v0, v117
	v_max_f32_e32 v0, v0, v117
	v_cmp_lt_f32_e32 vcc, s95, v0
	s_cbranch_vccz .LBB0_765
	v_max_f32_e32 v0, v0, v0
	v_max_f32_e32 v0, 0, v0
	v_exp_f32_e64 v118, -v0
	v_add_f32_e32 v116, v116, v0
	v_pk_add_f32 v[50:51], v[50:51], v[0:1] op_sel_hi:[1,0] neg_lo:[0,1] neg_hi:[0,1]
	v_pk_add_f32 v[52:53], v[52:53], v[0:1] op_sel_hi:[1,0] neg_lo:[0,1] neg_hi:[0,1]
	v_mul_f32_e32 v34, v34, v118
	v_pk_add_f32 v[54:55], v[54:55], v[0:1] op_sel_hi:[1,0] neg_lo:[0,1] neg_hi:[0,1]
	v_pk_add_f32 v[56:57], v[56:57], v[0:1] op_sel_hi:[1,0] neg_lo:[0,1] neg_hi:[0,1]
	v_pk_add_f32 v[58:59], v[58:59], v[0:1] op_sel_hi:[1,0] neg_lo:[0,1] neg_hi:[0,1]
	v_pk_add_f32 v[60:61], v[60:61], v[0:1] op_sel_hi:[1,0] neg_lo:[0,1] neg_hi:[0,1]
	v_pk_add_f32 v[62:63], v[62:63], v[0:1] op_sel_hi:[1,0] neg_lo:[0,1] neg_hi:[0,1]
	v_pk_add_f32 v[64:65], v[64:65], v[0:1] op_sel_hi:[1,0] neg_lo:[0,1] neg_hi:[0,1]
	v_sub_f32_e32 v81, v81, v0
	v_sub_f32_e32 v80, v80, v0
	v_sub_f32_e32 v79, v79, v0
	v_sub_f32_e32 v78, v78, v0
	v_sub_f32_e32 v77, v77, v0
	v_sub_f32_e32 v76, v76, v0
	v_sub_f32_e32 v75, v75, v0
	v_sub_f32_e32 v74, v74, v0
	v_sub_f32_e32 v73, v73, v0
	v_sub_f32_e32 v72, v72, v0
	v_sub_f32_e32 v71, v71, v0
	v_sub_f32_e32 v70, v70, v0
	v_sub_f32_e32 v69, v69, v0
	v_sub_f32_e32 v68, v68, v0
	v_sub_f32_e32 v67, v67, v0
	v_sub_f32_e32 v66, v66, v0
	v_pk_mul_f32 v[32:33], v[32:33], v[118:119] op_sel_hi:[1,0]
	v_pk_mul_f32 v[30:31], v[30:31], v[118:119] op_sel_hi:[1,0]
	v_pk_mul_f32 v[28:29], v[28:29], v[118:119] op_sel_hi:[1,0]
	v_pk_mul_f32 v[26:27], v[26:27], v[118:119] op_sel_hi:[1,0]
	v_pk_mul_f32 v[24:25], v[24:25], v[118:119] op_sel_hi:[1,0]
	v_pk_mul_f32 v[22:23], v[22:23], v[118:119] op_sel_hi:[1,0]
	v_pk_mul_f32 v[20:21], v[20:21], v[118:119] op_sel_hi:[1,0]
	v_pk_mul_f32 v[18:19], v[18:19], v[118:119] op_sel_hi:[1,0]
	v_pk_mul_f32 v[16:17], v[16:17], v[118:119] op_sel_hi:[1,0]
	v_pk_mul_f32 v[14:15], v[14:15], v[118:119] op_sel_hi:[1,0]
	v_pk_mul_f32 v[12:13], v[12:13], v[118:119] op_sel_hi:[1,0]
	v_pk_mul_f32 v[10:11], v[10:11], v[118:119] op_sel_hi:[1,0]
	v_pk_mul_f32 v[8:9], v[8:9], v[118:119] op_sel_hi:[1,0]
	v_pk_mul_f32 v[6:7], v[6:7], v[118:119] op_sel_hi:[1,0]
	v_pk_mul_f32 v[4:5], v[4:5], v[118:119] op_sel_hi:[1,0]
	v_pk_mul_f32 v[2:3], v[2:3], v[118:119] op_sel_hi:[1,0]
.LBB0_765:
	v_add_u32_e32 v0, s91, v129
	v_add_u32_e32 v117, v0, v130
	v_exp_f32_e32 v50, v50
	v_exp_f32_e32 v51, v51
	v_exp_f32_e32 v52, v52
	v_exp_f32_e32 v53, v53
	ds_read_b64_tr_b16 v[118:119], v117 offset:24576
	ds_read_b64_tr_b16 v[120:121], v117 offset:25600
	v_exp_f32_e32 v54, v54
	v_exp_f32_e32 v55, v55
	v_exp_f32_e32 v56, v56
	v_exp_f32_e32 v57, v57
	v_cvt_pk_bf16_f32 v136, v50, v51
	v_cvt_pk_bf16_f32 v137, v52, v53
	v_cvt_pk_bf16_f32 v138, v54, v55
	v_cvt_pk_bf16_f32 v139, v56, v57
	v_add_u32_e32 v0, v0, v131
	v_exp_f32_e32 v58, v58
	s_waitcnt lgkmcnt(0)
	v_mfma_f32_32x32x16_bf16 v[2:17], v[118:121], v[136:139], v[2:17]
	ds_read_b64_tr_b16 v[118:119], v0 offset:24576
	ds_read_b64_tr_b16 v[120:121], v0 offset:25600
	v_exp_f32_e32 v59, v59
	v_exp_f32_e32 v60, v60
	v_exp_f32_e32 v61, v61
	v_exp_f32_e32 v62, v62
	v_exp_f32_e32 v63, v63
	v_exp_f32_e32 v64, v64
	s_waitcnt lgkmcnt(0)
	v_mfma_f32_32x32x16_bf16 v[18:33], v[118:121], v[136:139], v[18:33]
	ds_read_b64_tr_b16 v[118:119], v117 offset:26624
	ds_read_b64_tr_b16 v[120:121], v117 offset:27648
	v_exp_f32_e32 v65, v65
	v_mfma_f32_32x32x16_bf16 v[34:49], v[84:87], v[136:139], v[34:49]
	v_cvt_pk_bf16_f32 v136, v58, v59
	v_cvt_pk_bf16_f32 v137, v60, v61
	v_cvt_pk_bf16_f32 v138, v62, v63
	v_cvt_pk_bf16_f32 v139, v64, v65
	s_waitcnt lgkmcnt(0)
	s_nop 0
	v_mfma_f32_32x32x16_bf16 v[2:17], v[118:121], v[136:139], v[2:17]
	ds_read_b64_tr_b16 v[118:119], v0 offset:26624
	ds_read_b64_tr_b16 v[120:121], v0 offset:27648
	s_waitcnt lgkmcnt(0)
	v_mfma_f32_32x32x16_bf16 v[18:33], v[118:121], v[136:139], v[18:33]
	v_max_f32_e32 v118, v66, v67
	v_max3_f32 v118, v118, v68, v69
	v_max3_f32 v118, v118, v70, v71
	v_max3_f32 v118, v118, v72, v73
	v_max3_f32 v118, v118, v74, v75
	v_max3_f32 v118, v118, v76, v77
	v_mfma_f32_32x32x16_bf16 v[34:49], v[84:87], v[136:139], v[34:49]
	v_max3_f32 v118, v118, v78, v79
	v_max3_f32 v118, v118, v80, v81
	v_mov_b32_e32 v119, v118
	s_nop 1
	v_permlane32_swap_b32_e32 v118, v119
	v_max_f32_e32 v118, v118, v119
	v_cmp_lt_f32_e32 vcc, s95, v118
	s_cbranch_vccz .LBB0_767
	v_max_f32_e32 v118, v118, v118
	v_max_f32_e32 v118, 0, v118
	v_exp_f32_e64 v120, -v118
	v_add_f32_e32 v116, v116, v118
	v_pk_add_f32 v[66:67], v[66:67], v[118:119] op_sel_hi:[1,0] neg_lo:[0,1] neg_hi:[0,1]
	v_pk_add_f32 v[68:69], v[68:69], v[118:119] op_sel_hi:[1,0] neg_lo:[0,1] neg_hi:[0,1]
	v_mul_f32_e32 v34, v34, v120
	v_pk_add_f32 v[70:71], v[70:71], v[118:119] op_sel_hi:[1,0] neg_lo:[0,1] neg_hi:[0,1]
	v_pk_add_f32 v[72:73], v[72:73], v[118:119] op_sel_hi:[1,0] neg_lo:[0,1] neg_hi:[0,1]
	v_pk_add_f32 v[74:75], v[74:75], v[118:119] op_sel_hi:[1,0] neg_lo:[0,1] neg_hi:[0,1]
	v_pk_add_f32 v[76:77], v[76:77], v[118:119] op_sel_hi:[1,0] neg_lo:[0,1] neg_hi:[0,1]
	v_pk_add_f32 v[78:79], v[78:79], v[118:119] op_sel_hi:[1,0] neg_lo:[0,1] neg_hi:[0,1]
	v_pk_add_f32 v[80:81], v[80:81], v[118:119] op_sel_hi:[1,0] neg_lo:[0,1] neg_hi:[0,1]
	v_pk_mul_f32 v[32:33], v[32:33], v[120:121] op_sel_hi:[1,0]
	v_pk_mul_f32 v[30:31], v[30:31], v[120:121] op_sel_hi:[1,0]
	v_pk_mul_f32 v[28:29], v[28:29], v[120:121] op_sel_hi:[1,0]
	v_pk_mul_f32 v[26:27], v[26:27], v[120:121] op_sel_hi:[1,0]
	v_pk_mul_f32 v[24:25], v[24:25], v[120:121] op_sel_hi:[1,0]
	v_pk_mul_f32 v[22:23], v[22:23], v[120:121] op_sel_hi:[1,0]
	v_pk_mul_f32 v[20:21], v[20:21], v[120:121] op_sel_hi:[1,0]
	v_pk_mul_f32 v[18:19], v[18:19], v[120:121] op_sel_hi:[1,0]
	v_pk_mul_f32 v[16:17], v[16:17], v[120:121] op_sel_hi:[1,0]
	v_pk_mul_f32 v[14:15], v[14:15], v[120:121] op_sel_hi:[1,0]
	v_pk_mul_f32 v[12:13], v[12:13], v[120:121] op_sel_hi:[1,0]
	v_pk_mul_f32 v[10:11], v[10:11], v[120:121] op_sel_hi:[1,0]
	v_pk_mul_f32 v[8:9], v[8:9], v[120:121] op_sel_hi:[1,0]
	v_pk_mul_f32 v[6:7], v[6:7], v[120:121] op_sel_hi:[1,0]
	v_pk_mul_f32 v[4:5], v[4:5], v[120:121] op_sel_hi:[1,0]
	v_pk_mul_f32 v[2:3], v[2:3], v[120:121] op_sel_hi:[1,0]

.LBB0_781:
	s_andn2_b64 vcc, exec, s[0:1]
	s_cbranch_vccnz .LBB0_787
	s_nop 8
	v_max_f32_e32 v142, v52, v53
	v_max3_f32 v142, v142, v54, v55
	v_max3_f32 v142, v142, v56, v57
	v_max3_f32 v142, v142, v58, v59
	v_max3_f32 v142, v142, v60, v61
	v_max3_f32 v142, v142, v62, v63
	v_max3_f32 v142, v142, v64, v65
	v_max3_f32 v142, v142, v66, v67
	v_mov_b32_e32 v143, v142
	s_nop 1
	v_permlane32_swap_b32_e32 v142, v143
	v_max_f32_e32 v142, v142, v143
	s_cmp_eq_u32 s95, 0
	s_cselect_b64 s[0:1], -1, 0
	v_cmp_lt_f32_e32 vcc, s94, v142
	s_or_b64 vcc, s[0:1], vcc
	s_cbranch_vccz .LBB0_784
	v_max_f32_e32 v143, v142, v142
	v_max_f32_e32 v143, 0, v143
	v_cndmask_b32_e64 v142, v143, v142, s[0:1]
	v_exp_f32_e64 v143, -v142
	v_add_f32_e32 v137, v137, v142
	v_sub_f32_e32 v83, v83, v142
	v_sub_f32_e32 v82, v82, v142
	v_cndmask_b32_e64 v144, v143, 1.0, s[0:1]
	v_pk_add_f32 v[52:53], v[52:53], v[142:143] op_sel_hi:[1,0] neg_lo:[0,1] neg_hi:[0,1]
	v_pk_add_f32 v[54:55], v[54:55], v[142:143] op_sel_hi:[1,0] neg_lo:[0,1] neg_hi:[0,1]
	v_mul_f32_e32 v36, v36, v144
	v_pk_add_f32 v[56:57], v[56:57], v[142:143] op_sel_hi:[1,0] neg_lo:[0,1] neg_hi:[0,1]
	v_pk_add_f32 v[58:59], v[58:59], v[142:143] op_sel_hi:[1,0] neg_lo:[0,1] neg_hi:[0,1]
	v_pk_add_f32 v[60:61], v[60:61], v[142:143] op_sel_hi:[1,0] neg_lo:[0,1] neg_hi:[0,1]
	v_pk_add_f32 v[62:63], v[62:63], v[142:143] op_sel_hi:[1,0] neg_lo:[0,1] neg_hi:[0,1]
	v_pk_add_f32 v[64:65], v[64:65], v[142:143] op_sel_hi:[1,0] neg_lo:[0,1] neg_hi:[0,1]
	v_pk_add_f32 v[66:67], v[66:67], v[142:143] op_sel_hi:[1,0] neg_lo:[0,1] neg_hi:[0,1]
	v_sub_f32_e32 v81, v81, v142
	v_sub_f32_e32 v80, v80, v142
	v_sub_f32_e32 v79, v79, v142
	v_sub_f32_e32 v78, v78, v142
	v_sub_f32_e32 v77, v77, v142
	v_sub_f32_e32 v76, v76, v142
	v_sub_f32_e32 v75, v75, v142
	v_sub_f32_e32 v74, v74, v142
	v_sub_f32_e32 v73, v73, v142
	v_sub_f32_e32 v72, v72, v142
	v_sub_f32_e32 v71, v71, v142
	v_sub_f32_e32 v70, v70, v142
	v_sub_f32_e32 v69, v69, v142
	v_sub_f32_e32 v68, v68, v142
	v_pk_mul_f32 v[34:35], v[34:35], v[144:145] op_sel_hi:[1,0]
	v_pk_mul_f32 v[32:33], v[32:33], v[144:145] op_sel_hi:[1,0]
	v_pk_mul_f32 v[30:31], v[30:31], v[144:145] op_sel_hi:[1,0]
	v_pk_mul_f32 v[28:29], v[28:29], v[144:145] op_sel_hi:[1,0]
	v_pk_mul_f32 v[26:27], v[26:27], v[144:145] op_sel_hi:[1,0]
	v_pk_mul_f32 v[24:25], v[24:25], v[144:145] op_sel_hi:[1,0]
	v_pk_mul_f32 v[22:23], v[22:23], v[144:145] op_sel_hi:[1,0]
	v_pk_mul_f32 v[20:21], v[20:21], v[144:145] op_sel_hi:[1,0]
	v_pk_mul_f32 v[18:19], v[18:19], v[144:145] op_sel_hi:[1,0]
	v_pk_mul_f32 v[16:17], v[16:17], v[144:145] op_sel_hi:[1,0]
	v_pk_mul_f32 v[14:15], v[14:15], v[144:145] op_sel_hi:[1,0]
	v_pk_mul_f32 v[12:13], v[12:13], v[144:145] op_sel_hi:[1,0]
	v_pk_mul_f32 v[10:11], v[10:11], v[144:145] op_sel_hi:[1,0]
	v_pk_mul_f32 v[8:9], v[8:9], v[144:145] op_sel_hi:[1,0]
	v_pk_mul_f32 v[6:7], v[6:7], v[144:145] op_sel_hi:[1,0]
	v_pk_mul_f32 v[4:5], v[4:5], v[144:145] op_sel_hi:[1,0]
.LBB0_784:
	v_add_u32_e32 v142, s91, v129
	v_add_u32_e32 v143, v142, v130
	v_exp_f32_e32 v52, v52
	v_exp_f32_e32 v53, v53
	v_exp_f32_e32 v54, v54
	v_exp_f32_e32 v55, v55
	ds_read_b64_tr_b16 v[144:145], v143 offset:16384
	ds_read_b64_tr_b16 v[146:147], v143 offset:17408
	v_exp_f32_e32 v56, v56
	v_exp_f32_e32 v57, v57
	v_exp_f32_e32 v58, v58
	v_exp_f32_e32 v59, v59
	v_cvt_pk_bf16_f32 v148, v52, v53
	v_cvt_pk_bf16_f32 v149, v54, v55
	v_cvt_pk_bf16_f32 v150, v56, v57
	v_cvt_pk_bf16_f32 v151, v58, v59
	v_add_u32_e32 v142, v142, v131
	v_exp_f32_e32 v60, v60
	s_waitcnt lgkmcnt(0)
	v_mfma_f32_32x32x16_bf16 v[4:19], v[144:147], v[148:151], v[4:19]
	ds_read_b64_tr_b16 v[144:145], v142 offset:16384
	ds_read_b64_tr_b16 v[146:147], v142 offset:17408
	v_exp_f32_e32 v61, v61
	v_exp_f32_e32 v62, v62
	v_exp_f32_e32 v63, v63
	v_exp_f32_e32 v64, v64
	v_exp_f32_e32 v65, v65
	v_exp_f32_e32 v66, v66
	s_waitcnt lgkmcnt(0)
	v_mfma_f32_32x32x16_bf16 v[20:35], v[144:147], v[148:151], v[20:35]
	ds_read_b64_tr_b16 v[144:145], v143 offset:18432
	ds_read_b64_tr_b16 v[146:147], v143 offset:19456
	v_exp_f32_e32 v67, v67
	v_mfma_f32_32x32x16_bf16 v[36:51], v[84:87], v[148:151], v[36:51]
	v_cvt_pk_bf16_f32 v148, v60, v61
	v_cvt_pk_bf16_f32 v149, v62, v63
	v_cvt_pk_bf16_f32 v150, v64, v65
	v_cvt_pk_bf16_f32 v151, v66, v67
	s_waitcnt lgkmcnt(0)
	s_nop 0
	v_mfma_f32_32x32x16_bf16 v[4:19], v[144:147], v[148:151], v[4:19]
	ds_read_b64_tr_b16 v[144:145], v142 offset:18432
	ds_read_b64_tr_b16 v[146:147], v142 offset:19456
	s_waitcnt lgkmcnt(0)
	v_mfma_f32_32x32x16_bf16 v[20:35], v[144:147], v[148:151], v[20:35]
	v_max_f32_e32 v144, v68, v69
	v_max3_f32 v144, v144, v70, v71
	v_max3_f32 v144, v144, v72, v73
	v_max3_f32 v144, v144, v74, v75
	v_max3_f32 v144, v144, v76, v77
	v_max3_f32 v144, v144, v78, v79
	v_mfma_f32_32x32x16_bf16 v[36:51], v[84:87], v[148:151], v[36:51]
	v_max3_f32 v144, v144, v80, v81
	v_max3_f32 v144, v144, v82, v83
	v_mov_b32_e32 v145, v144
	s_nop 1
	v_permlane32_swap_b32_e32 v144, v145
	v_max_f32_e32 v144, v144, v145
	v_cmp_lt_f32_e32 vcc, s94, v144
	s_cbranch_vccz .LBB0_786
	v_max_f32_e32 v144, v144, v144
	v_max_f32_e32 v144, 0, v144
	v_exp_f32_e64 v146, -v144
	v_add_f32_e32 v137, v137, v144
	v_pk_add_f32 v[68:69], v[68:69], v[144:145] op_sel_hi:[1,0] neg_lo:[0,1] neg_hi:[0,1]
	v_pk_add_f32 v[70:71], v[70:71], v[144:145] op_sel_hi:[1,0] neg_lo:[0,1] neg_hi:[0,1]
	v_mul_f32_e32 v36, v36, v146
	v_pk_add_f32 v[72:73], v[72:73], v[144:145] op_sel_hi:[1,0] neg_lo:[0,1] neg_hi:[0,1]
	v_pk_add_f32 v[74:75], v[74:75], v[144:145] op_sel_hi:[1,0] neg_lo:[0,1] neg_hi:[0,1]
	v_pk_add_f32 v[76:77], v[76:77], v[144:145] op_sel_hi:[1,0] neg_lo:[0,1] neg_hi:[0,1]
	v_pk_add_f32 v[78:79], v[78:79], v[144:145] op_sel_hi:[1,0] neg_lo:[0,1] neg_hi:[0,1]
	v_pk_add_f32 v[80:81], v[80:81], v[144:145] op_sel_hi:[1,0] neg_lo:[0,1] neg_hi:[0,1]
	v_pk_add_f32 v[82:83], v[82:83], v[144:145] op_sel_hi:[1,0] neg_lo:[0,1] neg_hi:[0,1]
	v_pk_mul_f32 v[34:35], v[34:35], v[146:147] op_sel_hi:[1,0]
	v_pk_mul_f32 v[32:33], v[32:33], v[146:147] op_sel_hi:[1,0]
	v_pk_mul_f32 v[30:31], v[30:31], v[146:147] op_sel_hi:[1,0]
	v_pk_mul_f32 v[28:29], v[28:29], v[146:147] op_sel_hi:[1,0]
	v_pk_mul_f32 v[26:27], v[26:27], v[146:147] op_sel_hi:[1,0]
	v_pk_mul_f32 v[24:25], v[24:25], v[146:147] op_sel_hi:[1,0]
	v_pk_mul_f32 v[22:23], v[22:23], v[146:147] op_sel_hi:[1,0]
	v_pk_mul_f32 v[20:21], v[20:21], v[146:147] op_sel_hi:[1,0]
	v_pk_mul_f32 v[18:19], v[18:19], v[146:147] op_sel_hi:[1,0]
	v_pk_mul_f32 v[16:17], v[16:17], v[146:147] op_sel_hi:[1,0]
	v_pk_mul_f32 v[14:15], v[14:15], v[146:147] op_sel_hi:[1,0]
	v_pk_mul_f32 v[12:13], v[12:13], v[146:147] op_sel_hi:[1,0]
	v_pk_mul_f32 v[10:11], v[10:11], v[146:147] op_sel_hi:[1,0]
	v_pk_mul_f32 v[8:9], v[8:9], v[146:147] op_sel_hi:[1,0]
	v_pk_mul_f32 v[6:7], v[6:7], v[146:147] op_sel_hi:[1,0]
	v_pk_mul_f32 v[4:5], v[4:5], v[146:147] op_sel_hi:[1,0]

.LBB0_790:
	s_andn2_b64 vcc, exec, s[0:1]
	s_cbranch_vccnz .LBB0_796
	s_nop 8
	v_max_f32_e32 v2, v52, v53
	v_max3_f32 v2, v2, v54, v55
	v_max3_f32 v2, v2, v56, v57
	v_max3_f32 v2, v2, v58, v59
	v_max3_f32 v2, v2, v60, v61
	v_max3_f32 v2, v2, v62, v63
	v_max3_f32 v2, v2, v64, v65
	v_max3_f32 v2, v2, v66, v67
	v_mov_b32_e32 v138, v2
	s_nop 1
	v_permlane32_swap_b32_e32 v2, v138
	v_max_f32_e32 v2, v2, v138
	v_cmp_lt_f32_e32 vcc, s94, v2
	s_cbranch_vccz .LBB0_793
	v_max_f32_e32 v2, v2, v2
	v_max_f32_e32 v2, 0, v2
	v_exp_f32_e64 v138, -v2
	v_add_f32_e32 v137, v137, v2
	v_pk_add_f32 v[52:53], v[52:53], v[2:3] op_sel_hi:[1,0] neg_lo:[0,1] neg_hi:[0,1]
	v_pk_add_f32 v[54:55], v[54:55], v[2:3] op_sel_hi:[1,0] neg_lo:[0,1] neg_hi:[0,1]
	v_mul_f32_e32 v36, v36, v138
	v_pk_add_f32 v[56:57], v[56:57], v[2:3] op_sel_hi:[1,0] neg_lo:[0,1] neg_hi:[0,1]
	v_pk_add_f32 v[58:59], v[58:59], v[2:3] op_sel_hi:[1,0] neg_lo:[0,1] neg_hi:[0,1]
	v_pk_add_f32 v[60:61], v[60:61], v[2:3] op_sel_hi:[1,0] neg_lo:[0,1] neg_hi:[0,1]
	v_pk_add_f32 v[62:63], v[62:63], v[2:3] op_sel_hi:[1,0] neg_lo:[0,1] neg_hi:[0,1]
	v_pk_add_f32 v[64:65], v[64:65], v[2:3] op_sel_hi:[1,0] neg_lo:[0,1] neg_hi:[0,1]
	v_pk_add_f32 v[66:67], v[66:67], v[2:3] op_sel_hi:[1,0] neg_lo:[0,1] neg_hi:[0,1]
	v_sub_f32_e32 v83, v83, v2
	v_sub_f32_e32 v82, v82, v2
	v_sub_f32_e32 v81, v81, v2
	v_sub_f32_e32 v80, v80, v2
	v_sub_f32_e32 v79, v79, v2
	v_sub_f32_e32 v78, v78, v2
	v_sub_f32_e32 v77, v77, v2
	v_sub_f32_e32 v76, v76, v2
	v_sub_f32_e32 v75, v75, v2
	v_sub_f32_e32 v74, v74, v2
	v_sub_f32_e32 v73, v73, v2
	v_sub_f32_e32 v72, v72, v2
	v_sub_f32_e32 v71, v71, v2
	v_sub_f32_e32 v70, v70, v2
	v_sub_f32_e32 v69, v69, v2
	v_sub_f32_e32 v68, v68, v2
	v_pk_mul_f32 v[34:35], v[34:35], v[138:139] op_sel_hi:[1,0]
	v_pk_mul_f32 v[32:33], v[32:33], v[138:139] op_sel_hi:[1,0]
	v_pk_mul_f32 v[30:31], v[30:31], v[138:139] op_sel_hi:[1,0]
	v_pk_mul_f32 v[28:29], v[28:29], v[138:139] op_sel_hi:[1,0]
	v_pk_mul_f32 v[26:27], v[26:27], v[138:139] op_sel_hi:[1,0]
	v_pk_mul_f32 v[24:25], v[24:25], v[138:139] op_sel_hi:[1,0]
	v_pk_mul_f32 v[22:23], v[22:23], v[138:139] op_sel_hi:[1,0]
	v_pk_mul_f32 v[20:21], v[20:21], v[138:139] op_sel_hi:[1,0]
	v_pk_mul_f32 v[18:19], v[18:19], v[138:139] op_sel_hi:[1,0]
	v_pk_mul_f32 v[16:17], v[16:17], v[138:139] op_sel_hi:[1,0]
	v_pk_mul_f32 v[14:15], v[14:15], v[138:139] op_sel_hi:[1,0]
	v_pk_mul_f32 v[12:13], v[12:13], v[138:139] op_sel_hi:[1,0]
	v_pk_mul_f32 v[10:11], v[10:11], v[138:139] op_sel_hi:[1,0]
	v_pk_mul_f32 v[8:9], v[8:9], v[138:139] op_sel_hi:[1,0]
	v_pk_mul_f32 v[6:7], v[6:7], v[138:139] op_sel_hi:[1,0]
	v_pk_mul_f32 v[4:5], v[4:5], v[138:139] op_sel_hi:[1,0]
.LBB0_793:
	v_add_u32_e32 v2, s91, v129
	v_add_u32_e32 v138, v2, v130
	v_exp_f32_e32 v52, v52
	v_exp_f32_e32 v53, v53
	v_exp_f32_e32 v54, v54
	v_exp_f32_e32 v55, v55
	ds_read_b64_tr_b16 v[140:141], v138 offset:24576
	ds_read_b64_tr_b16 v[142:143], v138 offset:25600
	v_exp_f32_e32 v56, v56
	v_exp_f32_e32 v57, v57
	v_exp_f32_e32 v58, v58
	v_exp_f32_e32 v59, v59
	v_cvt_pk_bf16_f32 v144, v52, v53
	v_cvt_pk_bf16_f32 v145, v54, v55
	v_cvt_pk_bf16_f32 v146, v56, v57
	v_cvt_pk_bf16_f32 v147, v58, v59
	v_add_u32_e32 v2, v2, v131
	v_exp_f32_e32 v60, v60
	s_waitcnt lgkmcnt(0)
	v_mfma_f32_32x32x16_bf16 v[4:19], v[140:143], v[144:147], v[4:19]
	ds_read_b64_tr_b16 v[140:141], v2 offset:24576
	ds_read_b64_tr_b16 v[142:143], v2 offset:25600
	v_exp_f32_e32 v61, v61
	v_exp_f32_e32 v62, v62
	v_exp_f32_e32 v63, v63
	v_exp_f32_e32 v64, v64
	v_exp_f32_e32 v65, v65
	v_exp_f32_e32 v66, v66
	s_waitcnt lgkmcnt(0)
	v_mfma_f32_32x32x16_bf16 v[20:35], v[140:143], v[144:147], v[20:35]
	ds_read_b64_tr_b16 v[140:141], v138 offset:26624
	ds_read_b64_tr_b16 v[142:143], v138 offset:27648
	v_exp_f32_e32 v67, v67
	v_max_f32_e32 v139, v69, v69
	v_mfma_f32_32x32x16_bf16 v[36:51], v[84:87], v[144:147], v[36:51]
	v_cvt_pk_bf16_f32 v144, v60, v61
	v_cvt_pk_bf16_f32 v145, v62, v63
	v_cvt_pk_bf16_f32 v146, v64, v65
	v_cvt_pk_bf16_f32 v147, v66, v67
	s_waitcnt lgkmcnt(0)
	s_nop 0
	v_mfma_f32_32x32x16_bf16 v[4:19], v[140:143], v[144:147], v[4:19]
	ds_read_b64_tr_b16 v[140:141], v2 offset:26624
	ds_read_b64_tr_b16 v[142:143], v2 offset:27648
	s_waitcnt lgkmcnt(0)
	v_mfma_f32_32x32x16_bf16 v[20:35], v[140:143], v[144:147], v[20:35]
	v_max_f32_e32 v140, v68, v68
	v_max_f32_e32 v139, v140, v139
	v_max3_f32 v139, v139, v70, v71
	v_max3_f32 v139, v139, v72, v73
	v_max3_f32 v139, v139, v74, v75
	v_max3_f32 v139, v139, v76, v77
	v_max3_f32 v139, v139, v78, v79
	v_mfma_f32_32x32x16_bf16 v[36:51], v[84:87], v[144:147], v[36:51]
	v_max3_f32 v139, v139, v80, v81
	v_max3_f32 v139, v139, v82, v83
	v_mov_b32_e32 v140, v139
	s_nop 1
	v_permlane32_swap_b32_e32 v139, v140
	v_max_f32_e32 v139, v139, v140
	v_cmp_lt_f32_e32 vcc, s94, v139
	s_cbranch_vccz .LBB0_795
	v_max_f32_e32 v139, v139, v139
	v_max_f32_e32 v140, 0, v139
	v_exp_f32_e64 v142, -v140
	v_add_f32_e32 v137, v137, v140
	v_pk_add_f32 v[68:69], v[68:69], v[140:141] op_sel_hi:[1,0] neg_lo:[0,1] neg_hi:[0,1]
	v_pk_add_f32 v[70:71], v[70:71], v[140:141] op_sel_hi:[1,0] neg_lo:[0,1] neg_hi:[0,1]
	v_mul_f32_e32 v36, v36, v142
	v_pk_add_f32 v[72:73], v[72:73], v[140:141] op_sel_hi:[1,0] neg_lo:[0,1] neg_hi:[0,1]
	v_pk_add_f32 v[74:75], v[74:75], v[140:141] op_sel_hi:[1,0] neg_lo:[0,1] neg_hi:[0,1]
	v_pk_add_f32 v[76:77], v[76:77], v[140:141] op_sel_hi:[1,0] neg_lo:[0,1] neg_hi:[0,1]
	v_pk_add_f32 v[78:79], v[78:79], v[140:141] op_sel_hi:[1,0] neg_lo:[0,1] neg_hi:[0,1]
	v_pk_add_f32 v[80:81], v[80:81], v[140:141] op_sel_hi:[1,0] neg_lo:[0,1] neg_hi:[0,1]
	v_pk_add_f32 v[82:83], v[82:83], v[140:141] op_sel_hi:[1,0] neg_lo:[0,1] neg_hi:[0,1]
	v_pk_mul_f32 v[34:35], v[34:35], v[142:143] op_sel_hi:[1,0]
	v_pk_mul_f32 v[32:33], v[32:33], v[142:143] op_sel_hi:[1,0]
	v_pk_mul_f32 v[30:31], v[30:31], v[142:143] op_sel_hi:[1,0]
	v_pk_mul_f32 v[28:29], v[28:29], v[142:143] op_sel_hi:[1,0]
	v_pk_mul_f32 v[26:27], v[26:27], v[142:143] op_sel_hi:[1,0]
	v_pk_mul_f32 v[24:25], v[24:25], v[142:143] op_sel_hi:[1,0]
	v_pk_mul_f32 v[22:23], v[22:23], v[142:143] op_sel_hi:[1,0]
	v_pk_mul_f32 v[20:21], v[20:21], v[142:143] op_sel_hi:[1,0]
	v_pk_mul_f32 v[18:19], v[18:19], v[142:143] op_sel_hi:[1,0]
	v_pk_mul_f32 v[16:17], v[16:17], v[142:143] op_sel_hi:[1,0]
	v_pk_mul_f32 v[14:15], v[14:15], v[142:143] op_sel_hi:[1,0]
	v_pk_mul_f32 v[12:13], v[12:13], v[142:143] op_sel_hi:[1,0]
	v_pk_mul_f32 v[10:11], v[10:11], v[142:143] op_sel_hi:[1,0]
	v_pk_mul_f32 v[8:9], v[8:9], v[142:143] op_sel_hi:[1,0]
	v_pk_mul_f32 v[6:7], v[6:7], v[142:143] op_sel_hi:[1,0]
	v_pk_mul_f32 v[4:5], v[4:5], v[142:143] op_sel_hi:[1,0]

.LBB0_809:
	s_andn2_b64 vcc, exec, s[0:1]
	s_cbranch_vccnz .LBB0_815
	s_nop 8
	v_max_f32_e32 v142, v52, v53
	v_max3_f32 v142, v142, v54, v55
	v_max3_f32 v142, v142, v56, v57
	v_max3_f32 v142, v142, v58, v59
	v_max3_f32 v142, v142, v60, v61
	v_max3_f32 v142, v142, v62, v63
	v_max3_f32 v142, v142, v64, v65
	v_max3_f32 v142, v142, v66, v67
	v_mov_b32_e32 v143, v142
	s_nop 1
	v_permlane32_swap_b32_e32 v142, v143
	v_max_f32_e32 v142, v142, v143
	s_cmp_eq_u32 s90, 0
	s_cselect_b64 s[0:1], -1, 0
	v_cmp_lt_f32_e32 vcc, s94, v142
	s_or_b64 vcc, s[0:1], vcc
	s_cbranch_vccz .LBB0_812
	v_max_f32_e32 v143, v142, v142
	v_max_f32_e32 v143, 0, v143
	v_cndmask_b32_e64 v142, v143, v142, s[0:1]
	v_exp_f32_e64 v143, -v142
	v_add_f32_e32 v137, v137, v142
	v_sub_f32_e32 v83, v83, v142
	v_sub_f32_e32 v82, v82, v142
	v_cndmask_b32_e64 v144, v143, 1.0, s[0:1]
	v_pk_add_f32 v[52:53], v[52:53], v[142:143] op_sel_hi:[1,0] neg_lo:[0,1] neg_hi:[0,1]
	v_pk_add_f32 v[54:55], v[54:55], v[142:143] op_sel_hi:[1,0] neg_lo:[0,1] neg_hi:[0,1]
	v_mul_f32_e32 v36, v36, v144
	v_pk_add_f32 v[56:57], v[56:57], v[142:143] op_sel_hi:[1,0] neg_lo:[0,1] neg_hi:[0,1]
	v_pk_add_f32 v[58:59], v[58:59], v[142:143] op_sel_hi:[1,0] neg_lo:[0,1] neg_hi:[0,1]
	v_pk_add_f32 v[60:61], v[60:61], v[142:143] op_sel_hi:[1,0] neg_lo:[0,1] neg_hi:[0,1]
	v_pk_add_f32 v[62:63], v[62:63], v[142:143] op_sel_hi:[1,0] neg_lo:[0,1] neg_hi:[0,1]
	v_pk_add_f32 v[64:65], v[64:65], v[142:143] op_sel_hi:[1,0] neg_lo:[0,1] neg_hi:[0,1]
	v_pk_add_f32 v[66:67], v[66:67], v[142:143] op_sel_hi:[1,0] neg_lo:[0,1] neg_hi:[0,1]
	v_sub_f32_e32 v81, v81, v142
	v_sub_f32_e32 v80, v80, v142
	v_sub_f32_e32 v79, v79, v142
	v_sub_f32_e32 v78, v78, v142
	v_sub_f32_e32 v77, v77, v142
	v_sub_f32_e32 v76, v76, v142
	v_sub_f32_e32 v75, v75, v142
	v_sub_f32_e32 v74, v74, v142
	v_sub_f32_e32 v73, v73, v142
	v_sub_f32_e32 v72, v72, v142
	v_sub_f32_e32 v71, v71, v142
	v_sub_f32_e32 v70, v70, v142
	v_sub_f32_e32 v69, v69, v142
	v_sub_f32_e32 v68, v68, v142
	v_pk_mul_f32 v[34:35], v[34:35], v[144:145] op_sel_hi:[1,0]
	v_pk_mul_f32 v[32:33], v[32:33], v[144:145] op_sel_hi:[1,0]
	v_pk_mul_f32 v[30:31], v[30:31], v[144:145] op_sel_hi:[1,0]
	v_pk_mul_f32 v[28:29], v[28:29], v[144:145] op_sel_hi:[1,0]
	v_pk_mul_f32 v[26:27], v[26:27], v[144:145] op_sel_hi:[1,0]
	v_pk_mul_f32 v[24:25], v[24:25], v[144:145] op_sel_hi:[1,0]
	v_pk_mul_f32 v[22:23], v[22:23], v[144:145] op_sel_hi:[1,0]
	v_pk_mul_f32 v[20:21], v[20:21], v[144:145] op_sel_hi:[1,0]
	v_pk_mul_f32 v[18:19], v[18:19], v[144:145] op_sel_hi:[1,0]
	v_pk_mul_f32 v[16:17], v[16:17], v[144:145] op_sel_hi:[1,0]
	v_pk_mul_f32 v[14:15], v[14:15], v[144:145] op_sel_hi:[1,0]
	v_pk_mul_f32 v[12:13], v[12:13], v[144:145] op_sel_hi:[1,0]
	v_pk_mul_f32 v[10:11], v[10:11], v[144:145] op_sel_hi:[1,0]
	v_pk_mul_f32 v[8:9], v[8:9], v[144:145] op_sel_hi:[1,0]
	v_pk_mul_f32 v[6:7], v[6:7], v[144:145] op_sel_hi:[1,0]
	v_pk_mul_f32 v[4:5], v[4:5], v[144:145] op_sel_hi:[1,0]
.LBB0_812:
	v_add_u32_e32 v142, s95, v129
	v_add_u32_e32 v143, v142, v130
	v_exp_f32_e32 v52, v52
	v_exp_f32_e32 v53, v53
	v_exp_f32_e32 v54, v54
	v_exp_f32_e32 v55, v55
	ds_read_b64_tr_b16 v[144:145], v143 offset:16384
	ds_read_b64_tr_b16 v[146:147], v143 offset:17408
	v_exp_f32_e32 v56, v56
	v_exp_f32_e32 v57, v57
	v_exp_f32_e32 v58, v58
	v_exp_f32_e32 v59, v59
	v_cvt_pk_bf16_f32 v148, v52, v53
	v_cvt_pk_bf16_f32 v149, v54, v55
	v_cvt_pk_bf16_f32 v150, v56, v57
	v_cvt_pk_bf16_f32 v151, v58, v59
	v_add_u32_e32 v142, v142, v131
	v_exp_f32_e32 v60, v60
	s_waitcnt lgkmcnt(0)
	v_mfma_f32_32x32x16_bf16 v[4:19], v[144:147], v[148:151], v[4:19]
	ds_read_b64_tr_b16 v[144:145], v142 offset:16384
	ds_read_b64_tr_b16 v[146:147], v142 offset:17408
	v_exp_f32_e32 v61, v61
	v_exp_f32_e32 v62, v62
	v_exp_f32_e32 v63, v63
	v_exp_f32_e32 v64, v64
	v_exp_f32_e32 v65, v65
	v_exp_f32_e32 v66, v66
	s_waitcnt lgkmcnt(0)
	v_mfma_f32_32x32x16_bf16 v[20:35], v[144:147], v[148:151], v[20:35]
	ds_read_b64_tr_b16 v[144:145], v143 offset:18432
	ds_read_b64_tr_b16 v[146:147], v143 offset:19456
	v_exp_f32_e32 v67, v67
	v_mfma_f32_32x32x16_bf16 v[36:51], v[84:87], v[148:151], v[36:51]
	v_cvt_pk_bf16_f32 v148, v60, v61
	v_cvt_pk_bf16_f32 v149, v62, v63
	v_cvt_pk_bf16_f32 v150, v64, v65
	v_cvt_pk_bf16_f32 v151, v66, v67
	s_waitcnt lgkmcnt(0)
	s_nop 0
	v_mfma_f32_32x32x16_bf16 v[4:19], v[144:147], v[148:151], v[4:19]
	ds_read_b64_tr_b16 v[144:145], v142 offset:18432
	ds_read_b64_tr_b16 v[146:147], v142 offset:19456
	s_waitcnt lgkmcnt(0)
	v_mfma_f32_32x32x16_bf16 v[20:35], v[144:147], v[148:151], v[20:35]
	v_max_f32_e32 v144, v68, v69
	v_max3_f32 v144, v144, v70, v71
	v_max3_f32 v144, v144, v72, v73
	v_max3_f32 v144, v144, v74, v75
	v_max3_f32 v144, v144, v76, v77
	v_max3_f32 v144, v144, v78, v79
	v_mfma_f32_32x32x16_bf16 v[36:51], v[84:87], v[148:151], v[36:51]
	v_max3_f32 v144, v144, v80, v81
	v_max3_f32 v144, v144, v82, v83
	v_mov_b32_e32 v145, v144
	s_nop 1
	v_permlane32_swap_b32_e32 v144, v145
	v_max_f32_e32 v144, v144, v145
	v_cmp_lt_f32_e32 vcc, s94, v144
	s_cbranch_vccz .LBB0_814
	v_max_f32_e32 v144, v144, v144
	v_max_f32_e32 v144, 0, v144
	v_exp_f32_e64 v146, -v144
	v_add_f32_e32 v137, v137, v144
	v_pk_add_f32 v[68:69], v[68:69], v[144:145] op_sel_hi:[1,0] neg_lo:[0,1] neg_hi:[0,1]
	v_pk_add_f32 v[70:71], v[70:71], v[144:145] op_sel_hi:[1,0] neg_lo:[0,1] neg_hi:[0,1]
	v_mul_f32_e32 v36, v36, v146
	v_pk_add_f32 v[72:73], v[72:73], v[144:145] op_sel_hi:[1,0] neg_lo:[0,1] neg_hi:[0,1]
	v_pk_add_f32 v[74:75], v[74:75], v[144:145] op_sel_hi:[1,0] neg_lo:[0,1] neg_hi:[0,1]
	v_pk_add_f32 v[76:77], v[76:77], v[144:145] op_sel_hi:[1,0] neg_lo:[0,1] neg_hi:[0,1]
	v_pk_add_f32 v[78:79], v[78:79], v[144:145] op_sel_hi:[1,0] neg_lo:[0,1] neg_hi:[0,1]
	v_pk_add_f32 v[80:81], v[80:81], v[144:145] op_sel_hi:[1,0] neg_lo:[0,1] neg_hi:[0,1]
	v_pk_add_f32 v[82:83], v[82:83], v[144:145] op_sel_hi:[1,0] neg_lo:[0,1] neg_hi:[0,1]
	v_pk_mul_f32 v[34:35], v[34:35], v[146:147] op_sel_hi:[1,0]
	v_pk_mul_f32 v[32:33], v[32:33], v[146:147] op_sel_hi:[1,0]
	v_pk_mul_f32 v[30:31], v[30:31], v[146:147] op_sel_hi:[1,0]
	v_pk_mul_f32 v[28:29], v[28:29], v[146:147] op_sel_hi:[1,0]
	v_pk_mul_f32 v[26:27], v[26:27], v[146:147] op_sel_hi:[1,0]
	v_pk_mul_f32 v[24:25], v[24:25], v[146:147] op_sel_hi:[1,0]
	v_pk_mul_f32 v[22:23], v[22:23], v[146:147] op_sel_hi:[1,0]
	v_pk_mul_f32 v[20:21], v[20:21], v[146:147] op_sel_hi:[1,0]
	v_pk_mul_f32 v[18:19], v[18:19], v[146:147] op_sel_hi:[1,0]
	v_pk_mul_f32 v[16:17], v[16:17], v[146:147] op_sel_hi:[1,0]
	v_pk_mul_f32 v[14:15], v[14:15], v[146:147] op_sel_hi:[1,0]
	v_pk_mul_f32 v[12:13], v[12:13], v[146:147] op_sel_hi:[1,0]
	v_pk_mul_f32 v[10:11], v[10:11], v[146:147] op_sel_hi:[1,0]
	v_pk_mul_f32 v[8:9], v[8:9], v[146:147] op_sel_hi:[1,0]
	v_pk_mul_f32 v[6:7], v[6:7], v[146:147] op_sel_hi:[1,0]
	v_pk_mul_f32 v[4:5], v[4:5], v[146:147] op_sel_hi:[1,0]

.LBB0_821:
	v_add_u32_e32 v2, s95, v129
	v_add_u32_e32 v138, v2, v130
	v_exp_f32_e32 v52, v52
	v_exp_f32_e32 v53, v53
	v_exp_f32_e32 v54, v54
	v_exp_f32_e32 v55, v55
	ds_read_b64_tr_b16 v[140:141], v138 offset:24576
	ds_read_b64_tr_b16 v[142:143], v138 offset:25600
	v_exp_f32_e32 v56, v56
	v_exp_f32_e32 v57, v57
	v_exp_f32_e32 v58, v58
	v_exp_f32_e32 v59, v59
	v_cvt_pk_bf16_f32 v144, v52, v53
	v_cvt_pk_bf16_f32 v145, v54, v55
	v_cvt_pk_bf16_f32 v146, v56, v57
	v_cvt_pk_bf16_f32 v147, v58, v59
	v_add_u32_e32 v2, v2, v131
	v_exp_f32_e32 v60, v60
	s_waitcnt lgkmcnt(0)
	v_mfma_f32_32x32x16_bf16 v[4:19], v[140:143], v[144:147], v[4:19]
	ds_read_b64_tr_b16 v[140:141], v2 offset:24576
	ds_read_b64_tr_b16 v[142:143], v2 offset:25600
	v_exp_f32_e32 v61, v61
	v_exp_f32_e32 v62, v62
	v_exp_f32_e32 v63, v63
	v_exp_f32_e32 v64, v64
	v_exp_f32_e32 v65, v65
	v_exp_f32_e32 v66, v66
	s_waitcnt lgkmcnt(0)
	v_mfma_f32_32x32x16_bf16 v[20:35], v[140:143], v[144:147], v[20:35]
	ds_read_b64_tr_b16 v[140:141], v138 offset:26624
	ds_read_b64_tr_b16 v[142:143], v138 offset:27648
	v_exp_f32_e32 v67, v67
	v_max_f32_e32 v139, v69, v69
	v_mfma_f32_32x32x16_bf16 v[36:51], v[84:87], v[144:147], v[36:51]
	v_cvt_pk_bf16_f32 v144, v60, v61
	v_cvt_pk_bf16_f32 v145, v62, v63
	v_cvt_pk_bf16_f32 v146, v64, v65
	v_cvt_pk_bf16_f32 v147, v66, v67
	s_waitcnt lgkmcnt(0)
	s_nop 0
	v_mfma_f32_32x32x16_bf16 v[4:19], v[140:143], v[144:147], v[4:19]
	ds_read_b64_tr_b16 v[140:141], v2 offset:26624
	ds_read_b64_tr_b16 v[142:143], v2 offset:27648
	s_waitcnt lgkmcnt(0)
	v_mfma_f32_32x32x16_bf16 v[20:35], v[140:143], v[144:147], v[20:35]
	v_max_f32_e32 v140, v68, v68
	v_max_f32_e32 v139, v140, v139
	v_max3_f32 v139, v139, v70, v71
	v_max3_f32 v139, v139, v72, v73
	v_max3_f32 v139, v139, v74, v75
	v_max3_f32 v139, v139, v76, v77
	v_max3_f32 v139, v139, v78, v79
	v_mfma_f32_32x32x16_bf16 v[36:51], v[84:87], v[144:147], v[36:51]
	v_max3_f32 v139, v139, v80, v81
	v_max3_f32 v139, v139, v82, v83
	v_mov_b32_e32 v140, v139
	s_nop 1
	v_permlane32_swap_b32_e32 v139, v140
	v_max_f32_e32 v139, v139, v140
	v_cmp_lt_f32_e32 vcc, s94, v139
	s_cbranch_vccz .LBB0_823
	v_max_f32_e32 v139, v139, v139
	v_max_f32_e32 v140, 0, v139
	v_exp_f32_e64 v142, -v140
	v_add_f32_e32 v137, v137, v140
	v_pk_add_f32 v[68:69], v[68:69], v[140:141] op_sel_hi:[1,0] neg_lo:[0,1] neg_hi:[0,1]
	v_pk_add_f32 v[70:71], v[70:71], v[140:141] op_sel_hi:[1,0] neg_lo:[0,1] neg_hi:[0,1]
	v_mul_f32_e32 v36, v36, v142
	v_pk_add_f32 v[72:73], v[72:73], v[140:141] op_sel_hi:[1,0] neg_lo:[0,1] neg_hi:[0,1]
	v_pk_add_f32 v[74:75], v[74:75], v[140:141] op_sel_hi:[1,0] neg_lo:[0,1] neg_hi:[0,1]
	v_pk_add_f32 v[76:77], v[76:77], v[140:141] op_sel_hi:[1,0] neg_lo:[0,1] neg_hi:[0,1]
	v_pk_add_f32 v[78:79], v[78:79], v[140:141] op_sel_hi:[1,0] neg_lo:[0,1] neg_hi:[0,1]
	v_pk_add_f32 v[80:81], v[80:81], v[140:141] op_sel_hi:[1,0] neg_lo:[0,1] neg_hi:[0,1]
	v_pk_add_f32 v[82:83], v[82:83], v[140:141] op_sel_hi:[1,0] neg_lo:[0,1] neg_hi:[0,1]
	v_pk_mul_f32 v[34:35], v[34:35], v[142:143] op_sel_hi:[1,0]
	v_pk_mul_f32 v[32:33], v[32:33], v[142:143] op_sel_hi:[1,0]
	v_pk_mul_f32 v[30:31], v[30:31], v[142:143] op_sel_hi:[1,0]
	v_pk_mul_f32 v[28:29], v[28:29], v[142:143] op_sel_hi:[1,0]
	v_pk_mul_f32 v[26:27], v[26:27], v[142:143] op_sel_hi:[1,0]
	v_pk_mul_f32 v[24:25], v[24:25], v[142:143] op_sel_hi:[1,0]
	v_pk_mul_f32 v[22:23], v[22:23], v[142:143] op_sel_hi:[1,0]
	v_pk_mul_f32 v[20:21], v[20:21], v[142:143] op_sel_hi:[1,0]
	v_pk_mul_f32 v[18:19], v[18:19], v[142:143] op_sel_hi:[1,0]
	v_pk_mul_f32 v[16:17], v[16:17], v[142:143] op_sel_hi:[1,0]
	v_pk_mul_f32 v[14:15], v[14:15], v[142:143] op_sel_hi:[1,0]
	v_pk_mul_f32 v[12:13], v[12:13], v[142:143] op_sel_hi:[1,0]
	v_pk_mul_f32 v[10:11], v[10:11], v[142:143] op_sel_hi:[1,0]
	v_pk_mul_f32 v[8:9], v[8:9], v[142:143] op_sel_hi:[1,0]
	v_pk_mul_f32 v[6:7], v[6:7], v[142:143] op_sel_hi:[1,0]
	v_pk_mul_f32 v[4:5], v[4:5], v[142:143] op_sel_hi:[1,0]

.LBB0_837:
	s_andn2_b64 vcc, exec, s[0:1]
	s_cbranch_vccnz .LBB0_843
	s_nop 8
	v_max_f32_e32 v142, v52, v53
	v_max3_f32 v142, v142, v54, v55
	v_max3_f32 v142, v142, v56, v57
	v_max3_f32 v142, v142, v58, v59
	v_max3_f32 v142, v142, v60, v61
	v_max3_f32 v142, v142, v62, v63
	v_max3_f32 v142, v142, v64, v65
	v_max3_f32 v142, v142, v66, v67
	v_mov_b32_e32 v143, v142
	s_nop 1
	v_permlane32_swap_b32_e32 v142, v143
	v_max_f32_e32 v142, v142, v143
	s_cmp_eq_u32 s96, 0
	s_cselect_b64 s[0:1], -1, 0
	v_cmp_lt_f32_e32 vcc, s95, v142
	s_or_b64 vcc, s[0:1], vcc
	s_cbranch_vccz .LBB0_840
	v_max_f32_e32 v143, v142, v142
	v_max_f32_e32 v143, 0, v143
	v_cndmask_b32_e64 v142, v143, v142, s[0:1]
	v_exp_f32_e64 v143, -v142
	v_add_f32_e32 v137, v137, v142
	v_sub_f32_e32 v83, v83, v142
	v_sub_f32_e32 v82, v82, v142
	v_cndmask_b32_e64 v144, v143, 1.0, s[0:1]
	v_pk_add_f32 v[52:53], v[52:53], v[142:143] op_sel_hi:[1,0] neg_lo:[0,1] neg_hi:[0,1]
	v_pk_add_f32 v[54:55], v[54:55], v[142:143] op_sel_hi:[1,0] neg_lo:[0,1] neg_hi:[0,1]
	v_mul_f32_e32 v36, v36, v144
	v_pk_add_f32 v[56:57], v[56:57], v[142:143] op_sel_hi:[1,0] neg_lo:[0,1] neg_hi:[0,1]
	v_pk_add_f32 v[58:59], v[58:59], v[142:143] op_sel_hi:[1,0] neg_lo:[0,1] neg_hi:[0,1]
	v_pk_add_f32 v[60:61], v[60:61], v[142:143] op_sel_hi:[1,0] neg_lo:[0,1] neg_hi:[0,1]
	v_pk_add_f32 v[62:63], v[62:63], v[142:143] op_sel_hi:[1,0] neg_lo:[0,1] neg_hi:[0,1]
	v_pk_add_f32 v[64:65], v[64:65], v[142:143] op_sel_hi:[1,0] neg_lo:[0,1] neg_hi:[0,1]
	v_pk_add_f32 v[66:67], v[66:67], v[142:143] op_sel_hi:[1,0] neg_lo:[0,1] neg_hi:[0,1]
	v_sub_f32_e32 v81, v81, v142
	v_sub_f32_e32 v80, v80, v142
	v_sub_f32_e32 v79, v79, v142
	v_sub_f32_e32 v78, v78, v142
	v_sub_f32_e32 v77, v77, v142
	v_sub_f32_e32 v76, v76, v142
	v_sub_f32_e32 v75, v75, v142
	v_sub_f32_e32 v74, v74, v142
	v_sub_f32_e32 v73, v73, v142
	v_sub_f32_e32 v72, v72, v142
	v_sub_f32_e32 v71, v71, v142
	v_sub_f32_e32 v70, v70, v142
	v_sub_f32_e32 v69, v69, v142
	v_sub_f32_e32 v68, v68, v142
	v_pk_mul_f32 v[34:35], v[34:35], v[144:145] op_sel_hi:[1,0]
	v_pk_mul_f32 v[32:33], v[32:33], v[144:145] op_sel_hi:[1,0]
	v_pk_mul_f32 v[30:31], v[30:31], v[144:145] op_sel_hi:[1,0]
	v_pk_mul_f32 v[28:29], v[28:29], v[144:145] op_sel_hi:[1,0]
	v_pk_mul_f32 v[26:27], v[26:27], v[144:145] op_sel_hi:[1,0]
	v_pk_mul_f32 v[24:25], v[24:25], v[144:145] op_sel_hi:[1,0]
	v_pk_mul_f32 v[22:23], v[22:23], v[144:145] op_sel_hi:[1,0]
	v_pk_mul_f32 v[20:21], v[20:21], v[144:145] op_sel_hi:[1,0]
	v_pk_mul_f32 v[18:19], v[18:19], v[144:145] op_sel_hi:[1,0]
	v_pk_mul_f32 v[16:17], v[16:17], v[144:145] op_sel_hi:[1,0]
	v_pk_mul_f32 v[14:15], v[14:15], v[144:145] op_sel_hi:[1,0]
	v_pk_mul_f32 v[12:13], v[12:13], v[144:145] op_sel_hi:[1,0]
	v_pk_mul_f32 v[10:11], v[10:11], v[144:145] op_sel_hi:[1,0]
	v_pk_mul_f32 v[8:9], v[8:9], v[144:145] op_sel_hi:[1,0]
	v_pk_mul_f32 v[6:7], v[6:7], v[144:145] op_sel_hi:[1,0]
	v_pk_mul_f32 v[4:5], v[4:5], v[144:145] op_sel_hi:[1,0]
.LBB0_840:
	v_add_u32_e32 v142, s91, v129
	v_add_u32_e32 v143, v142, v130
	v_exp_f32_e32 v52, v52
	v_exp_f32_e32 v53, v53
	v_exp_f32_e32 v54, v54
	v_exp_f32_e32 v55, v55
	ds_read_b64_tr_b16 v[144:145], v143 offset:16384
	ds_read_b64_tr_b16 v[146:147], v143 offset:17408
	v_exp_f32_e32 v56, v56
	v_exp_f32_e32 v57, v57
	v_exp_f32_e32 v58, v58
	v_exp_f32_e32 v59, v59
	v_cvt_pk_bf16_f32 v148, v52, v53
	v_cvt_pk_bf16_f32 v149, v54, v55
	v_cvt_pk_bf16_f32 v150, v56, v57
	v_cvt_pk_bf16_f32 v151, v58, v59
	v_add_u32_e32 v142, v142, v131
	v_exp_f32_e32 v60, v60
	s_waitcnt lgkmcnt(0)
	v_mfma_f32_32x32x16_bf16 v[4:19], v[144:147], v[148:151], v[4:19]
	ds_read_b64_tr_b16 v[144:145], v142 offset:16384
	ds_read_b64_tr_b16 v[146:147], v142 offset:17408
	v_exp_f32_e32 v61, v61
	v_exp_f32_e32 v62, v62
	v_exp_f32_e32 v63, v63
	v_exp_f32_e32 v64, v64
	v_exp_f32_e32 v65, v65
	v_exp_f32_e32 v66, v66
	s_waitcnt lgkmcnt(0)
	v_mfma_f32_32x32x16_bf16 v[20:35], v[144:147], v[148:151], v[20:35]
	ds_read_b64_tr_b16 v[144:145], v143 offset:18432
	ds_read_b64_tr_b16 v[146:147], v143 offset:19456
	v_exp_f32_e32 v67, v67
	v_mfma_f32_32x32x16_bf16 v[36:51], v[84:87], v[148:151], v[36:51]
	v_cvt_pk_bf16_f32 v148, v60, v61
	v_cvt_pk_bf16_f32 v149, v62, v63
	v_cvt_pk_bf16_f32 v150, v64, v65
	v_cvt_pk_bf16_f32 v151, v66, v67
	s_waitcnt lgkmcnt(0)
	s_nop 0
	v_mfma_f32_32x32x16_bf16 v[4:19], v[144:147], v[148:151], v[4:19]
	ds_read_b64_tr_b16 v[144:145], v142 offset:18432
	ds_read_b64_tr_b16 v[146:147], v142 offset:19456
	s_waitcnt lgkmcnt(0)
	v_mfma_f32_32x32x16_bf16 v[20:35], v[144:147], v[148:151], v[20:35]
	v_max_f32_e32 v144, v68, v69
	v_max3_f32 v144, v144, v70, v71
	v_max3_f32 v144, v144, v72, v73
	v_max3_f32 v144, v144, v74, v75
	v_max3_f32 v144, v144, v76, v77
	v_max3_f32 v144, v144, v78, v79
	v_mfma_f32_32x32x16_bf16 v[36:51], v[84:87], v[148:151], v[36:51]
	v_max3_f32 v144, v144, v80, v81
	v_max3_f32 v144, v144, v82, v83
	v_mov_b32_e32 v145, v144
	s_nop 1
	v_permlane32_swap_b32_e32 v144, v145
	v_max_f32_e32 v144, v144, v145
	v_cmp_lt_f32_e32 vcc, s95, v144
	s_cbranch_vccz .LBB0_842
	v_max_f32_e32 v144, v144, v144
	v_max_f32_e32 v144, 0, v144
	v_exp_f32_e64 v146, -v144
	v_add_f32_e32 v137, v137, v144
	v_pk_add_f32 v[68:69], v[68:69], v[144:145] op_sel_hi:[1,0] neg_lo:[0,1] neg_hi:[0,1]
	v_pk_add_f32 v[70:71], v[70:71], v[144:145] op_sel_hi:[1,0] neg_lo:[0,1] neg_hi:[0,1]
	v_mul_f32_e32 v36, v36, v146
	v_pk_add_f32 v[72:73], v[72:73], v[144:145] op_sel_hi:[1,0] neg_lo:[0,1] neg_hi:[0,1]
	v_pk_add_f32 v[74:75], v[74:75], v[144:145] op_sel_hi:[1,0] neg_lo:[0,1] neg_hi:[0,1]
	v_pk_add_f32 v[76:77], v[76:77], v[144:145] op_sel_hi:[1,0] neg_lo:[0,1] neg_hi:[0,1]
	v_pk_add_f32 v[78:79], v[78:79], v[144:145] op_sel_hi:[1,0] neg_lo:[0,1] neg_hi:[0,1]
	v_pk_add_f32 v[80:81], v[80:81], v[144:145] op_sel_hi:[1,0] neg_lo:[0,1] neg_hi:[0,1]
	v_pk_add_f32 v[82:83], v[82:83], v[144:145] op_sel_hi:[1,0] neg_lo:[0,1] neg_hi:[0,1]
	v_pk_mul_f32 v[34:35], v[34:35], v[146:147] op_sel_hi:[1,0]
	v_pk_mul_f32 v[32:33], v[32:33], v[146:147] op_sel_hi:[1,0]
	v_pk_mul_f32 v[30:31], v[30:31], v[146:147] op_sel_hi:[1,0]
	v_pk_mul_f32 v[28:29], v[28:29], v[146:147] op_sel_hi:[1,0]
	v_pk_mul_f32 v[26:27], v[26:27], v[146:147] op_sel_hi:[1,0]
	v_pk_mul_f32 v[24:25], v[24:25], v[146:147] op_sel_hi:[1,0]
	v_pk_mul_f32 v[22:23], v[22:23], v[146:147] op_sel_hi:[1,0]
	v_pk_mul_f32 v[20:21], v[20:21], v[146:147] op_sel_hi:[1,0]
	v_pk_mul_f32 v[18:19], v[18:19], v[146:147] op_sel_hi:[1,0]
	v_pk_mul_f32 v[16:17], v[16:17], v[146:147] op_sel_hi:[1,0]
	v_pk_mul_f32 v[14:15], v[14:15], v[146:147] op_sel_hi:[1,0]
	v_pk_mul_f32 v[12:13], v[12:13], v[146:147] op_sel_hi:[1,0]
	v_pk_mul_f32 v[10:11], v[10:11], v[146:147] op_sel_hi:[1,0]
	v_pk_mul_f32 v[8:9], v[8:9], v[146:147] op_sel_hi:[1,0]
	v_pk_mul_f32 v[6:7], v[6:7], v[146:147] op_sel_hi:[1,0]
	v_pk_mul_f32 v[4:5], v[4:5], v[146:147] op_sel_hi:[1,0]

.LBB0_846:
	s_andn2_b64 vcc, exec, s[0:1]
	s_cbranch_vccnz .LBB0_852
	s_nop 8
	v_max_f32_e32 v2, v52, v53
	v_max3_f32 v2, v2, v54, v55
	v_max3_f32 v2, v2, v56, v57
	v_max3_f32 v2, v2, v58, v59
	v_max3_f32 v2, v2, v60, v61
	v_max3_f32 v2, v2, v62, v63
	v_max3_f32 v2, v2, v64, v65
	v_max3_f32 v2, v2, v66, v67
	v_mov_b32_e32 v138, v2
	s_nop 1
	v_permlane32_swap_b32_e32 v2, v138
	v_max_f32_e32 v2, v2, v138
	v_cmp_lt_f32_e32 vcc, s95, v2
	s_cbranch_vccz .LBB0_849
	v_max_f32_e32 v2, v2, v2
	v_max_f32_e32 v2, 0, v2
	v_exp_f32_e64 v138, -v2
	v_add_f32_e32 v137, v137, v2
	v_pk_add_f32 v[52:53], v[52:53], v[2:3] op_sel_hi:[1,0] neg_lo:[0,1] neg_hi:[0,1]
	v_pk_add_f32 v[54:55], v[54:55], v[2:3] op_sel_hi:[1,0] neg_lo:[0,1] neg_hi:[0,1]
	v_mul_f32_e32 v36, v36, v138
	v_pk_add_f32 v[56:57], v[56:57], v[2:3] op_sel_hi:[1,0] neg_lo:[0,1] neg_hi:[0,1]
	v_pk_add_f32 v[58:59], v[58:59], v[2:3] op_sel_hi:[1,0] neg_lo:[0,1] neg_hi:[0,1]
	v_pk_add_f32 v[60:61], v[60:61], v[2:3] op_sel_hi:[1,0] neg_lo:[0,1] neg_hi:[0,1]
	v_pk_add_f32 v[62:63], v[62:63], v[2:3] op_sel_hi:[1,0] neg_lo:[0,1] neg_hi:[0,1]
	v_pk_add_f32 v[64:65], v[64:65], v[2:3] op_sel_hi:[1,0] neg_lo:[0,1] neg_hi:[0,1]
	v_pk_add_f32 v[66:67], v[66:67], v[2:3] op_sel_hi:[1,0] neg_lo:[0,1] neg_hi:[0,1]
	v_sub_f32_e32 v83, v83, v2
	v_sub_f32_e32 v82, v82, v2
	v_sub_f32_e32 v81, v81, v2
	v_sub_f32_e32 v80, v80, v2
	v_sub_f32_e32 v79, v79, v2
	v_sub_f32_e32 v78, v78, v2
	v_sub_f32_e32 v77, v77, v2
	v_sub_f32_e32 v76, v76, v2
	v_sub_f32_e32 v75, v75, v2
	v_sub_f32_e32 v74, v74, v2
	v_sub_f32_e32 v73, v73, v2
	v_sub_f32_e32 v72, v72, v2
	v_sub_f32_e32 v71, v71, v2
	v_sub_f32_e32 v70, v70, v2
	v_sub_f32_e32 v69, v69, v2
	v_sub_f32_e32 v68, v68, v2
	v_pk_mul_f32 v[34:35], v[34:35], v[138:139] op_sel_hi:[1,0]
	v_pk_mul_f32 v[32:33], v[32:33], v[138:139] op_sel_hi:[1,0]
	v_pk_mul_f32 v[30:31], v[30:31], v[138:139] op_sel_hi:[1,0]
	v_pk_mul_f32 v[28:29], v[28:29], v[138:139] op_sel_hi:[1,0]
	v_pk_mul_f32 v[26:27], v[26:27], v[138:139] op_sel_hi:[1,0]
	v_pk_mul_f32 v[24:25], v[24:25], v[138:139] op_sel_hi:[1,0]
	v_pk_mul_f32 v[22:23], v[22:23], v[138:139] op_sel_hi:[1,0]
	v_pk_mul_f32 v[20:21], v[20:21], v[138:139] op_sel_hi:[1,0]
	v_pk_mul_f32 v[18:19], v[18:19], v[138:139] op_sel_hi:[1,0]
	v_pk_mul_f32 v[16:17], v[16:17], v[138:139] op_sel_hi:[1,0]
	v_pk_mul_f32 v[14:15], v[14:15], v[138:139] op_sel_hi:[1,0]
	v_pk_mul_f32 v[12:13], v[12:13], v[138:139] op_sel_hi:[1,0]
	v_pk_mul_f32 v[10:11], v[10:11], v[138:139] op_sel_hi:[1,0]
	v_pk_mul_f32 v[8:9], v[8:9], v[138:139] op_sel_hi:[1,0]
	v_pk_mul_f32 v[6:7], v[6:7], v[138:139] op_sel_hi:[1,0]
	v_pk_mul_f32 v[4:5], v[4:5], v[138:139] op_sel_hi:[1,0]
.LBB0_849:
	v_add_u32_e32 v2, s91, v129
	v_add_u32_e32 v138, v2, v130
	v_exp_f32_e32 v52, v52
	v_exp_f32_e32 v53, v53
	v_exp_f32_e32 v54, v54
	v_exp_f32_e32 v55, v55
	ds_read_b64_tr_b16 v[140:141], v138 offset:24576
	ds_read_b64_tr_b16 v[142:143], v138 offset:25600
	v_exp_f32_e32 v56, v56
	v_exp_f32_e32 v57, v57
	v_exp_f32_e32 v58, v58
	v_exp_f32_e32 v59, v59
	v_cvt_pk_bf16_f32 v144, v52, v53
	v_cvt_pk_bf16_f32 v145, v54, v55
	v_cvt_pk_bf16_f32 v146, v56, v57
	v_cvt_pk_bf16_f32 v147, v58, v59
	v_add_u32_e32 v2, v2, v131
	v_exp_f32_e32 v60, v60
	s_waitcnt lgkmcnt(0)
	v_mfma_f32_32x32x16_bf16 v[4:19], v[140:143], v[144:147], v[4:19]
	ds_read_b64_tr_b16 v[140:141], v2 offset:24576
	ds_read_b64_tr_b16 v[142:143], v2 offset:25600
	v_exp_f32_e32 v61, v61
	v_exp_f32_e32 v62, v62
	v_exp_f32_e32 v63, v63
	v_exp_f32_e32 v64, v64
	v_exp_f32_e32 v65, v65
	v_exp_f32_e32 v66, v66
	s_waitcnt lgkmcnt(0)
	v_mfma_f32_32x32x16_bf16 v[20:35], v[140:143], v[144:147], v[20:35]
	ds_read_b64_tr_b16 v[140:141], v138 offset:26624
	ds_read_b64_tr_b16 v[142:143], v138 offset:27648
	v_exp_f32_e32 v67, v67
	v_max_f32_e32 v139, v69, v69
	v_mfma_f32_32x32x16_bf16 v[36:51], v[84:87], v[144:147], v[36:51]
	v_cvt_pk_bf16_f32 v144, v60, v61
	v_cvt_pk_bf16_f32 v145, v62, v63
	v_cvt_pk_bf16_f32 v146, v64, v65
	v_cvt_pk_bf16_f32 v147, v66, v67
	s_waitcnt lgkmcnt(0)
	s_nop 0
	v_mfma_f32_32x32x16_bf16 v[4:19], v[140:143], v[144:147], v[4:19]
	ds_read_b64_tr_b16 v[140:141], v2 offset:26624
	ds_read_b64_tr_b16 v[142:143], v2 offset:27648
	s_waitcnt lgkmcnt(0)
	v_mfma_f32_32x32x16_bf16 v[20:35], v[140:143], v[144:147], v[20:35]
	v_max_f32_e32 v140, v68, v68
	v_max_f32_e32 v139, v140, v139
	v_max3_f32 v139, v139, v70, v71
	v_max3_f32 v139, v139, v72, v73
	v_max3_f32 v139, v139, v74, v75
	v_max3_f32 v139, v139, v76, v77
	v_max3_f32 v139, v139, v78, v79
	v_mfma_f32_32x32x16_bf16 v[36:51], v[84:87], v[144:147], v[36:51]
	v_max3_f32 v139, v139, v80, v81
	v_max3_f32 v139, v139, v82, v83
	v_mov_b32_e32 v140, v139
	s_nop 1
	v_permlane32_swap_b32_e32 v139, v140
	v_max_f32_e32 v139, v139, v140
	v_cmp_lt_f32_e32 vcc, s95, v139
	s_cbranch_vccz .LBB0_851
	v_max_f32_e32 v139, v139, v139
	v_max_f32_e32 v140, 0, v139
	v_exp_f32_e64 v142, -v140
	v_add_f32_e32 v137, v137, v140
	v_pk_add_f32 v[68:69], v[68:69], v[140:141] op_sel_hi:[1,0] neg_lo:[0,1] neg_hi:[0,1]
	v_pk_add_f32 v[70:71], v[70:71], v[140:141] op_sel_hi:[1,0] neg_lo:[0,1] neg_hi:[0,1]
	v_mul_f32_e32 v36, v36, v142
	v_pk_add_f32 v[72:73], v[72:73], v[140:141] op_sel_hi:[1,0] neg_lo:[0,1] neg_hi:[0,1]
	v_pk_add_f32 v[74:75], v[74:75], v[140:141] op_sel_hi:[1,0] neg_lo:[0,1] neg_hi:[0,1]
	v_pk_add_f32 v[76:77], v[76:77], v[140:141] op_sel_hi:[1,0] neg_lo:[0,1] neg_hi:[0,1]
	v_pk_add_f32 v[78:79], v[78:79], v[140:141] op_sel_hi:[1,0] neg_lo:[0,1] neg_hi:[0,1]
	v_pk_add_f32 v[80:81], v[80:81], v[140:141] op_sel_hi:[1,0] neg_lo:[0,1] neg_hi:[0,1]
	v_pk_add_f32 v[82:83], v[82:83], v[140:141] op_sel_hi:[1,0] neg_lo:[0,1] neg_hi:[0,1]
	v_pk_mul_f32 v[34:35], v[34:35], v[142:143] op_sel_hi:[1,0]
	v_pk_mul_f32 v[32:33], v[32:33], v[142:143] op_sel_hi:[1,0]
	v_pk_mul_f32 v[30:31], v[30:31], v[142:143] op_sel_hi:[1,0]
	v_pk_mul_f32 v[28:29], v[28:29], v[142:143] op_sel_hi:[1,0]
	v_pk_mul_f32 v[26:27], v[26:27], v[142:143] op_sel_hi:[1,0]
	v_pk_mul_f32 v[24:25], v[24:25], v[142:143] op_sel_hi:[1,0]
	v_pk_mul_f32 v[22:23], v[22:23], v[142:143] op_sel_hi:[1,0]
	v_pk_mul_f32 v[20:21], v[20:21], v[142:143] op_sel_hi:[1,0]
	v_pk_mul_f32 v[18:19], v[18:19], v[142:143] op_sel_hi:[1,0]
	v_pk_mul_f32 v[16:17], v[16:17], v[142:143] op_sel_hi:[1,0]
	v_pk_mul_f32 v[14:15], v[14:15], v[142:143] op_sel_hi:[1,0]
	v_pk_mul_f32 v[12:13], v[12:13], v[142:143] op_sel_hi:[1,0]
	v_pk_mul_f32 v[10:11], v[10:11], v[142:143] op_sel_hi:[1,0]
	v_pk_mul_f32 v[8:9], v[8:9], v[142:143] op_sel_hi:[1,0]
	v_pk_mul_f32 v[6:7], v[6:7], v[142:143] op_sel_hi:[1,0]
	v_pk_mul_f32 v[4:5], v[4:5], v[142:143] op_sel_hi:[1,0]

.LBB0_949:
	s_andn2_b64 vcc, exec, s[0:1]
	s_cbranch_vccnz .LBB0_955
	s_nop 8
	v_max_f32_e32 v122, v50, v51
	v_max3_f32 v122, v122, v52, v53
	v_max3_f32 v122, v122, v54, v55
	v_max3_f32 v122, v122, v56, v57
	v_max3_f32 v122, v122, v58, v59
	v_max3_f32 v122, v122, v60, v61
	v_max3_f32 v122, v122, v62, v63
	v_max3_f32 v122, v122, v64, v65
	v_mov_b32_e32 v123, v122
	s_nop 1
	v_permlane32_swap_b32_e32 v122, v123
	v_max_f32_e32 v122, v122, v123
	s_cmp_eq_u32 s90, 0
	s_cselect_b64 s[0:1], -1, 0
	v_cmp_lt_f32_e32 vcc, s92, v122
	s_or_b64 vcc, s[0:1], vcc
	s_cbranch_vccz .LBB0_952
	v_max_f32_e32 v123, v122, v122
	v_max_f32_e32 v123, 0, v123
	v_cndmask_b32_e64 v122, v123, v122, s[0:1]
	v_exp_f32_e64 v123, -v122
	v_add_f32_e32 v113, v113, v122
	v_sub_f32_e32 v81, v81, v122
	v_sub_f32_e32 v80, v80, v122
	v_cndmask_b32_e64 v134, v123, 1.0, s[0:1]
	v_pk_add_f32 v[50:51], v[50:51], v[122:123] op_sel_hi:[1,0] neg_lo:[0,1] neg_hi:[0,1]
	v_pk_add_f32 v[52:53], v[52:53], v[122:123] op_sel_hi:[1,0] neg_lo:[0,1] neg_hi:[0,1]
	v_mul_f32_e32 v34, v34, v134
	v_pk_add_f32 v[54:55], v[54:55], v[122:123] op_sel_hi:[1,0] neg_lo:[0,1] neg_hi:[0,1]
	v_pk_add_f32 v[56:57], v[56:57], v[122:123] op_sel_hi:[1,0] neg_lo:[0,1] neg_hi:[0,1]
	v_pk_add_f32 v[58:59], v[58:59], v[122:123] op_sel_hi:[1,0] neg_lo:[0,1] neg_hi:[0,1]
	v_pk_add_f32 v[60:61], v[60:61], v[122:123] op_sel_hi:[1,0] neg_lo:[0,1] neg_hi:[0,1]
	v_pk_add_f32 v[62:63], v[62:63], v[122:123] op_sel_hi:[1,0] neg_lo:[0,1] neg_hi:[0,1]
	v_pk_add_f32 v[64:65], v[64:65], v[122:123] op_sel_hi:[1,0] neg_lo:[0,1] neg_hi:[0,1]
	v_sub_f32_e32 v79, v79, v122
	v_sub_f32_e32 v78, v78, v122
	v_sub_f32_e32 v77, v77, v122
	v_sub_f32_e32 v76, v76, v122
	v_sub_f32_e32 v75, v75, v122
	v_sub_f32_e32 v74, v74, v122
	v_sub_f32_e32 v73, v73, v122
	v_sub_f32_e32 v72, v72, v122
	v_sub_f32_e32 v71, v71, v122
	v_sub_f32_e32 v70, v70, v122
	v_sub_f32_e32 v69, v69, v122
	v_sub_f32_e32 v68, v68, v122
	v_sub_f32_e32 v67, v67, v122
	v_sub_f32_e32 v66, v66, v122
	v_pk_mul_f32 v[32:33], v[32:33], v[134:135] op_sel_hi:[1,0]
	v_pk_mul_f32 v[30:31], v[30:31], v[134:135] op_sel_hi:[1,0]
	v_pk_mul_f32 v[28:29], v[28:29], v[134:135] op_sel_hi:[1,0]
	v_pk_mul_f32 v[26:27], v[26:27], v[134:135] op_sel_hi:[1,0]
	v_pk_mul_f32 v[24:25], v[24:25], v[134:135] op_sel_hi:[1,0]
	v_pk_mul_f32 v[22:23], v[22:23], v[134:135] op_sel_hi:[1,0]
	v_pk_mul_f32 v[20:21], v[20:21], v[134:135] op_sel_hi:[1,0]
	v_pk_mul_f32 v[18:19], v[18:19], v[134:135] op_sel_hi:[1,0]
	v_pk_mul_f32 v[16:17], v[16:17], v[134:135] op_sel_hi:[1,0]
	v_pk_mul_f32 v[14:15], v[14:15], v[134:135] op_sel_hi:[1,0]
	v_pk_mul_f32 v[12:13], v[12:13], v[134:135] op_sel_hi:[1,0]
	v_pk_mul_f32 v[10:11], v[10:11], v[134:135] op_sel_hi:[1,0]
	v_pk_mul_f32 v[8:9], v[8:9], v[134:135] op_sel_hi:[1,0]
	v_pk_mul_f32 v[6:7], v[6:7], v[134:135] op_sel_hi:[1,0]
	v_pk_mul_f32 v[4:5], v[4:5], v[134:135] op_sel_hi:[1,0]
	v_pk_mul_f32 v[2:3], v[2:3], v[134:135] op_sel_hi:[1,0]
.LBB0_952:
	v_add_u32_e32 v122, s93, v129
	v_add_u32_e32 v123, v122, v130
	v_exp_f32_e32 v50, v50
	v_exp_f32_e32 v51, v51
	v_exp_f32_e32 v52, v52
	v_exp_f32_e32 v53, v53
	ds_read_b64_tr_b16 v[138:139], v123 offset:16384
	ds_read_b64_tr_b16 v[140:141], v123 offset:17408
	v_exp_f32_e32 v54, v54
	v_exp_f32_e32 v55, v55
	v_exp_f32_e32 v56, v56
	v_exp_f32_e32 v57, v57
	v_cvt_pk_bf16_f32 v142, v50, v51
	v_cvt_pk_bf16_f32 v143, v52, v53
	v_cvt_pk_bf16_f32 v144, v54, v55
	v_cvt_pk_bf16_f32 v145, v56, v57
	v_add_u32_e32 v122, v122, v131
	v_exp_f32_e32 v58, v58
	s_waitcnt lgkmcnt(0)
	v_mfma_f32_32x32x16_bf16 v[2:17], v[138:141], v[142:145], v[2:17]
	ds_read_b64_tr_b16 v[138:139], v122 offset:16384
	ds_read_b64_tr_b16 v[140:141], v122 offset:17408
	v_exp_f32_e32 v59, v59
	v_exp_f32_e32 v60, v60
	v_exp_f32_e32 v61, v61
	v_exp_f32_e32 v62, v62
	v_exp_f32_e32 v63, v63
	v_exp_f32_e32 v64, v64
	s_waitcnt lgkmcnt(0)
	v_mfma_f32_32x32x16_bf16 v[18:33], v[138:141], v[142:145], v[18:33]
	ds_read_b64_tr_b16 v[138:139], v123 offset:18432
	ds_read_b64_tr_b16 v[140:141], v123 offset:19456
	v_exp_f32_e32 v65, v65
	v_max_f32_e32 v133, v66, v67
	v_max3_f32 v133, v133, v68, v69
	v_max3_f32 v133, v133, v70, v71
	v_mfma_f32_32x32x16_bf16 v[34:49], v[84:87], v[142:145], v[34:49]
	v_cvt_pk_bf16_f32 v142, v58, v59
	v_cvt_pk_bf16_f32 v143, v60, v61
	v_cvt_pk_bf16_f32 v144, v62, v63
	v_cvt_pk_bf16_f32 v145, v64, v65
	v_max3_f32 v133, v133, v72, v73
	v_max3_f32 v133, v133, v74, v75
	v_max3_f32 v133, v133, v76, v77
	s_waitcnt lgkmcnt(0)
	v_mfma_f32_32x32x16_bf16 v[2:17], v[138:141], v[142:145], v[2:17]
	ds_read_b64_tr_b16 v[138:139], v122 offset:18432
	ds_read_b64_tr_b16 v[140:141], v122 offset:19456
	v_max3_f32 v133, v133, v78, v79
	v_max3_f32 v133, v133, v80, v81
	v_mov_b32_e32 v134, v133
	s_nop 1
	v_permlane32_swap_b32_e32 v133, v134
	v_max_f32_e32 v134, v134, v134
	s_waitcnt lgkmcnt(0)
	v_mfma_f32_32x32x16_bf16 v[18:33], v[138:141], v[142:145], v[18:33]
	v_max_f32_e32 v133, v133, v133
	v_max_f32_e32 v133, v133, v134
	v_cmp_lt_f32_e32 vcc, s92, v133
	v_mfma_f32_32x32x16_bf16 v[34:49], v[84:87], v[142:145], v[34:49]
	s_cbranch_vccz .LBB0_954
	v_max_f32_e32 v133, v133, v133
	v_max_f32_e32 v134, 0, v133
	v_exp_f32_e64 v138, -v134
	v_add_f32_e32 v113, v113, v134
	v_pk_add_f32 v[66:67], v[66:67], v[134:135] op_sel_hi:[1,0] neg_lo:[0,1] neg_hi:[0,1]
	v_pk_add_f32 v[68:69], v[68:69], v[134:135] op_sel_hi:[1,0] neg_lo:[0,1] neg_hi:[0,1]
	s_nop 4
	v_mul_f32_e32 v34, v34, v138
	v_pk_add_f32 v[70:71], v[70:71], v[134:135] op_sel_hi:[1,0] neg_lo:[0,1] neg_hi:[0,1]
	v_pk_add_f32 v[72:73], v[72:73], v[134:135] op_sel_hi:[1,0] neg_lo:[0,1] neg_hi:[0,1]
	v_pk_add_f32 v[74:75], v[74:75], v[134:135] op_sel_hi:[1,0] neg_lo:[0,1] neg_hi:[0,1]
	v_pk_add_f32 v[76:77], v[76:77], v[134:135] op_sel_hi:[1,0] neg_lo:[0,1] neg_hi:[0,1]
	v_pk_add_f32 v[78:79], v[78:79], v[134:135] op_sel_hi:[1,0] neg_lo:[0,1] neg_hi:[0,1]
	v_pk_add_f32 v[80:81], v[80:81], v[134:135] op_sel_hi:[1,0] neg_lo:[0,1] neg_hi:[0,1]
	v_pk_mul_f32 v[32:33], v[32:33], v[138:139] op_sel_hi:[1,0]
	v_pk_mul_f32 v[30:31], v[30:31], v[138:139] op_sel_hi:[1,0]
	v_pk_mul_f32 v[28:29], v[28:29], v[138:139] op_sel_hi:[1,0]
	v_pk_mul_f32 v[26:27], v[26:27], v[138:139] op_sel_hi:[1,0]
	v_pk_mul_f32 v[24:25], v[24:25], v[138:139] op_sel_hi:[1,0]
	v_pk_mul_f32 v[22:23], v[22:23], v[138:139] op_sel_hi:[1,0]
	v_pk_mul_f32 v[20:21], v[20:21], v[138:139] op_sel_hi:[1,0]
	v_pk_mul_f32 v[18:19], v[18:19], v[138:139] op_sel_hi:[1,0]
	v_pk_mul_f32 v[16:17], v[16:17], v[138:139] op_sel_hi:[1,0]
	v_pk_mul_f32 v[14:15], v[14:15], v[138:139] op_sel_hi:[1,0]
	v_pk_mul_f32 v[12:13], v[12:13], v[138:139] op_sel_hi:[1,0]
	v_pk_mul_f32 v[10:11], v[10:11], v[138:139] op_sel_hi:[1,0]
	v_pk_mul_f32 v[8:9], v[8:9], v[138:139] op_sel_hi:[1,0]
	v_pk_mul_f32 v[6:7], v[6:7], v[138:139] op_sel_hi:[1,0]
	v_pk_mul_f32 v[4:5], v[4:5], v[138:139] op_sel_hi:[1,0]
	v_pk_mul_f32 v[2:3], v[2:3], v[138:139] op_sel_hi:[1,0]

.LBB0_958:
	s_andn2_b64 vcc, exec, s[0:1]
	s_cbranch_vccnz .LBB0_964
	s_nop 8
	v_max_f32_e32 v0, v50, v51
	v_max3_f32 v0, v0, v52, v53
	v_max3_f32 v0, v0, v54, v55
	v_max3_f32 v0, v0, v56, v57
	v_max3_f32 v0, v0, v58, v59
	v_max3_f32 v0, v0, v60, v61
	v_max3_f32 v0, v0, v62, v63
	v_max3_f32 v0, v0, v64, v65
	v_mov_b32_e32 v115, v0
	s_nop 1
	v_permlane32_swap_b32_e32 v0, v115
	v_max_f32_e32 v0, v0, v115
	v_cmp_lt_f32_e32 vcc, s92, v0
	s_cbranch_vccz .LBB0_961
	v_max_f32_e32 v0, v0, v0
	v_max_f32_e32 v0, 0, v0
	v_exp_f32_e64 v122, -v0
	v_add_f32_e32 v113, v113, v0
	v_pk_add_f32 v[50:51], v[50:51], v[0:1] op_sel_hi:[1,0] neg_lo:[0,1] neg_hi:[0,1]
	v_pk_add_f32 v[52:53], v[52:53], v[0:1] op_sel_hi:[1,0] neg_lo:[0,1] neg_hi:[0,1]
	v_mul_f32_e32 v34, v34, v122
	v_pk_add_f32 v[54:55], v[54:55], v[0:1] op_sel_hi:[1,0] neg_lo:[0,1] neg_hi:[0,1]
	v_pk_add_f32 v[56:57], v[56:57], v[0:1] op_sel_hi:[1,0] neg_lo:[0,1] neg_hi:[0,1]
	v_pk_add_f32 v[58:59], v[58:59], v[0:1] op_sel_hi:[1,0] neg_lo:[0,1] neg_hi:[0,1]
	v_pk_add_f32 v[60:61], v[60:61], v[0:1] op_sel_hi:[1,0] neg_lo:[0,1] neg_hi:[0,1]
	v_pk_add_f32 v[62:63], v[62:63], v[0:1] op_sel_hi:[1,0] neg_lo:[0,1] neg_hi:[0,1]
	v_pk_add_f32 v[64:65], v[64:65], v[0:1] op_sel_hi:[1,0] neg_lo:[0,1] neg_hi:[0,1]
	v_sub_f32_e32 v81, v81, v0
	v_sub_f32_e32 v80, v80, v0
	v_sub_f32_e32 v79, v79, v0
	v_sub_f32_e32 v78, v78, v0
	v_sub_f32_e32 v77, v77, v0
	v_sub_f32_e32 v76, v76, v0
	v_sub_f32_e32 v75, v75, v0
	v_sub_f32_e32 v74, v74, v0
	v_sub_f32_e32 v73, v73, v0
	v_sub_f32_e32 v72, v72, v0
	v_sub_f32_e32 v71, v71, v0
	v_sub_f32_e32 v70, v70, v0
	v_sub_f32_e32 v69, v69, v0
	v_sub_f32_e32 v68, v68, v0
	v_sub_f32_e32 v67, v67, v0
	v_sub_f32_e32 v66, v66, v0
	v_pk_mul_f32 v[32:33], v[32:33], v[122:123] op_sel_hi:[1,0]
	v_pk_mul_f32 v[30:31], v[30:31], v[122:123] op_sel_hi:[1,0]
	v_pk_mul_f32 v[28:29], v[28:29], v[122:123] op_sel_hi:[1,0]
	v_pk_mul_f32 v[26:27], v[26:27], v[122:123] op_sel_hi:[1,0]
	v_pk_mul_f32 v[24:25], v[24:25], v[122:123] op_sel_hi:[1,0]
	v_pk_mul_f32 v[22:23], v[22:23], v[122:123] op_sel_hi:[1,0]
	v_pk_mul_f32 v[20:21], v[20:21], v[122:123] op_sel_hi:[1,0]
	v_pk_mul_f32 v[18:19], v[18:19], v[122:123] op_sel_hi:[1,0]
	v_pk_mul_f32 v[16:17], v[16:17], v[122:123] op_sel_hi:[1,0]
	v_pk_mul_f32 v[14:15], v[14:15], v[122:123] op_sel_hi:[1,0]
	v_pk_mul_f32 v[12:13], v[12:13], v[122:123] op_sel_hi:[1,0]
	v_pk_mul_f32 v[10:11], v[10:11], v[122:123] op_sel_hi:[1,0]
	v_pk_mul_f32 v[8:9], v[8:9], v[122:123] op_sel_hi:[1,0]
	v_pk_mul_f32 v[6:7], v[6:7], v[122:123] op_sel_hi:[1,0]
	v_pk_mul_f32 v[4:5], v[4:5], v[122:123] op_sel_hi:[1,0]
	v_pk_mul_f32 v[2:3], v[2:3], v[122:123] op_sel_hi:[1,0]
.LBB0_961:
	v_add_u32_e32 v0, s93, v129
	v_add_u32_e32 v115, v0, v130
	v_exp_f32_e32 v50, v50
	v_exp_f32_e32 v51, v51
	v_exp_f32_e32 v52, v52
	v_exp_f32_e32 v53, v53
	ds_read_b64_tr_b16 v[138:139], v115 offset:24576
	ds_read_b64_tr_b16 v[140:141], v115 offset:25600
	v_exp_f32_e32 v54, v54
	v_exp_f32_e32 v55, v55
	v_exp_f32_e32 v56, v56
	v_exp_f32_e32 v57, v57
	v_cvt_pk_bf16_f32 v142, v50, v51
	v_cvt_pk_bf16_f32 v143, v52, v53
	v_cvt_pk_bf16_f32 v144, v54, v55
	v_cvt_pk_bf16_f32 v145, v56, v57
	v_add_u32_e32 v0, v0, v131
	v_exp_f32_e32 v58, v58
	s_waitcnt lgkmcnt(0)
	v_mfma_f32_32x32x16_bf16 v[2:17], v[138:141], v[142:145], v[2:17]
	ds_read_b64_tr_b16 v[138:139], v0 offset:24576
	ds_read_b64_tr_b16 v[140:141], v0 offset:25600
	v_exp_f32_e32 v59, v59
	v_exp_f32_e32 v60, v60
	v_exp_f32_e32 v61, v61
	v_exp_f32_e32 v62, v62
	v_exp_f32_e32 v63, v63
	v_exp_f32_e32 v64, v64
	s_waitcnt lgkmcnt(0)
	v_mfma_f32_32x32x16_bf16 v[18:33], v[138:141], v[142:145], v[18:33]
	ds_read_b64_tr_b16 v[138:139], v115 offset:26624
	ds_read_b64_tr_b16 v[140:141], v115 offset:27648
	v_exp_f32_e32 v65, v65
	v_max_f32_e32 v117, v66, v67
	v_max3_f32 v117, v117, v68, v69
	v_max3_f32 v117, v117, v70, v71
	v_mfma_f32_32x32x16_bf16 v[34:49], v[84:87], v[142:145], v[34:49]
	v_cvt_pk_bf16_f32 v142, v58, v59
	v_cvt_pk_bf16_f32 v143, v60, v61
	v_cvt_pk_bf16_f32 v144, v62, v63
	v_cvt_pk_bf16_f32 v145, v64, v65
	v_max3_f32 v117, v117, v72, v73
	v_max3_f32 v117, v117, v74, v75
	v_max3_f32 v117, v117, v76, v77
	s_waitcnt lgkmcnt(0)
	v_mfma_f32_32x32x16_bf16 v[2:17], v[138:141], v[142:145], v[2:17]
	ds_read_b64_tr_b16 v[138:139], v0 offset:26624
	ds_read_b64_tr_b16 v[140:141], v0 offset:27648
	v_max3_f32 v117, v117, v78, v79
	v_max3_f32 v117, v117, v80, v81
	v_mov_b32_e32 v119, v117
	s_nop 1
	v_permlane32_swap_b32_e32 v117, v119
	v_max_f32_e32 v119, v119, v119
	s_waitcnt lgkmcnt(0)
	v_mfma_f32_32x32x16_bf16 v[18:33], v[138:141], v[142:145], v[18:33]
	v_max_f32_e32 v117, v117, v117
	v_max_f32_e32 v117, v117, v119
	v_cmp_lt_f32_e32 vcc, s92, v117
	v_mfma_f32_32x32x16_bf16 v[34:49], v[84:87], v[142:145], v[34:49]
	s_cbranch_vccz .LBB0_963
	v_max_f32_e32 v117, v117, v117
	v_max_f32_e32 v122, 0, v117
	v_exp_f32_e64 v134, -v122
	v_add_f32_e32 v113, v113, v122
	v_pk_add_f32 v[66:67], v[66:67], v[122:123] op_sel_hi:[1,0] neg_lo:[0,1] neg_hi:[0,1]
	v_pk_add_f32 v[68:69], v[68:69], v[122:123] op_sel_hi:[1,0] neg_lo:[0,1] neg_hi:[0,1]
	s_nop 4
	v_mul_f32_e32 v34, v34, v134
	v_pk_add_f32 v[70:71], v[70:71], v[122:123] op_sel_hi:[1,0] neg_lo:[0,1] neg_hi:[0,1]
	v_pk_add_f32 v[72:73], v[72:73], v[122:123] op_sel_hi:[1,0] neg_lo:[0,1] neg_hi:[0,1]
	v_pk_add_f32 v[74:75], v[74:75], v[122:123] op_sel_hi:[1,0] neg_lo:[0,1] neg_hi:[0,1]
	v_pk_add_f32 v[76:77], v[76:77], v[122:123] op_sel_hi:[1,0] neg_lo:[0,1] neg_hi:[0,1]
	v_pk_add_f32 v[78:79], v[78:79], v[122:123] op_sel_hi:[1,0] neg_lo:[0,1] neg_hi:[0,1]
	v_pk_add_f32 v[80:81], v[80:81], v[122:123] op_sel_hi:[1,0] neg_lo:[0,1] neg_hi:[0,1]
	v_pk_mul_f32 v[32:33], v[32:33], v[134:135] op_sel_hi:[1,0]
	v_pk_mul_f32 v[30:31], v[30:31], v[134:135] op_sel_hi:[1,0]
	v_pk_mul_f32 v[28:29], v[28:29], v[134:135] op_sel_hi:[1,0]
	v_pk_mul_f32 v[26:27], v[26:27], v[134:135] op_sel_hi:[1,0]
	v_pk_mul_f32 v[24:25], v[24:25], v[134:135] op_sel_hi:[1,0]
	v_pk_mul_f32 v[22:23], v[22:23], v[134:135] op_sel_hi:[1,0]
	v_pk_mul_f32 v[20:21], v[20:21], v[134:135] op_sel_hi:[1,0]
	v_pk_mul_f32 v[18:19], v[18:19], v[134:135] op_sel_hi:[1,0]
	v_pk_mul_f32 v[16:17], v[16:17], v[134:135] op_sel_hi:[1,0]
	v_pk_mul_f32 v[14:15], v[14:15], v[134:135] op_sel_hi:[1,0]
	v_pk_mul_f32 v[12:13], v[12:13], v[134:135] op_sel_hi:[1,0]
	v_pk_mul_f32 v[10:11], v[10:11], v[134:135] op_sel_hi:[1,0]
	v_pk_mul_f32 v[8:9], v[8:9], v[134:135] op_sel_hi:[1,0]
	v_pk_mul_f32 v[6:7], v[6:7], v[134:135] op_sel_hi:[1,0]
	v_pk_mul_f32 v[4:5], v[4:5], v[134:135] op_sel_hi:[1,0]
	v_pk_mul_f32 v[2:3], v[2:3], v[134:135] op_sel_hi:[1,0]

.LBB0_1773:
	s_nop 10
	v_max_f32_e32 v0, v48, v49
	v_max3_f32 v0, v0, v50, v51
	v_max3_f32 v0, v0, v52, v53
	v_max3_f32 v0, v0, v54, v55
	v_max3_f32 v0, v0, v56, v57
	v_max3_f32 v0, v0, v58, v59
	v_max3_f32 v0, v0, v60, v61
	v_max3_f32 v0, v0, v62, v63
	v_mov_b32_e32 v1, v0
	s_nop 1
	v_permlane32_swap_b32_e32 v0, v1
	v_max_f32_e32 v0, v0, v1
	s_cmp_lg_u64 exec, 0
	v_add_f32_e32 v0, 0, v0
	s_cselect_b64 vcc, -1, 0
	v_cndmask_b32_e32 v151, 0, v0, vcc
	v_sub_f32_e32 v0, v48, v151
	v_exp_f32_e32 v48, v0
	v_sub_f32_e32 v0, v49, v151
	v_exp_f32_e32 v49, v0
	v_sub_f32_e32 v0, v50, v151
	v_exp_f32_e32 v50, v0
	v_sub_f32_e32 v0, v51, v151
	v_exp_f32_e32 v51, v0
	v_sub_f32_e32 v0, v52, v151
	v_exp_f32_e32 v52, v0
	v_sub_f32_e32 v0, v53, v151
	v_exp_f32_e32 v53, v0
	v_sub_f32_e32 v0, v54, v151
	v_exp_f32_e32 v54, v0
	v_sub_f32_e32 v0, v55, v151
	v_add_u32_e32 v191, v182, v178
	v_exp_f32_e32 v55, v0
	v_add_u32_e32 v193, v183, v178
	ds_read_b64_tr_b16 v[4:5], v191 offset:24576
	ds_read_b64_tr_b16 v[6:7], v193 offset:26624
	v_sub_f32_e32 v0, v56, v151
	v_exp_f32_e32 v56, v0
	v_sub_f32_e32 v0, v57, v151
	v_exp_f32_e32 v57, v0
	v_sub_f32_e32 v0, v58, v151
	v_exp_f32_e32 v58, v0
	v_cvt_pk_bf16_f32 v0, v48, v49
	v_cvt_pk_bf16_f32 v1, v50, v51
	v_cvt_pk_bf16_f32 v2, v52, v53
	v_cvt_pk_bf16_f32 v3, v54, v55
	v_add_u32_e32 v146, v182, v179
	v_add_u32_e32 v195, v182, v180
	v_add_u32_e32 v192, v183, v179
	ds_read_b64_tr_b16 v[8:9], v146 offset:24576
	ds_read_b64_tr_b16 v[10:11], v192 offset:26624
	ds_read_b64_tr_b16 v[202:203], v193 offset:30720
	ds_read_b64_tr_b16 v[200:201], v191 offset:28672
	s_waitcnt lgkmcnt(0)
	v_mfma_f32_32x32x16_bf16 v[64:79], v[4:7], v[0:3], 0
	v_add_u32_e32 v197, v183, v180
	ds_read_b64_tr_b16 v[4:5], v195 offset:24576
	ds_read_b64_tr_b16 v[6:7], v197 offset:26624
	ds_read_b64_tr_b16 v[206:207], v192 offset:30720
	ds_read_b64_tr_b16 v[204:205], v146 offset:28672
	v_sub_f32_e32 v12, v59, v151
	v_sub_f32_e32 v62, v62, v151
	v_sub_f32_e32 v63, v63, v151
	v_exp_f32_e32 v59, v12
	v_add_u32_e32 v196, v182, v181
	s_waitcnt lgkmcnt(0)
	v_mfma_f32_32x32x16_bf16 v[16:31], v[4:7], v[0:3], 0
	v_sub_f32_e32 v4, v60, v151
	v_exp_f32_e32 v60, v4
	v_sub_f32_e32 v4, v61, v151
	v_exp_f32_e32 v61, v4
	v_exp_f32_e32 v62, v62
	v_exp_f32_e32 v63, v63
	v_add_u32_e32 v198, v183, v181
	v_mfma_f32_32x32x16_bf16 v[32:47], v[8:11], v[0:3], 0
	ds_read_b64_tr_b16 v[8:9], v196 offset:24576
	ds_read_b64_tr_b16 v[10:11], v198 offset:26624
	ds_read_b64_tr_b16 v[210:211], v197 offset:30720
	ds_read_b64_tr_b16 v[208:209], v195 offset:28672
	v_add_f32_e32 v194, 0, v48
	v_cvt_pk_bf16_f32 v216, v56, v57
	v_cvt_pk_bf16_f32 v217, v58, v59
	v_cvt_pk_bf16_f32 v218, v60, v61
	v_cvt_pk_bf16_f32 v219, v62, v63
	v_add_f32_e32 v194, v49, v194
	s_waitcnt lgkmcnt(0)
	v_mfma_f32_32x32x16_bf16 v[0:15], v[8:11], v[0:3], 0
	v_add_f32_e32 v194, v50, v194
	v_max_f32_e32 v199, v81, v81
	v_add_f32_e32 v194, v51, v194
	ds_read_b64_tr_b16 v[214:215], v198 offset:30720
	ds_read_b64_tr_b16 v[212:213], v196 offset:28672
	v_add_f32_e32 v194, v52, v194
	v_add_f32_e32 v194, v53, v194
	v_add_f32_e32 v194, v54, v194
	v_mfma_f32_32x32x16_bf16 v[64:79], v[200:203], v[216:219], v[64:79]
	v_max_f32_e32 v200, v80, v80
	v_max_f32_e32 v199, v200, v199
	v_max3_f32 v199, v199, v82, v83
	v_max3_f32 v199, v199, v84, v85
	v_max3_f32 v199, v199, v86, v87
	v_add_f32_e32 v194, v55, v194
	v_max3_f32 v199, v199, v88, v89
	v_add_f32_e32 v194, v56, v194
	v_max3_f32 v199, v199, v90, v91
	v_mfma_f32_32x32x16_bf16 v[32:47], v[204:207], v[216:219], v[32:47]
	v_add_f32_e32 v194, v57, v194
	v_max3_f32 v199, v199, v92, v93
	v_add_f32_e32 v194, v58, v194
	v_max3_f32 v199, v199, v94, v95
	v_add_f32_e32 v194, v59, v194
	v_mov_b32_e32 v200, v199
	v_add_f32_e32 v194, v60, v194
	v_mfma_f32_32x32x16_bf16 v[16:31], v[208:211], v[216:219], v[16:31]
	v_permlane32_swap_b32_e32 v199, v200
	v_add_f32_e32 v194, v61, v194
	v_max_f32_e32 v200, v200, v200
	v_max_f32_e32 v199, v199, v199
	v_add_f32_e32 v194, v62, v194
	v_max_f32_e32 v199, v199, v200
	s_waitcnt lgkmcnt(0)
	v_mfma_f32_32x32x16_bf16 v[0:15], v[212:215], v[216:219], v[0:15]
	v_add_f32_e32 v194, v63, v194
	v_sub_f32_e32 v199, v199, v151
	v_add_f32_e32 v194, 0, v194
	v_cmp_lt_f32_e32 vcc, s20, v199
	s_cbranch_vccz .LBB0_1775
	v_max_f32_e32 v199, v199, v199
	v_max_f32_e32 v199, 0, v199
	v_exp_f32_e64 v200, -v199
	v_add_f32_e32 v151, v151, v199
	v_pk_mul_f32 v[78:79], v[78:79], v[200:201] op_sel_hi:[1,0]
	v_pk_mul_f32 v[76:77], v[76:77], v[200:201] op_sel_hi:[1,0]
	v_pk_mul_f32 v[74:75], v[74:75], v[200:201] op_sel_hi:[1,0]
	v_pk_mul_f32 v[72:73], v[72:73], v[200:201] op_sel_hi:[1,0]
	v_pk_mul_f32 v[70:71], v[70:71], v[200:201] op_sel_hi:[1,0]
	v_pk_mul_f32 v[68:69], v[68:69], v[200:201] op_sel_hi:[1,0]
	v_pk_mul_f32 v[66:67], v[66:67], v[200:201] op_sel_hi:[1,0]
	v_pk_mul_f32 v[64:65], v[64:65], v[200:201] op_sel_hi:[1,0]
	v_pk_mul_f32 v[46:47], v[46:47], v[200:201] op_sel_hi:[1,0]
	v_pk_mul_f32 v[44:45], v[44:45], v[200:201] op_sel_hi:[1,0]
	v_pk_mul_f32 v[42:43], v[42:43], v[200:201] op_sel_hi:[1,0]
	v_pk_mul_f32 v[40:41], v[40:41], v[200:201] op_sel_hi:[1,0]
	v_pk_mul_f32 v[38:39], v[38:39], v[200:201] op_sel_hi:[1,0]
	v_pk_mul_f32 v[36:37], v[36:37], v[200:201] op_sel_hi:[1,0]
	v_pk_mul_f32 v[34:35], v[34:35], v[200:201] op_sel_hi:[1,0]
	v_pk_mul_f32 v[32:33], v[32:33], v[200:201] op_sel_hi:[1,0]
	v_pk_mul_f32 v[30:31], v[30:31], v[200:201] op_sel_hi:[1,0]
	v_pk_mul_f32 v[28:29], v[28:29], v[200:201] op_sel_hi:[1,0]
	v_pk_mul_f32 v[26:27], v[26:27], v[200:201] op_sel_hi:[1,0]
	v_pk_mul_f32 v[24:25], v[24:25], v[200:201] op_sel_hi:[1,0]
	v_pk_mul_f32 v[22:23], v[22:23], v[200:201] op_sel_hi:[1,0]
	v_pk_mul_f32 v[20:21], v[20:21], v[200:201] op_sel_hi:[1,0]
	v_pk_mul_f32 v[18:19], v[18:19], v[200:201] op_sel_hi:[1,0]
	v_pk_mul_f32 v[16:17], v[16:17], v[200:201] op_sel_hi:[1,0]
	v_pk_mul_f32 v[14:15], v[14:15], v[200:201] op_sel_hi:[1,0]
	v_pk_mul_f32 v[12:13], v[12:13], v[200:201] op_sel_hi:[1,0]
	v_pk_mul_f32 v[10:11], v[10:11], v[200:201] op_sel_hi:[1,0]
	v_pk_mul_f32 v[8:9], v[8:9], v[200:201] op_sel_hi:[1,0]
	v_pk_mul_f32 v[6:7], v[6:7], v[200:201] op_sel_hi:[1,0]
	v_pk_mul_f32 v[4:5], v[4:5], v[200:201] op_sel_hi:[1,0]
	v_pk_mul_f32 v[2:3], v[2:3], v[200:201] op_sel_hi:[1,0]
	v_pk_mul_f32 v[0:1], v[0:1], v[200:201] op_sel_hi:[1,0]
	v_mul_f32_e32 v194, v194, v200

.LBB0_1788:
	s_setprio 1
	s_nop 7
	v_max_f32_e32 v159, v48, v49
	v_max3_f32 v159, v159, v50, v51
	v_max3_f32 v159, v159, v52, v53
	v_max3_f32 v159, v159, v54, v55
	v_max3_f32 v159, v159, v56, v57
	v_max3_f32 v159, v159, v58, v59
	v_max3_f32 v159, v159, v60, v61
	v_max3_f32 v159, v159, v62, v63
	v_mov_b32_e32 v161, v159
	s_nop 1
	v_permlane32_swap_b32_e32 v159, v161
	v_max_f32_e32 v159, v159, v161
	v_sub_f32_e32 v159, v159, v151
	v_cmp_lt_f32_e32 vcc, s20, v159
	s_cbranch_vccz .LBB0_1790
	v_max_f32_e32 v159, v159, v159
	v_max_f32_e32 v159, 0, v159
	v_exp_f32_e64 v190, -v159
	v_add_f32_e32 v151, v151, v159
	v_pk_mul_f32 v[78:79], v[78:79], v[190:191] op_sel_hi:[1,0]
	v_pk_mul_f32 v[76:77], v[76:77], v[190:191] op_sel_hi:[1,0]
	v_pk_mul_f32 v[74:75], v[74:75], v[190:191] op_sel_hi:[1,0]
	v_pk_mul_f32 v[72:73], v[72:73], v[190:191] op_sel_hi:[1,0]
	v_pk_mul_f32 v[70:71], v[70:71], v[190:191] op_sel_hi:[1,0]
	v_pk_mul_f32 v[68:69], v[68:69], v[190:191] op_sel_hi:[1,0]
	v_pk_mul_f32 v[66:67], v[66:67], v[190:191] op_sel_hi:[1,0]
	v_pk_mul_f32 v[64:65], v[64:65], v[190:191] op_sel_hi:[1,0]
	v_pk_mul_f32 v[46:47], v[46:47], v[190:191] op_sel_hi:[1,0]
	v_pk_mul_f32 v[44:45], v[44:45], v[190:191] op_sel_hi:[1,0]
	v_pk_mul_f32 v[42:43], v[42:43], v[190:191] op_sel_hi:[1,0]
	v_pk_mul_f32 v[40:41], v[40:41], v[190:191] op_sel_hi:[1,0]
	v_pk_mul_f32 v[38:39], v[38:39], v[190:191] op_sel_hi:[1,0]
	v_pk_mul_f32 v[36:37], v[36:37], v[190:191] op_sel_hi:[1,0]
	v_pk_mul_f32 v[34:35], v[34:35], v[190:191] op_sel_hi:[1,0]
	v_pk_mul_f32 v[32:33], v[32:33], v[190:191] op_sel_hi:[1,0]
	v_pk_mul_f32 v[30:31], v[30:31], v[190:191] op_sel_hi:[1,0]
	v_pk_mul_f32 v[28:29], v[28:29], v[190:191] op_sel_hi:[1,0]
	v_pk_mul_f32 v[26:27], v[26:27], v[190:191] op_sel_hi:[1,0]
	v_pk_mul_f32 v[24:25], v[24:25], v[190:191] op_sel_hi:[1,0]
	v_pk_mul_f32 v[22:23], v[22:23], v[190:191] op_sel_hi:[1,0]
	v_pk_mul_f32 v[20:21], v[20:21], v[190:191] op_sel_hi:[1,0]
	v_pk_mul_f32 v[18:19], v[18:19], v[190:191] op_sel_hi:[1,0]
	v_pk_mul_f32 v[16:17], v[16:17], v[190:191] op_sel_hi:[1,0]
	v_pk_mul_f32 v[14:15], v[14:15], v[190:191] op_sel_hi:[1,0]
	v_pk_mul_f32 v[12:13], v[12:13], v[190:191] op_sel_hi:[1,0]
	v_pk_mul_f32 v[10:11], v[10:11], v[190:191] op_sel_hi:[1,0]
	v_pk_mul_f32 v[8:9], v[8:9], v[190:191] op_sel_hi:[1,0]
	v_pk_mul_f32 v[6:7], v[6:7], v[190:191] op_sel_hi:[1,0]
	v_pk_mul_f32 v[4:5], v[4:5], v[190:191] op_sel_hi:[1,0]
	v_pk_mul_f32 v[2:3], v[2:3], v[190:191] op_sel_hi:[1,0]
	v_pk_mul_f32 v[0:1], v[0:1], v[190:191] op_sel_hi:[1,0]
	v_mul_f32_e32 v163, v163, v190
.LBB0_1790:
	v_add_u32_e32 v171, s28, v175
	v_add_u32_e32 v190, s28, v177
	v_sub_f32_e32 v48, v48, v151
	v_sub_f32_e32 v49, v49, v151
	v_sub_f32_e32 v50, v50, v151
	v_sub_f32_e32 v51, v51, v151
	v_sub_f32_e32 v52, v52, v151
	v_sub_f32_e32 v53, v53, v151
	v_sub_f32_e32 v54, v54, v151
	v_sub_f32_e32 v55, v55, v151
	v_add_u32_e32 v161, v171, v178
	v_exp_f32_e32 v48, v48
	v_exp_f32_e32 v49, v49
	v_exp_f32_e32 v50, v50
	v_exp_f32_e32 v51, v51
	v_exp_f32_e32 v52, v52
	v_exp_f32_e32 v53, v53
	v_exp_f32_e32 v54, v54
	v_exp_f32_e32 v55, v55
	v_add_u32_e32 v167, v190, v178
	ds_read_b64_tr_b16 v[196:197], v161 offset:24576
	ds_read_b64_tr_b16 v[198:199], v167 offset:26624
	v_add_u32_e32 v159, v171, v179
	v_add_u32_e32 v165, v190, v179
	ds_read_b64_tr_b16 v[200:201], v159 offset:24576
	ds_read_b64_tr_b16 v[202:203], v165 offset:26624
	ds_read_b64_tr_b16 v[206:207], v167 offset:30720
	ds_read_b64_tr_b16 v[204:205], v161 offset:28672
	v_cvt_pk_bf16_f32 v192, v48, v49
	v_cvt_pk_bf16_f32 v193, v50, v51
	v_cvt_pk_bf16_f32 v194, v52, v53
	v_cvt_pk_bf16_f32 v195, v54, v55
	v_add_u32_e32 v169, v171, v180
	v_add_u32_e32 v171, v171, v181
	s_waitcnt lgkmcnt(0)
	v_mfma_f32_32x32x16_bf16 v[64:79], v[196:199], v[192:195], v[64:79]
	v_add_u32_e32 v189, v190, v180
	ds_read_b64_tr_b16 v[196:197], v169 offset:24576
	ds_read_b64_tr_b16 v[198:199], v189 offset:26624
	ds_read_b64_tr_b16 v[210:211], v165 offset:30720
	ds_read_b64_tr_b16 v[208:209], v159 offset:28672
	v_add_u32_e32 v190, v190, v181
	v_add_f32_e32 v191, 0, v48
	v_sub_f32_e32 v56, v56, v151
	v_sub_f32_e32 v57, v57, v151
	v_sub_f32_e32 v58, v58, v151
	v_mfma_f32_32x32x16_bf16 v[32:47], v[200:203], v[192:195], v[32:47]
	ds_read_b64_tr_b16 v[200:201], v171 offset:24576
	ds_read_b64_tr_b16 v[202:203], v190 offset:26624
	ds_read_b64_tr_b16 v[214:215], v189 offset:30720
	ds_read_b64_tr_b16 v[212:213], v169 offset:28672
	v_sub_f32_e32 v59, v59, v151
	v_sub_f32_e32 v60, v60, v151
	v_sub_f32_e32 v61, v61, v151
	v_sub_f32_e32 v62, v62, v151
	v_sub_f32_e32 v63, v63, v151
	v_add_f32_e32 v191, v49, v191
	s_waitcnt lgkmcnt(0)
	v_mfma_f32_32x32x16_bf16 v[16:31], v[196:199], v[192:195], v[16:31]
	v_exp_f32_e32 v56, v56
	v_exp_f32_e32 v57, v57
	v_exp_f32_e32 v58, v58
	v_exp_f32_e32 v59, v59
	v_exp_f32_e32 v60, v60
	v_exp_f32_e32 v61, v61
	ds_read_b64_tr_b16 v[198:199], v190 offset:30720
	ds_read_b64_tr_b16 v[196:197], v171 offset:28672
	v_mfma_f32_32x32x16_bf16 v[0:15], v[200:203], v[192:195], v[0:15]
	v_exp_f32_e32 v62, v62
	v_exp_f32_e32 v63, v63
	v_add_f32_e32 v191, v50, v191
	v_add_f32_e32 v191, v51, v191
	v_add_f32_e32 v191, v52, v191
	v_add_f32_e32 v191, v53, v191
	v_cvt_pk_bf16_f32 v192, v56, v57
	v_cvt_pk_bf16_f32 v193, v58, v59
	v_cvt_pk_bf16_f32 v194, v60, v61
	v_cvt_pk_bf16_f32 v195, v62, v63
	v_add_f32_e32 v191, v54, v191
	v_add_f32_e32 v191, v55, v191
	v_mfma_f32_32x32x16_bf16 v[64:79], v[204:207], v[192:195], v[64:79]
	v_add_f32_e32 v191, v56, v191
	v_add_f32_e32 v191, v57, v191
	v_add_f32_e32 v191, v58, v191
	v_add_f32_e32 v191, v59, v191
	v_add_f32_e32 v191, v60, v191
	v_add_f32_e32 v191, v61, v191
	v_add_f32_e32 v191, v62, v191
	v_mfma_f32_32x32x16_bf16 v[32:47], v[208:211], v[192:195], v[32:47]
	v_add_f32_e32 v191, v63, v191
	v_add_f32_e32 v163, v163, v191
	v_mfma_f32_32x32x16_bf16 v[16:31], v[212:215], v[192:195], v[16:31]
	s_waitcnt lgkmcnt(0)
	v_mfma_f32_32x32x16_bf16 v[0:15], v[196:199], v[192:195], v[0:15]
	v_max_f32_e32 v192, v81, v81
	v_max_f32_e32 v193, v80, v80
	v_max_f32_e32 v192, v193, v192
	v_max3_f32 v192, v192, v82, v83
	v_max3_f32 v192, v192, v84, v85
	v_max3_f32 v192, v192, v86, v87
	v_max3_f32 v192, v192, v88, v89
	v_max3_f32 v192, v192, v90, v91
	v_max3_f32 v192, v192, v92, v93
	v_max3_f32 v192, v192, v94, v95
	v_mov_b32_e32 v191, v192
	s_nop 1
	v_permlane32_swap_b32_e32 v192, v191
	v_max_f32_e32 v191, v192, v191
	v_sub_f32_e32 v191, v191, v151
	v_cmp_lt_f32_e32 vcc, s20, v191
	s_cbranch_vccz .LBB0_1792
	v_max_f32_e32 v191, v191, v191
	v_max_f32_e32 v191, 0, v191
	v_exp_f32_e64 v192, -v191
	v_add_f32_e32 v151, v151, v191
	v_pk_mul_f32 v[78:79], v[78:79], v[192:193] op_sel_hi:[1,0]
	v_pk_mul_f32 v[76:77], v[76:77], v[192:193] op_sel_hi:[1,0]
	v_pk_mul_f32 v[74:75], v[74:75], v[192:193] op_sel_hi:[1,0]
	v_pk_mul_f32 v[72:73], v[72:73], v[192:193] op_sel_hi:[1,0]
	v_pk_mul_f32 v[70:71], v[70:71], v[192:193] op_sel_hi:[1,0]
	v_pk_mul_f32 v[68:69], v[68:69], v[192:193] op_sel_hi:[1,0]
	v_pk_mul_f32 v[66:67], v[66:67], v[192:193] op_sel_hi:[1,0]
	v_pk_mul_f32 v[64:65], v[64:65], v[192:193] op_sel_hi:[1,0]
	v_pk_mul_f32 v[46:47], v[46:47], v[192:193] op_sel_hi:[1,0]
	v_pk_mul_f32 v[44:45], v[44:45], v[192:193] op_sel_hi:[1,0]
	v_pk_mul_f32 v[42:43], v[42:43], v[192:193] op_sel_hi:[1,0]
	v_pk_mul_f32 v[40:41], v[40:41], v[192:193] op_sel_hi:[1,0]
	v_pk_mul_f32 v[38:39], v[38:39], v[192:193] op_sel_hi:[1,0]
	v_pk_mul_f32 v[36:37], v[36:37], v[192:193] op_sel_hi:[1,0]
	v_pk_mul_f32 v[34:35], v[34:35], v[192:193] op_sel_hi:[1,0]
	v_pk_mul_f32 v[32:33], v[32:33], v[192:193] op_sel_hi:[1,0]
	v_pk_mul_f32 v[30:31], v[30:31], v[192:193] op_sel_hi:[1,0]
	v_pk_mul_f32 v[28:29], v[28:29], v[192:193] op_sel_hi:[1,0]
	v_pk_mul_f32 v[26:27], v[26:27], v[192:193] op_sel_hi:[1,0]
	v_pk_mul_f32 v[24:25], v[24:25], v[192:193] op_sel_hi:[1,0]
	v_pk_mul_f32 v[22:23], v[22:23], v[192:193] op_sel_hi:[1,0]
	v_pk_mul_f32 v[20:21], v[20:21], v[192:193] op_sel_hi:[1,0]
	v_pk_mul_f32 v[18:19], v[18:19], v[192:193] op_sel_hi:[1,0]
	v_pk_mul_f32 v[16:17], v[16:17], v[192:193] op_sel_hi:[1,0]
	v_pk_mul_f32 v[14:15], v[14:15], v[192:193] op_sel_hi:[1,0]
	v_pk_mul_f32 v[12:13], v[12:13], v[192:193] op_sel_hi:[1,0]
	v_pk_mul_f32 v[10:11], v[10:11], v[192:193] op_sel_hi:[1,0]
	v_pk_mul_f32 v[8:9], v[8:9], v[192:193] op_sel_hi:[1,0]
	v_pk_mul_f32 v[6:7], v[6:7], v[192:193] op_sel_hi:[1,0]
	v_pk_mul_f32 v[4:5], v[4:5], v[192:193] op_sel_hi:[1,0]
	v_pk_mul_f32 v[2:3], v[2:3], v[192:193] op_sel_hi:[1,0]
	v_pk_mul_f32 v[0:1], v[0:1], v[192:193] op_sel_hi:[1,0]
	v_mul_f32_e32 v163, v163, v192

.LBB0_1809:
	v_bfe_u32 v2, v222, 2, 2
	v_lshrrev_b32_e32 v5, 3, v222
	v_lshlrev_b32_e32 v6, 3, v222
	v_lshlrev_b32_e32 v3, 10, v161
	v_lshlrev_b32_e32 v4, 8, v2
	v_and_b32_e32 v5, 2, v5
	v_and_b32_e32 v0, 1, v0
	v_and_b32_e32 v6, 8, v6
	v_or3_b32 v3, v4, v6, v3
	v_bitop3_b32 v4, v5, v161, v0 bitop3:0x36
	v_bitop3_b32 v0, v1, v5, v0 bitop3:0x1e
	v_lshl_or_b32 v175, v0, 4, v3
	v_max_f32_e32 v0, v48, v49
	v_max3_f32 v0, v0, v50, v51
	v_max3_f32 v0, v0, v52, v53
	v_max3_f32 v0, v0, v54, v55
	v_max3_f32 v0, v0, v56, v57
	v_max3_f32 v0, v0, v58, v59
	v_max3_f32 v0, v0, v60, v61
	v_max3_f32 v0, v0, v62, v63
	v_mov_b32_e32 v1, v0
	s_nop 1
	v_permlane32_swap_b32_e32 v0, v1
	v_max_f32_e32 v0, v0, v1
	s_cmp_lg_u64 exec, 0
	v_add_f32_e32 v0, 0, v0
	s_cselect_b64 vcc, -1, 0
	v_cndmask_b32_e32 v157, 0, v0, vcc
	v_sub_f32_e32 v0, v48, v157
	v_exp_f32_e32 v48, v0
	v_sub_f32_e32 v0, v49, v157
	v_exp_f32_e32 v49, v0
	v_sub_f32_e32 v0, v50, v157
	v_exp_f32_e32 v50, v0
	v_sub_f32_e32 v0, v51, v157
	v_exp_f32_e32 v51, v0
	v_sub_f32_e32 v0, v52, v157
	v_lshl_or_b32 v174, v4, 4, v3
	v_exp_f32_e32 v52, v0
	v_sub_f32_e32 v0, v53, v157
	v_lshlrev_b32_e32 v177, 6, v2
	v_add_u32_e32 v12, 0, v174
	v_exp_f32_e32 v53, v0
	v_sub_f32_e32 v0, v54, v157
	v_add_u32_e32 v13, 0, v175
	v_exp_f32_e32 v54, v0
	v_sub_f32_e32 v0, v55, v157
	v_add_u32_e32 v183, v12, v177
	v_exp_f32_e32 v55, v0
	v_add_u32_e32 v185, v13, v177
	ds_read_b64_tr_b16 v[4:5], v183 offset:24576
	ds_read_b64_tr_b16 v[6:7], v185 offset:26624
	v_sub_f32_e32 v0, v56, v157
	v_exp_f32_e32 v56, v0
	v_sub_f32_e32 v0, v57, v157
	v_xor_b32_e32 v178, 64, v177
	v_xor_b32_e32 v179, 0x80, v177
	v_exp_f32_e32 v57, v0
	v_sub_f32_e32 v0, v58, v157
	v_exp_f32_e32 v58, v0
	v_cvt_pk_bf16_f32 v0, v48, v49
	v_cvt_pk_bf16_f32 v1, v50, v51
	v_cvt_pk_bf16_f32 v2, v52, v53
	v_cvt_pk_bf16_f32 v3, v54, v55
	v_add_u32_e32 v182, v12, v178
	v_add_u32_e32 v186, v12, v179
	v_add_u32_e32 v184, v13, v178
	ds_read_b64_tr_b16 v[8:9], v182 offset:24576
	ds_read_b64_tr_b16 v[10:11], v184 offset:26624
	ds_read_b64_tr_b16 v[164:165], v185 offset:30720
	ds_read_b64_tr_b16 v[162:163], v183 offset:28672
	s_waitcnt lgkmcnt(0)
	v_mfma_f32_32x32x16_bf16 v[64:79], v[4:7], v[0:3], 0
	v_add_u32_e32 v188, v13, v179
	ds_read_b64_tr_b16 v[4:5], v186 offset:24576
	ds_read_b64_tr_b16 v[6:7], v188 offset:26624
	ds_read_b64_tr_b16 v[168:169], v184 offset:30720
	ds_read_b64_tr_b16 v[166:167], v182 offset:28672
	v_sub_f32_e32 v14, v59, v157
	v_sub_f32_e32 v62, v62, v157
	v_sub_f32_e32 v63, v63, v157
	v_exp_f32_e32 v59, v14
	v_exp_f32_e32 v62, v62
	s_waitcnt lgkmcnt(0)
	v_mfma_f32_32x32x16_bf16 v[16:31], v[4:7], v[0:3], 0
	v_sub_f32_e32 v4, v60, v157
	v_exp_f32_e32 v60, v4
	v_sub_f32_e32 v4, v61, v157
	v_exp_f32_e32 v61, v4
	v_exp_f32_e32 v63, v63
	v_xor_b32_e32 v180, 0xc0, v177
	v_add_u32_e32 v187, v12, v180
	v_mfma_f32_32x32x16_bf16 v[32:47], v[8:11], v[0:3], 0
	v_add_u32_e32 v189, v13, v180
	ds_read_b64_tr_b16 v[8:9], v187 offset:24576
	ds_read_b64_tr_b16 v[10:11], v189 offset:26624
	ds_read_b64_tr_b16 v[200:201], v188 offset:30720
	ds_read_b64_tr_b16 v[198:199], v186 offset:28672
	v_cvt_pk_bf16_f32 v206, v56, v57
	v_cvt_pk_bf16_f32 v207, v58, v59
	v_cvt_pk_bf16_f32 v208, v60, v61
	v_cvt_pk_bf16_f32 v209, v62, v63
	ds_read_b64_tr_b16 v[204:205], v189 offset:30720
	ds_read_b64_tr_b16 v[202:203], v187 offset:28672
	v_mfma_f32_32x32x16_bf16 v[64:79], v[162:165], v[206:209], v[64:79]
	v_add_f32_e32 v162, 0, v48
	v_add_f32_e32 v162, v49, v162
	v_add_f32_e32 v162, v50, v162
	v_max_f32_e32 v163, v81, v81
	v_max_f32_e32 v164, v80, v80
	v_add_f32_e32 v162, v51, v162
	v_max_f32_e32 v163, v164, v163
	s_waitcnt lgkmcnt(0)
	v_mfma_f32_32x32x16_bf16 v[0:15], v[8:11], v[0:3], 0
	v_add_f32_e32 v162, v52, v162
	v_max3_f32 v163, v163, v82, v83
	v_add_f32_e32 v162, v53, v162
	v_max3_f32 v163, v163, v84, v85
	v_add_f32_e32 v162, v54, v162
	v_max3_f32 v163, v163, v86, v87
	v_add_f32_e32 v162, v55, v162
	v_max3_f32 v163, v163, v88, v89
	v_add_f32_e32 v162, v56, v162
	v_max3_f32 v163, v163, v90, v91
	v_mfma_f32_32x32x16_bf16 v[32:47], v[166:169], v[206:209], v[32:47]
	v_add_f32_e32 v162, v57, v162
	v_max3_f32 v163, v163, v92, v93
	v_add_f32_e32 v162, v58, v162
	v_max3_f32 v163, v163, v94, v95
	v_add_f32_e32 v162, v59, v162
	v_mov_b32_e32 v164, v163
	v_add_f32_e32 v162, v60, v162
	v_mfma_f32_32x32x16_bf16 v[16:31], v[198:201], v[206:209], v[16:31]
	v_permlane32_swap_b32_e32 v163, v164
	v_add_f32_e32 v162, v61, v162
	v_max_f32_e32 v164, v164, v164
	v_max_f32_e32 v163, v163, v163
	v_add_f32_e32 v162, v62, v162
	v_max_f32_e32 v163, v163, v164
	v_mfma_f32_32x32x16_bf16 v[0:15], v[202:205], v[206:209], v[0:15]
	v_add_f32_e32 v162, v63, v162
	v_sub_f32_e32 v163, v163, v157
	s_mov_b32 s2, 0x41000000
	v_add_f32_e32 v162, 0, v162
	v_cmp_lt_f32_e32 vcc, s2, v163
	s_cbranch_vccz .LBB0_1811
	v_max_f32_e32 v163, v163, v163
	v_max_f32_e32 v163, 0, v163
	v_exp_f32_e64 v164, -v163
	v_add_f32_e32 v157, v157, v163
	v_pk_mul_f32 v[78:79], v[78:79], v[164:165] op_sel_hi:[1,0]
	v_pk_mul_f32 v[76:77], v[76:77], v[164:165] op_sel_hi:[1,0]
	v_pk_mul_f32 v[74:75], v[74:75], v[164:165] op_sel_hi:[1,0]
	v_pk_mul_f32 v[72:73], v[72:73], v[164:165] op_sel_hi:[1,0]
	v_pk_mul_f32 v[70:71], v[70:71], v[164:165] op_sel_hi:[1,0]
	v_pk_mul_f32 v[68:69], v[68:69], v[164:165] op_sel_hi:[1,0]
	v_pk_mul_f32 v[66:67], v[66:67], v[164:165] op_sel_hi:[1,0]
	v_pk_mul_f32 v[64:65], v[64:65], v[164:165] op_sel_hi:[1,0]
	v_pk_mul_f32 v[46:47], v[46:47], v[164:165] op_sel_hi:[1,0]
	v_pk_mul_f32 v[44:45], v[44:45], v[164:165] op_sel_hi:[1,0]
	v_pk_mul_f32 v[42:43], v[42:43], v[164:165] op_sel_hi:[1,0]
	v_pk_mul_f32 v[40:41], v[40:41], v[164:165] op_sel_hi:[1,0]
	v_pk_mul_f32 v[38:39], v[38:39], v[164:165] op_sel_hi:[1,0]
	v_pk_mul_f32 v[36:37], v[36:37], v[164:165] op_sel_hi:[1,0]
	v_pk_mul_f32 v[34:35], v[34:35], v[164:165] op_sel_hi:[1,0]
	v_pk_mul_f32 v[32:33], v[32:33], v[164:165] op_sel_hi:[1,0]
	v_pk_mul_f32 v[30:31], v[30:31], v[164:165] op_sel_hi:[1,0]
	v_pk_mul_f32 v[28:29], v[28:29], v[164:165] op_sel_hi:[1,0]
	v_pk_mul_f32 v[26:27], v[26:27], v[164:165] op_sel_hi:[1,0]
	v_pk_mul_f32 v[24:25], v[24:25], v[164:165] op_sel_hi:[1,0]
	v_pk_mul_f32 v[22:23], v[22:23], v[164:165] op_sel_hi:[1,0]
	v_pk_mul_f32 v[20:21], v[20:21], v[164:165] op_sel_hi:[1,0]
	v_pk_mul_f32 v[18:19], v[18:19], v[164:165] op_sel_hi:[1,0]
	v_pk_mul_f32 v[16:17], v[16:17], v[164:165] op_sel_hi:[1,0]
	v_pk_mul_f32 v[14:15], v[14:15], v[164:165] op_sel_hi:[1,0]
	v_pk_mul_f32 v[12:13], v[12:13], v[164:165] op_sel_hi:[1,0]
	v_pk_mul_f32 v[10:11], v[10:11], v[164:165] op_sel_hi:[1,0]
	v_pk_mul_f32 v[8:9], v[8:9], v[164:165] op_sel_hi:[1,0]
	v_pk_mul_f32 v[6:7], v[6:7], v[164:165] op_sel_hi:[1,0]
	v_pk_mul_f32 v[4:5], v[4:5], v[164:165] op_sel_hi:[1,0]
	v_pk_mul_f32 v[2:3], v[2:3], v[164:165] op_sel_hi:[1,0]
	v_pk_mul_f32 v[0:1], v[0:1], v[164:165] op_sel_hi:[1,0]
	v_mul_f32_e32 v162, v162, v164

.LBB0_1824:
	s_setprio 1
	s_nop 7
	v_max_f32_e32 v147, v48, v49
	v_max3_f32 v147, v147, v50, v51
	v_max3_f32 v147, v147, v52, v53
	v_max3_f32 v147, v147, v54, v55
	v_max3_f32 v147, v147, v56, v57
	v_max3_f32 v147, v147, v58, v59
	v_max3_f32 v147, v147, v60, v61
	v_max3_f32 v147, v147, v62, v63
	v_mov_b32_e32 v149, v147
	s_nop 1
	v_permlane32_swap_b32_e32 v147, v149
	v_max_f32_e32 v147, v147, v149
	v_sub_f32_e32 v147, v147, v157
	v_cmp_lt_f32_e32 vcc, s24, v147
	s_cbranch_vccz .LBB0_1826
	v_max_f32_e32 v147, v147, v147
	v_max_f32_e32 v147, 0, v147
	v_exp_f32_e64 v158, -v147
	v_add_f32_e32 v157, v157, v147
	v_pk_mul_f32 v[78:79], v[78:79], v[158:159] op_sel_hi:[1,0]
	v_pk_mul_f32 v[76:77], v[76:77], v[158:159] op_sel_hi:[1,0]
	v_pk_mul_f32 v[74:75], v[74:75], v[158:159] op_sel_hi:[1,0]
	v_pk_mul_f32 v[72:73], v[72:73], v[158:159] op_sel_hi:[1,0]
	v_pk_mul_f32 v[70:71], v[70:71], v[158:159] op_sel_hi:[1,0]
	v_pk_mul_f32 v[68:69], v[68:69], v[158:159] op_sel_hi:[1,0]
	v_pk_mul_f32 v[66:67], v[66:67], v[158:159] op_sel_hi:[1,0]
	v_pk_mul_f32 v[64:65], v[64:65], v[158:159] op_sel_hi:[1,0]
	v_pk_mul_f32 v[46:47], v[46:47], v[158:159] op_sel_hi:[1,0]
	v_pk_mul_f32 v[44:45], v[44:45], v[158:159] op_sel_hi:[1,0]
	v_pk_mul_f32 v[42:43], v[42:43], v[158:159] op_sel_hi:[1,0]
	v_pk_mul_f32 v[40:41], v[40:41], v[158:159] op_sel_hi:[1,0]
	v_pk_mul_f32 v[38:39], v[38:39], v[158:159] op_sel_hi:[1,0]
	v_pk_mul_f32 v[36:37], v[36:37], v[158:159] op_sel_hi:[1,0]
	v_pk_mul_f32 v[34:35], v[34:35], v[158:159] op_sel_hi:[1,0]
	v_pk_mul_f32 v[32:33], v[32:33], v[158:159] op_sel_hi:[1,0]
	v_pk_mul_f32 v[30:31], v[30:31], v[158:159] op_sel_hi:[1,0]
	v_pk_mul_f32 v[28:29], v[28:29], v[158:159] op_sel_hi:[1,0]
	v_pk_mul_f32 v[26:27], v[26:27], v[158:159] op_sel_hi:[1,0]
	v_pk_mul_f32 v[24:25], v[24:25], v[158:159] op_sel_hi:[1,0]
	v_pk_mul_f32 v[22:23], v[22:23], v[158:159] op_sel_hi:[1,0]
	v_pk_mul_f32 v[20:21], v[20:21], v[158:159] op_sel_hi:[1,0]
	v_pk_mul_f32 v[18:19], v[18:19], v[158:159] op_sel_hi:[1,0]
	v_pk_mul_f32 v[16:17], v[16:17], v[158:159] op_sel_hi:[1,0]
	v_pk_mul_f32 v[14:15], v[14:15], v[158:159] op_sel_hi:[1,0]
	v_pk_mul_f32 v[12:13], v[12:13], v[158:159] op_sel_hi:[1,0]
	v_pk_mul_f32 v[10:11], v[10:11], v[158:159] op_sel_hi:[1,0]
	v_pk_mul_f32 v[8:9], v[8:9], v[158:159] op_sel_hi:[1,0]
	v_pk_mul_f32 v[6:7], v[6:7], v[158:159] op_sel_hi:[1,0]
	v_pk_mul_f32 v[4:5], v[4:5], v[158:159] op_sel_hi:[1,0]
	v_pk_mul_f32 v[2:3], v[2:3], v[158:159] op_sel_hi:[1,0]
	v_pk_mul_f32 v[0:1], v[0:1], v[158:159] op_sel_hi:[1,0]
	v_mul_f32_e32 v161, v161, v158
.LBB0_1826:
	v_add_u32_e32 v159, s26, v174
	v_add_u32_e32 v162, s26, v175
	v_sub_f32_e32 v48, v48, v157
	v_sub_f32_e32 v49, v49, v157
	v_sub_f32_e32 v50, v50, v157
	v_sub_f32_e32 v51, v51, v157
	v_sub_f32_e32 v52, v52, v157
	v_sub_f32_e32 v53, v53, v157
	v_sub_f32_e32 v54, v54, v157
	v_sub_f32_e32 v55, v55, v157
	v_add_u32_e32 v149, v159, v177
	v_exp_f32_e32 v48, v48
	v_exp_f32_e32 v49, v49
	v_exp_f32_e32 v50, v50
	v_exp_f32_e32 v51, v51
	v_exp_f32_e32 v52, v52
	v_exp_f32_e32 v53, v53
	v_exp_f32_e32 v54, v54
	v_exp_f32_e32 v55, v55
	v_add_u32_e32 v153, v162, v177
	ds_read_b64_tr_b16 v[198:199], v149 offset:24576
	ds_read_b64_tr_b16 v[200:201], v153 offset:26624
	v_add_u32_e32 v147, v159, v178
	v_add_u32_e32 v151, v162, v178
	ds_read_b64_tr_b16 v[202:203], v147 offset:24576
	ds_read_b64_tr_b16 v[204:205], v151 offset:26624
	ds_read_b64_tr_b16 v[208:209], v153 offset:30720
	ds_read_b64_tr_b16 v[206:207], v149 offset:28672
	v_cvt_pk_bf16_f32 v164, v48, v49
	v_cvt_pk_bf16_f32 v165, v50, v51
	v_cvt_pk_bf16_f32 v166, v52, v53
	v_cvt_pk_bf16_f32 v167, v54, v55
	v_add_u32_e32 v158, v159, v179
	v_add_u32_e32 v159, v159, v180
	s_waitcnt lgkmcnt(0)
	v_mfma_f32_32x32x16_bf16 v[64:79], v[198:201], v[164:167], v[64:79]
	v_add_u32_e32 v160, v162, v179
	ds_read_b64_tr_b16 v[198:199], v158 offset:24576
	ds_read_b64_tr_b16 v[200:201], v160 offset:26624
	ds_read_b64_tr_b16 v[212:213], v151 offset:30720
	ds_read_b64_tr_b16 v[210:211], v147 offset:28672
	v_add_u32_e32 v162, v162, v180
	v_add_f32_e32 v163, 0, v48
	v_sub_f32_e32 v56, v56, v157
	v_sub_f32_e32 v57, v57, v157
	v_sub_f32_e32 v58, v58, v157
	v_mfma_f32_32x32x16_bf16 v[32:47], v[202:205], v[164:167], v[32:47]
	ds_read_b64_tr_b16 v[202:203], v159 offset:24576
	ds_read_b64_tr_b16 v[204:205], v162 offset:26624
	ds_read_b64_tr_b16 v[216:217], v160 offset:30720
	ds_read_b64_tr_b16 v[214:215], v158 offset:28672
	v_sub_f32_e32 v59, v59, v157
	v_sub_f32_e32 v60, v60, v157
	v_sub_f32_e32 v61, v61, v157
	v_sub_f32_e32 v62, v62, v157
	v_sub_f32_e32 v63, v63, v157
	v_add_f32_e32 v163, v49, v163
	s_waitcnt lgkmcnt(0)
	v_mfma_f32_32x32x16_bf16 v[16:31], v[198:201], v[164:167], v[16:31]
	v_exp_f32_e32 v56, v56
	v_exp_f32_e32 v57, v57
	v_exp_f32_e32 v58, v58
	v_exp_f32_e32 v59, v59
	v_exp_f32_e32 v60, v60
	v_exp_f32_e32 v61, v61
	ds_read_b64_tr_b16 v[200:201], v162 offset:30720
	ds_read_b64_tr_b16 v[198:199], v159 offset:28672
	v_mfma_f32_32x32x16_bf16 v[0:15], v[202:205], v[164:167], v[0:15]
	v_exp_f32_e32 v62, v62
	v_exp_f32_e32 v63, v63
	v_add_f32_e32 v163, v50, v163
	v_add_f32_e32 v163, v51, v163
	v_add_f32_e32 v163, v52, v163
	v_add_f32_e32 v163, v53, v163
	v_cvt_pk_bf16_f32 v164, v56, v57
	v_cvt_pk_bf16_f32 v165, v58, v59
	v_cvt_pk_bf16_f32 v166, v60, v61
	v_cvt_pk_bf16_f32 v167, v62, v63
	v_add_f32_e32 v163, v54, v163
	v_add_f32_e32 v163, v55, v163
	v_mfma_f32_32x32x16_bf16 v[64:79], v[206:209], v[164:167], v[64:79]
	v_add_f32_e32 v163, v56, v163
	v_add_f32_e32 v163, v57, v163
	v_add_f32_e32 v163, v58, v163
	v_add_f32_e32 v163, v59, v163
	v_add_f32_e32 v163, v60, v163
	v_add_f32_e32 v163, v61, v163
	v_add_f32_e32 v163, v62, v163
	v_mfma_f32_32x32x16_bf16 v[32:47], v[210:213], v[164:167], v[32:47]
	v_add_f32_e32 v163, v63, v163
	v_add_f32_e32 v161, v161, v163
	v_mfma_f32_32x32x16_bf16 v[16:31], v[214:217], v[164:167], v[16:31]
	s_waitcnt lgkmcnt(0)
	v_mfma_f32_32x32x16_bf16 v[0:15], v[198:201], v[164:167], v[0:15]
	v_max_f32_e32 v164, v81, v81
	v_max_f32_e32 v165, v80, v80
	v_max_f32_e32 v164, v165, v164
	v_max3_f32 v164, v164, v82, v83
	v_max3_f32 v164, v164, v84, v85
	v_max3_f32 v164, v164, v86, v87
	v_max3_f32 v164, v164, v88, v89
	v_max3_f32 v164, v164, v90, v91
	v_max3_f32 v164, v164, v92, v93
	v_max3_f32 v164, v164, v94, v95
	v_mov_b32_e32 v163, v164
	s_nop 1
	v_permlane32_swap_b32_e32 v164, v163
	v_max_f32_e32 v163, v164, v163
	v_sub_f32_e32 v163, v163, v157
	v_cmp_lt_f32_e32 vcc, s24, v163
	s_cbranch_vccz .LBB0_1828
	v_max_f32_e32 v163, v163, v163
	v_max_f32_e32 v163, 0, v163
	v_exp_f32_e64 v164, -v163
	v_add_f32_e32 v157, v157, v163
	v_pk_mul_f32 v[78:79], v[78:79], v[164:165] op_sel_hi:[1,0]
	v_pk_mul_f32 v[76:77], v[76:77], v[164:165] op_sel_hi:[1,0]
	v_pk_mul_f32 v[74:75], v[74:75], v[164:165] op_sel_hi:[1,0]
	v_pk_mul_f32 v[72:73], v[72:73], v[164:165] op_sel_hi:[1,0]
	v_pk_mul_f32 v[70:71], v[70:71], v[164:165] op_sel_hi:[1,0]
	v_pk_mul_f32 v[68:69], v[68:69], v[164:165] op_sel_hi:[1,0]
	v_pk_mul_f32 v[66:67], v[66:67], v[164:165] op_sel_hi:[1,0]
	v_pk_mul_f32 v[64:65], v[64:65], v[164:165] op_sel_hi:[1,0]
	v_pk_mul_f32 v[46:47], v[46:47], v[164:165] op_sel_hi:[1,0]
	v_pk_mul_f32 v[44:45], v[44:45], v[164:165] op_sel_hi:[1,0]
	v_pk_mul_f32 v[42:43], v[42:43], v[164:165] op_sel_hi:[1,0]
	v_pk_mul_f32 v[40:41], v[40:41], v[164:165] op_sel_hi:[1,0]
	v_pk_mul_f32 v[38:39], v[38:39], v[164:165] op_sel_hi:[1,0]
	v_pk_mul_f32 v[36:37], v[36:37], v[164:165] op_sel_hi:[1,0]
	v_pk_mul_f32 v[34:35], v[34:35], v[164:165] op_sel_hi:[1,0]
	v_pk_mul_f32 v[32:33], v[32:33], v[164:165] op_sel_hi:[1,0]
	v_pk_mul_f32 v[30:31], v[30:31], v[164:165] op_sel_hi:[1,0]
	v_pk_mul_f32 v[28:29], v[28:29], v[164:165] op_sel_hi:[1,0]
	v_pk_mul_f32 v[26:27], v[26:27], v[164:165] op_sel_hi:[1,0]
	v_pk_mul_f32 v[24:25], v[24:25], v[164:165] op_sel_hi:[1,0]
	v_pk_mul_f32 v[22:23], v[22:23], v[164:165] op_sel_hi:[1,0]
	v_pk_mul_f32 v[20:21], v[20:21], v[164:165] op_sel_hi:[1,0]
	v_pk_mul_f32 v[18:19], v[18:19], v[164:165] op_sel_hi:[1,0]
	v_pk_mul_f32 v[16:17], v[16:17], v[164:165] op_sel_hi:[1,0]
	v_pk_mul_f32 v[14:15], v[14:15], v[164:165] op_sel_hi:[1,0]
	v_pk_mul_f32 v[12:13], v[12:13], v[164:165] op_sel_hi:[1,0]
	v_pk_mul_f32 v[10:11], v[10:11], v[164:165] op_sel_hi:[1,0]
	v_pk_mul_f32 v[8:9], v[8:9], v[164:165] op_sel_hi:[1,0]
	v_pk_mul_f32 v[6:7], v[6:7], v[164:165] op_sel_hi:[1,0]
	v_pk_mul_f32 v[4:5], v[4:5], v[164:165] op_sel_hi:[1,0]
	v_pk_mul_f32 v[2:3], v[2:3], v[164:165] op_sel_hi:[1,0]
	v_pk_mul_f32 v[0:1], v[0:1], v[164:165] op_sel_hi:[1,0]
	v_mul_f32_e32 v161, v161, v164

.LBB0_1843:
	s_nop 10
	v_max_f32_e32 v0, v48, v49
	v_max3_f32 v0, v0, v50, v51
	v_max3_f32 v0, v0, v52, v53
	v_max3_f32 v0, v0, v54, v55
	v_max3_f32 v0, v0, v56, v57
	v_max3_f32 v0, v0, v58, v59
	v_max3_f32 v0, v0, v60, v61
	v_max3_f32 v0, v0, v62, v63
	v_mov_b32_e32 v1, v0
	s_nop 1
	v_permlane32_swap_b32_e32 v0, v1
	v_max_f32_e32 v0, v0, v1
	s_cmp_lg_u64 exec, 0
	v_add_f32_e32 v0, 0, v0
	s_cselect_b64 vcc, -1, 0
	v_cndmask_b32_e32 v151, 0, v0, vcc
	v_sub_f32_e32 v0, v48, v151
	v_exp_f32_e32 v48, v0
	v_sub_f32_e32 v0, v49, v151
	v_exp_f32_e32 v49, v0
	v_sub_f32_e32 v0, v50, v151
	v_exp_f32_e32 v50, v0
	v_sub_f32_e32 v0, v51, v151
	v_exp_f32_e32 v51, v0
	v_sub_f32_e32 v0, v52, v151
	v_exp_f32_e32 v52, v0
	v_sub_f32_e32 v0, v53, v151
	v_exp_f32_e32 v53, v0
	v_sub_f32_e32 v0, v54, v151
	v_exp_f32_e32 v54, v0
	v_sub_f32_e32 v0, v55, v151
	v_exp_f32_e32 v55, v0
	v_sub_f32_e32 v0, v56, v151
	v_exp_f32_e32 v56, v0
	ds_read_b64_tr_b16 v[0:1], v183 offset:24576
	ds_read_b64_tr_b16 v[2:3], v185 offset:26624
	v_cvt_pk_bf16_f32 v4, v48, v49
	v_cvt_pk_bf16_f32 v5, v50, v51
	v_cvt_pk_bf16_f32 v6, v52, v53
	v_cvt_pk_bf16_f32 v7, v54, v55
	ds_read_b64_tr_b16 v[8:9], v182 offset:24576
	ds_read_b64_tr_b16 v[10:11], v184 offset:26624
	ds_read_b64_tr_b16 v[202:203], v185 offset:30720
	ds_read_b64_tr_b16 v[200:201], v183 offset:28672
	s_waitcnt lgkmcnt(0)
	v_mfma_f32_32x32x16_bf16 v[64:79], v[0:3], v[4:7], 0
	v_sub_f32_e32 v0, v57, v151
	v_add_f32_e32 v153, 0, v48
	v_exp_f32_e32 v57, v0
	ds_read_b64_tr_b16 v[0:1], v186 offset:24576
	ds_read_b64_tr_b16 v[2:3], v188 offset:26624
	ds_read_b64_tr_b16 v[206:207], v184 offset:30720
	ds_read_b64_tr_b16 v[204:205], v182 offset:28672
	v_add_f32_e32 v153, v49, v153
	v_add_f32_e32 v153, v50, v153
	v_add_f32_e32 v153, v51, v153
	v_mfma_f32_32x32x16_bf16 v[32:47], v[8:11], v[4:7], 0
	v_sub_f32_e32 v8, v59, v151
	v_exp_f32_e32 v59, v8
	ds_read_b64_tr_b16 v[8:9], v187 offset:24576
	ds_read_b64_tr_b16 v[10:11], v189 offset:26624
	ds_read_b64_tr_b16 v[210:211], v188 offset:30720
	ds_read_b64_tr_b16 v[208:209], v186 offset:28672
	v_add_f32_e32 v153, v52, v153
	v_sub_f32_e32 v12, v58, v151
	v_add_f32_e32 v153, v53, v153
	v_exp_f32_e32 v58, v12
	s_waitcnt lgkmcnt(0)
	v_mfma_f32_32x32x16_bf16 v[16:31], v[0:3], v[4:7], 0
	v_sub_f32_e32 v0, v60, v151
	v_exp_f32_e32 v60, v0
	v_sub_f32_e32 v0, v61, v151
	v_exp_f32_e32 v61, v0
	v_add_f32_e32 v153, v54, v153
	v_add_f32_e32 v153, v55, v153
	v_max_f32_e32 v157, v81, v81
	v_mfma_f32_32x32x16_bf16 v[0:15], v[8:11], v[4:7], 0
	v_max_f32_e32 v199, v80, v80
	v_sub_f32_e32 v62, v62, v151
	v_sub_f32_e32 v63, v63, v151
	v_add_f32_e32 v153, v56, v153
	v_max_f32_e32 v157, v199, v157
	ds_read_b64_tr_b16 v[214:215], v189 offset:30720
	ds_read_b64_tr_b16 v[212:213], v187 offset:28672
	v_exp_f32_e32 v62, v62
	v_exp_f32_e32 v63, v63
	v_add_f32_e32 v153, v57, v153
	v_max3_f32 v157, v157, v82, v83
	v_add_f32_e32 v153, v58, v153
	v_max3_f32 v157, v157, v84, v85
	v_add_f32_e32 v153, v59, v153
	v_max3_f32 v157, v157, v86, v87
	v_add_f32_e32 v153, v60, v153
	v_max3_f32 v157, v157, v88, v89
	v_cvt_pk_bf16_f32 v216, v56, v57
	v_cvt_pk_bf16_f32 v217, v58, v59
	v_cvt_pk_bf16_f32 v218, v60, v61
	v_cvt_pk_bf16_f32 v219, v62, v63
	v_add_f32_e32 v153, v61, v153
	v_max3_f32 v157, v157, v90, v91
	v_mfma_f32_32x32x16_bf16 v[64:79], v[200:203], v[216:219], v[64:79]
	v_add_f32_e32 v153, v62, v153
	v_max3_f32 v157, v157, v92, v93
	v_add_f32_e32 v153, v63, v153
	v_max3_f32 v199, v157, v94, v95
	v_add_f32_e32 v157, 0, v153
	v_mov_b32_e32 v153, v199
	s_nop 1
	v_permlane32_swap_b32_e32 v199, v153
	v_mfma_f32_32x32x16_bf16 v[32:47], v[204:207], v[216:219], v[32:47]
	v_max_f32_e32 v153, v153, v153
	v_max_f32_e32 v199, v199, v199
	v_max_f32_e32 v153, v199, v153
	v_sub_f32_e32 v153, v153, v151
	s_mov_b32 s2, 0x41000000
	v_cmp_lt_f32_e32 vcc, s2, v153
	v_mfma_f32_32x32x16_bf16 v[16:31], v[208:211], v[216:219], v[16:31]
	s_waitcnt lgkmcnt(0)
	v_mfma_f32_32x32x16_bf16 v[0:15], v[212:215], v[216:219], v[0:15]
	s_cbranch_vccz .LBB0_1845
	v_max_f32_e32 v153, v153, v153
	v_max_f32_e32 v153, 0, v153
	v_exp_f32_e64 v200, -v153
	v_add_f32_e32 v151, v151, v153
	v_pk_mul_f32 v[78:79], v[78:79], v[200:201] op_sel_hi:[1,0]
	v_pk_mul_f32 v[76:77], v[76:77], v[200:201] op_sel_hi:[1,0]
	v_pk_mul_f32 v[74:75], v[74:75], v[200:201] op_sel_hi:[1,0]
	v_pk_mul_f32 v[72:73], v[72:73], v[200:201] op_sel_hi:[1,0]
	v_pk_mul_f32 v[70:71], v[70:71], v[200:201] op_sel_hi:[1,0]
	v_pk_mul_f32 v[68:69], v[68:69], v[200:201] op_sel_hi:[1,0]
	v_pk_mul_f32 v[66:67], v[66:67], v[200:201] op_sel_hi:[1,0]
	v_pk_mul_f32 v[64:65], v[64:65], v[200:201] op_sel_hi:[1,0]
	v_pk_mul_f32 v[46:47], v[46:47], v[200:201] op_sel_hi:[1,0]
	v_pk_mul_f32 v[44:45], v[44:45], v[200:201] op_sel_hi:[1,0]
	v_pk_mul_f32 v[42:43], v[42:43], v[200:201] op_sel_hi:[1,0]
	v_pk_mul_f32 v[40:41], v[40:41], v[200:201] op_sel_hi:[1,0]
	v_pk_mul_f32 v[38:39], v[38:39], v[200:201] op_sel_hi:[1,0]
	v_pk_mul_f32 v[36:37], v[36:37], v[200:201] op_sel_hi:[1,0]
	v_pk_mul_f32 v[34:35], v[34:35], v[200:201] op_sel_hi:[1,0]
	v_pk_mul_f32 v[32:33], v[32:33], v[200:201] op_sel_hi:[1,0]
	v_pk_mul_f32 v[30:31], v[30:31], v[200:201] op_sel_hi:[1,0]
	v_pk_mul_f32 v[28:29], v[28:29], v[200:201] op_sel_hi:[1,0]
	v_pk_mul_f32 v[26:27], v[26:27], v[200:201] op_sel_hi:[1,0]
	v_pk_mul_f32 v[24:25], v[24:25], v[200:201] op_sel_hi:[1,0]
	v_pk_mul_f32 v[22:23], v[22:23], v[200:201] op_sel_hi:[1,0]
	v_pk_mul_f32 v[20:21], v[20:21], v[200:201] op_sel_hi:[1,0]
	v_pk_mul_f32 v[18:19], v[18:19], v[200:201] op_sel_hi:[1,0]
	v_pk_mul_f32 v[16:17], v[16:17], v[200:201] op_sel_hi:[1,0]
	v_pk_mul_f32 v[14:15], v[14:15], v[200:201] op_sel_hi:[1,0]
	v_pk_mul_f32 v[12:13], v[12:13], v[200:201] op_sel_hi:[1,0]
	v_pk_mul_f32 v[10:11], v[10:11], v[200:201] op_sel_hi:[1,0]
	v_pk_mul_f32 v[8:9], v[8:9], v[200:201] op_sel_hi:[1,0]
	v_pk_mul_f32 v[6:7], v[6:7], v[200:201] op_sel_hi:[1,0]
	v_pk_mul_f32 v[4:5], v[4:5], v[200:201] op_sel_hi:[1,0]
	v_pk_mul_f32 v[2:3], v[2:3], v[200:201] op_sel_hi:[1,0]
	v_pk_mul_f32 v[0:1], v[0:1], v[200:201] op_sel_hi:[1,0]
	v_mul_f32_e32 v157, v157, v200

.LBB0_1858:
	s_setprio 1
	s_nop 7
	v_max_f32_e32 v155, v48, v49
	v_max3_f32 v155, v155, v50, v51
	v_max3_f32 v155, v155, v52, v53
	v_max3_f32 v155, v155, v54, v55
	v_max3_f32 v155, v155, v56, v57
	v_max3_f32 v155, v155, v58, v59
	v_max3_f32 v155, v155, v60, v61
	v_max3_f32 v155, v155, v62, v63
	v_mov_b32_e32 v161, v155
	s_nop 1
	v_permlane32_swap_b32_e32 v155, v161
	v_max_f32_e32 v155, v155, v161
	v_sub_f32_e32 v155, v155, v151
	v_cmp_lt_f32_e32 vcc, s26, v155
	s_cbranch_vccz .LBB0_1860
	v_max_f32_e32 v155, v155, v155
	v_max_f32_e32 v155, 0, v155
	v_exp_f32_e64 v168, -v155
	v_add_f32_e32 v151, v151, v155
	v_pk_mul_f32 v[78:79], v[78:79], v[168:169] op_sel_hi:[1,0]
	v_pk_mul_f32 v[76:77], v[76:77], v[168:169] op_sel_hi:[1,0]
	v_pk_mul_f32 v[74:75], v[74:75], v[168:169] op_sel_hi:[1,0]
	v_pk_mul_f32 v[72:73], v[72:73], v[168:169] op_sel_hi:[1,0]
	v_pk_mul_f32 v[70:71], v[70:71], v[168:169] op_sel_hi:[1,0]
	v_pk_mul_f32 v[68:69], v[68:69], v[168:169] op_sel_hi:[1,0]
	v_pk_mul_f32 v[66:67], v[66:67], v[168:169] op_sel_hi:[1,0]
	v_pk_mul_f32 v[64:65], v[64:65], v[168:169] op_sel_hi:[1,0]
	v_pk_mul_f32 v[46:47], v[46:47], v[168:169] op_sel_hi:[1,0]
	v_pk_mul_f32 v[44:45], v[44:45], v[168:169] op_sel_hi:[1,0]
	v_pk_mul_f32 v[42:43], v[42:43], v[168:169] op_sel_hi:[1,0]
	v_pk_mul_f32 v[40:41], v[40:41], v[168:169] op_sel_hi:[1,0]
	v_pk_mul_f32 v[38:39], v[38:39], v[168:169] op_sel_hi:[1,0]
	v_pk_mul_f32 v[36:37], v[36:37], v[168:169] op_sel_hi:[1,0]
	v_pk_mul_f32 v[34:35], v[34:35], v[168:169] op_sel_hi:[1,0]
	v_pk_mul_f32 v[32:33], v[32:33], v[168:169] op_sel_hi:[1,0]
	v_pk_mul_f32 v[30:31], v[30:31], v[168:169] op_sel_hi:[1,0]
	v_pk_mul_f32 v[28:29], v[28:29], v[168:169] op_sel_hi:[1,0]
	v_pk_mul_f32 v[26:27], v[26:27], v[168:169] op_sel_hi:[1,0]
	v_pk_mul_f32 v[24:25], v[24:25], v[168:169] op_sel_hi:[1,0]
	v_pk_mul_f32 v[22:23], v[22:23], v[168:169] op_sel_hi:[1,0]
	v_pk_mul_f32 v[20:21], v[20:21], v[168:169] op_sel_hi:[1,0]
	v_pk_mul_f32 v[18:19], v[18:19], v[168:169] op_sel_hi:[1,0]
	v_pk_mul_f32 v[16:17], v[16:17], v[168:169] op_sel_hi:[1,0]
	v_pk_mul_f32 v[14:15], v[14:15], v[168:169] op_sel_hi:[1,0]
	v_pk_mul_f32 v[12:13], v[12:13], v[168:169] op_sel_hi:[1,0]
	v_pk_mul_f32 v[10:11], v[10:11], v[168:169] op_sel_hi:[1,0]
	v_pk_mul_f32 v[8:9], v[8:9], v[168:169] op_sel_hi:[1,0]
	v_pk_mul_f32 v[6:7], v[6:7], v[168:169] op_sel_hi:[1,0]
	v_pk_mul_f32 v[4:5], v[4:5], v[168:169] op_sel_hi:[1,0]
	v_pk_mul_f32 v[2:3], v[2:3], v[168:169] op_sel_hi:[1,0]
	v_pk_mul_f32 v[0:1], v[0:1], v[168:169] op_sel_hi:[1,0]
	v_mul_f32_e32 v157, v157, v168
.LBB0_1860:
	v_add_u32_e32 v168, s27, v174
	v_add_u32_e32 v198, s27, v175
	v_sub_f32_e32 v48, v48, v151
	v_sub_f32_e32 v49, v49, v151
	v_sub_f32_e32 v50, v50, v151
	v_sub_f32_e32 v51, v51, v151
	v_sub_f32_e32 v52, v52, v151
	v_sub_f32_e32 v53, v53, v151
	v_sub_f32_e32 v54, v54, v151
	v_sub_f32_e32 v55, v55, v151
	v_add_u32_e32 v161, v168, v177
	v_exp_f32_e32 v48, v48
	v_exp_f32_e32 v49, v49
	v_exp_f32_e32 v50, v50
	v_exp_f32_e32 v51, v51
	v_exp_f32_e32 v52, v52
	v_exp_f32_e32 v53, v53
	v_exp_f32_e32 v54, v54
	v_exp_f32_e32 v55, v55
	v_add_u32_e32 v165, v198, v177
	ds_read_b64_tr_b16 v[204:205], v161 offset:24576
	ds_read_b64_tr_b16 v[206:207], v165 offset:26624
	v_add_u32_e32 v155, v168, v178
	v_add_u32_e32 v163, v198, v178
	ds_read_b64_tr_b16 v[208:209], v155 offset:24576
	ds_read_b64_tr_b16 v[210:211], v163 offset:26624
	ds_read_b64_tr_b16 v[214:215], v165 offset:30720
	ds_read_b64_tr_b16 v[212:213], v161 offset:28672
	v_cvt_pk_bf16_f32 v200, v48, v49
	v_cvt_pk_bf16_f32 v201, v50, v51
	v_cvt_pk_bf16_f32 v202, v52, v53
	v_cvt_pk_bf16_f32 v203, v54, v55
	v_add_u32_e32 v167, v168, v179
	v_add_u32_e32 v168, v168, v180
	s_waitcnt lgkmcnt(0)
	v_mfma_f32_32x32x16_bf16 v[64:79], v[204:207], v[200:203], v[64:79]
	v_add_u32_e32 v169, v198, v179
	ds_read_b64_tr_b16 v[204:205], v167 offset:24576
	ds_read_b64_tr_b16 v[206:207], v169 offset:26624
	ds_read_b64_tr_b16 v[218:219], v163 offset:30720
	ds_read_b64_tr_b16 v[216:217], v155 offset:28672
	v_add_u32_e32 v198, v198, v180
	v_add_f32_e32 v199, 0, v48
	v_sub_f32_e32 v56, v56, v151
	v_sub_f32_e32 v57, v57, v151
	v_sub_f32_e32 v58, v58, v151
	v_mfma_f32_32x32x16_bf16 v[32:47], v[208:211], v[200:203], v[32:47]
	ds_read_b64_tr_b16 v[208:209], v168 offset:24576
	ds_read_b64_tr_b16 v[210:211], v198 offset:26624
	ds_read_b64_tr_b16 v[226:227], v169 offset:30720
	ds_read_b64_tr_b16 v[224:225], v167 offset:28672
	v_sub_f32_e32 v59, v59, v151
	v_sub_f32_e32 v60, v60, v151
	v_sub_f32_e32 v61, v61, v151
	v_sub_f32_e32 v62, v62, v151
	v_sub_f32_e32 v63, v63, v151
	v_add_f32_e32 v199, v49, v199
	s_waitcnt lgkmcnt(0)
	v_mfma_f32_32x32x16_bf16 v[16:31], v[204:207], v[200:203], v[16:31]
	v_exp_f32_e32 v56, v56
	v_exp_f32_e32 v57, v57
	v_exp_f32_e32 v58, v58
	v_exp_f32_e32 v59, v59
	v_exp_f32_e32 v60, v60
	v_exp_f32_e32 v61, v61
	ds_read_b64_tr_b16 v[206:207], v198 offset:30720
	ds_read_b64_tr_b16 v[204:205], v168 offset:28672
	v_mfma_f32_32x32x16_bf16 v[0:15], v[208:211], v[200:203], v[0:15]
	v_exp_f32_e32 v62, v62
	v_exp_f32_e32 v63, v63
	v_add_f32_e32 v199, v50, v199
	v_add_f32_e32 v199, v51, v199
	v_add_f32_e32 v199, v52, v199
	v_add_f32_e32 v199, v53, v199
	v_cvt_pk_bf16_f32 v200, v56, v57
	v_cvt_pk_bf16_f32 v201, v58, v59
	v_cvt_pk_bf16_f32 v202, v60, v61
	v_cvt_pk_bf16_f32 v203, v62, v63
	v_add_f32_e32 v199, v54, v199
	v_add_f32_e32 v199, v55, v199
	v_mfma_f32_32x32x16_bf16 v[64:79], v[212:215], v[200:203], v[64:79]
	v_add_f32_e32 v199, v56, v199
	v_add_f32_e32 v199, v57, v199
	v_add_f32_e32 v199, v58, v199
	v_add_f32_e32 v199, v59, v199
	v_add_f32_e32 v199, v60, v199
	v_add_f32_e32 v199, v61, v199
	v_add_f32_e32 v199, v62, v199
	v_mfma_f32_32x32x16_bf16 v[32:47], v[216:219], v[200:203], v[32:47]
	v_add_f32_e32 v199, v63, v199
	v_add_f32_e32 v157, v157, v199
	v_mfma_f32_32x32x16_bf16 v[16:31], v[224:227], v[200:203], v[16:31]
	s_waitcnt lgkmcnt(0)
	v_mfma_f32_32x32x16_bf16 v[0:15], v[204:207], v[200:203], v[0:15]
	v_max_f32_e32 v200, v81, v81
	v_max_f32_e32 v201, v80, v80
	v_max_f32_e32 v200, v201, v200
	v_max3_f32 v200, v200, v82, v83
	v_max3_f32 v200, v200, v84, v85
	v_max3_f32 v200, v200, v86, v87
	v_max3_f32 v200, v200, v88, v89
	v_max3_f32 v200, v200, v90, v91
	v_max3_f32 v200, v200, v92, v93
	v_max3_f32 v200, v200, v94, v95
	v_mov_b32_e32 v199, v200
	s_nop 1
	v_permlane32_swap_b32_e32 v200, v199
	v_max_f32_e32 v199, v200, v199
	v_sub_f32_e32 v199, v199, v151
	v_cmp_lt_f32_e32 vcc, s26, v199
	s_cbranch_vccz .LBB0_1862
	v_max_f32_e32 v199, v199, v199
	v_max_f32_e32 v199, 0, v199
	v_exp_f32_e64 v200, -v199
	v_add_f32_e32 v151, v151, v199
	v_pk_mul_f32 v[78:79], v[78:79], v[200:201] op_sel_hi:[1,0]
	v_pk_mul_f32 v[76:77], v[76:77], v[200:201] op_sel_hi:[1,0]
	v_pk_mul_f32 v[74:75], v[74:75], v[200:201] op_sel_hi:[1,0]
	v_pk_mul_f32 v[72:73], v[72:73], v[200:201] op_sel_hi:[1,0]
	v_pk_mul_f32 v[70:71], v[70:71], v[200:201] op_sel_hi:[1,0]
	v_pk_mul_f32 v[68:69], v[68:69], v[200:201] op_sel_hi:[1,0]
	v_pk_mul_f32 v[66:67], v[66:67], v[200:201] op_sel_hi:[1,0]
	v_pk_mul_f32 v[64:65], v[64:65], v[200:201] op_sel_hi:[1,0]
	v_pk_mul_f32 v[46:47], v[46:47], v[200:201] op_sel_hi:[1,0]
	v_pk_mul_f32 v[44:45], v[44:45], v[200:201] op_sel_hi:[1,0]
	v_pk_mul_f32 v[42:43], v[42:43], v[200:201] op_sel_hi:[1,0]
	v_pk_mul_f32 v[40:41], v[40:41], v[200:201] op_sel_hi:[1,0]
	v_pk_mul_f32 v[38:39], v[38:39], v[200:201] op_sel_hi:[1,0]
	v_pk_mul_f32 v[36:37], v[36:37], v[200:201] op_sel_hi:[1,0]
	v_pk_mul_f32 v[34:35], v[34:35], v[200:201] op_sel_hi:[1,0]
	v_pk_mul_f32 v[32:33], v[32:33], v[200:201] op_sel_hi:[1,0]
	v_pk_mul_f32 v[30:31], v[30:31], v[200:201] op_sel_hi:[1,0]
	v_pk_mul_f32 v[28:29], v[28:29], v[200:201] op_sel_hi:[1,0]
	v_pk_mul_f32 v[26:27], v[26:27], v[200:201] op_sel_hi:[1,0]
	v_pk_mul_f32 v[24:25], v[24:25], v[200:201] op_sel_hi:[1,0]
	v_pk_mul_f32 v[22:23], v[22:23], v[200:201] op_sel_hi:[1,0]
	v_pk_mul_f32 v[20:21], v[20:21], v[200:201] op_sel_hi:[1,0]
	v_pk_mul_f32 v[18:19], v[18:19], v[200:201] op_sel_hi:[1,0]
	v_pk_mul_f32 v[16:17], v[16:17], v[200:201] op_sel_hi:[1,0]
	v_pk_mul_f32 v[14:15], v[14:15], v[200:201] op_sel_hi:[1,0]
	v_pk_mul_f32 v[12:13], v[12:13], v[200:201] op_sel_hi:[1,0]
	v_pk_mul_f32 v[10:11], v[10:11], v[200:201] op_sel_hi:[1,0]
	v_pk_mul_f32 v[8:9], v[8:9], v[200:201] op_sel_hi:[1,0]
	v_pk_mul_f32 v[6:7], v[6:7], v[200:201] op_sel_hi:[1,0]
	v_pk_mul_f32 v[4:5], v[4:5], v[200:201] op_sel_hi:[1,0]
	v_pk_mul_f32 v[2:3], v[2:3], v[200:201] op_sel_hi:[1,0]
	v_pk_mul_f32 v[0:1], v[0:1], v[200:201] op_sel_hi:[1,0]
	v_mul_f32_e32 v157, v157, v200

.LBB0_1877:
	s_nop 10
	v_max_f32_e32 v0, v48, v49
	v_max3_f32 v0, v0, v50, v51
	v_max3_f32 v0, v0, v52, v53
	v_max3_f32 v0, v0, v54, v55
	v_max3_f32 v0, v0, v56, v57
	v_max3_f32 v0, v0, v58, v59
	v_max3_f32 v0, v0, v60, v61
	v_max3_f32 v0, v0, v62, v63
	v_mov_b32_e32 v1, v0
	s_nop 1
	v_permlane32_swap_b32_e32 v0, v1
	v_max_f32_e32 v0, v0, v1
	s_cmp_lg_u64 exec, 0
	v_add_f32_e32 v0, 0, v0
	s_cselect_b64 vcc, -1, 0
	v_cndmask_b32_e32 v151, 0, v0, vcc
	v_sub_f32_e32 v0, v48, v151
	v_exp_f32_e32 v48, v0
	v_sub_f32_e32 v0, v49, v151
	v_exp_f32_e32 v49, v0
	v_sub_f32_e32 v0, v50, v151
	v_exp_f32_e32 v50, v0
	v_sub_f32_e32 v0, v51, v151
	v_exp_f32_e32 v51, v0
	v_sub_f32_e32 v0, v52, v151
	v_exp_f32_e32 v52, v0
	v_sub_f32_e32 v0, v53, v151
	v_exp_f32_e32 v53, v0
	v_sub_f32_e32 v0, v54, v151
	v_exp_f32_e32 v54, v0
	v_sub_f32_e32 v0, v55, v151
	v_exp_f32_e32 v55, v0
	v_sub_f32_e32 v0, v56, v151
	v_exp_f32_e32 v56, v0
	ds_read_b64_tr_b16 v[0:1], v183 offset:24576
	ds_read_b64_tr_b16 v[2:3], v185 offset:26624
	v_cvt_pk_bf16_f32 v4, v48, v49
	v_cvt_pk_bf16_f32 v5, v50, v51
	v_cvt_pk_bf16_f32 v6, v52, v53
	v_cvt_pk_bf16_f32 v7, v54, v55
	ds_read_b64_tr_b16 v[8:9], v182 offset:24576
	ds_read_b64_tr_b16 v[10:11], v184 offset:26624
	ds_read_b64_tr_b16 v[200:201], v185 offset:30720
	ds_read_b64_tr_b16 v[198:199], v183 offset:28672
	s_waitcnt lgkmcnt(0)
	v_mfma_f32_32x32x16_bf16 v[64:79], v[0:3], v[4:7], 0
	v_sub_f32_e32 v0, v57, v151
	v_exp_f32_e32 v57, v0
	ds_read_b64_tr_b16 v[0:1], v186 offset:24576
	ds_read_b64_tr_b16 v[2:3], v188 offset:26624
	ds_read_b64_tr_b16 v[204:205], v184 offset:30720
	ds_read_b64_tr_b16 v[202:203], v182 offset:28672
	v_sub_f32_e32 v12, v58, v151
	v_sub_f32_e32 v62, v62, v151
	v_sub_f32_e32 v63, v63, v151
	v_exp_f32_e32 v58, v12
	s_waitcnt lgkmcnt(0)
	v_mfma_f32_32x32x16_bf16 v[16:31], v[0:3], v[4:7], 0
	v_sub_f32_e32 v0, v60, v151
	v_exp_f32_e32 v60, v0
	v_sub_f32_e32 v0, v61, v151
	v_exp_f32_e32 v61, v0
	v_exp_f32_e32 v62, v62
	v_exp_f32_e32 v63, v63
	v_add_f32_e32 v157, 0, v48
	v_mfma_f32_32x32x16_bf16 v[32:47], v[8:11], v[4:7], 0
	v_sub_f32_e32 v8, v59, v151
	v_exp_f32_e32 v59, v8
	ds_read_b64_tr_b16 v[8:9], v187 offset:24576
	ds_read_b64_tr_b16 v[10:11], v189 offset:26624
	ds_read_b64_tr_b16 v[208:209], v188 offset:30720
	ds_read_b64_tr_b16 v[206:207], v186 offset:28672
	v_cvt_pk_bf16_f32 v214, v56, v57
	v_cvt_pk_bf16_f32 v216, v60, v61
	v_cvt_pk_bf16_f32 v215, v58, v59
	v_cvt_pk_bf16_f32 v217, v62, v63
	s_waitcnt lgkmcnt(0)
	v_mfma_f32_32x32x16_bf16 v[0:15], v[8:11], v[4:7], 0
	v_add_f32_e32 v157, v49, v157
	v_add_f32_e32 v157, v50, v157
	v_add_f32_e32 v157, v51, v157
	ds_read_b64_tr_b16 v[212:213], v189 offset:30720
	ds_read_b64_tr_b16 v[210:211], v187 offset:28672
	v_add_f32_e32 v157, v52, v157
	v_add_f32_e32 v157, v53, v157
	v_add_f32_e32 v157, v54, v157
	v_mfma_f32_32x32x16_bf16 v[64:79], v[198:201], v[214:217], v[64:79]
	v_max_f32_e32 v198, v80, v81
	v_max3_f32 v198, v198, v82, v83
	v_max3_f32 v198, v198, v84, v85
	v_max3_f32 v198, v198, v86, v87
	v_add_f32_e32 v157, v55, v157
	v_max3_f32 v198, v198, v88, v89
	v_add_f32_e32 v157, v56, v157
	v_max3_f32 v198, v198, v90, v91
	v_mfma_f32_32x32x16_bf16 v[32:47], v[202:205], v[214:217], v[32:47]
	v_add_f32_e32 v157, v57, v157
	v_max3_f32 v198, v198, v92, v93
	v_add_f32_e32 v157, v58, v157
	v_max3_f32 v198, v198, v94, v95
	v_add_f32_e32 v157, v59, v157
	v_mov_b32_e32 v199, v198
	v_add_f32_e32 v157, v60, v157
	v_mfma_f32_32x32x16_bf16 v[16:31], v[206:209], v[214:217], v[16:31]
	v_permlane32_swap_b32_e32 v198, v199
	v_add_f32_e32 v157, v61, v157
	v_max_f32_e32 v199, v199, v199
	v_max_f32_e32 v198, v198, v198
	v_add_f32_e32 v157, v62, v157
	v_max_f32_e32 v198, v198, v199
	s_waitcnt lgkmcnt(0)
	v_mfma_f32_32x32x16_bf16 v[0:15], v[210:213], v[214:217], v[0:15]
	v_add_f32_e32 v157, v63, v157
	v_sub_f32_e32 v198, v198, v151
	s_mov_b32 s2, 0x41000000
	v_add_f32_e32 v157, 0, v157
	v_cmp_lt_f32_e32 vcc, s2, v198
	s_cbranch_vccz .LBB0_1879
	v_max_f32_e32 v198, v198, v198
	v_max_f32_e32 v199, 0, v198
	v_exp_f32_e64 v198, -v199
	v_add_f32_e32 v151, v151, v199
	v_pk_mul_f32 v[78:79], v[78:79], v[198:199] op_sel_hi:[1,0]
	v_pk_mul_f32 v[76:77], v[76:77], v[198:199] op_sel_hi:[1,0]
	v_pk_mul_f32 v[74:75], v[74:75], v[198:199] op_sel_hi:[1,0]
	v_pk_mul_f32 v[72:73], v[72:73], v[198:199] op_sel_hi:[1,0]
	v_pk_mul_f32 v[70:71], v[70:71], v[198:199] op_sel_hi:[1,0]
	v_pk_mul_f32 v[68:69], v[68:69], v[198:199] op_sel_hi:[1,0]
	v_pk_mul_f32 v[66:67], v[66:67], v[198:199] op_sel_hi:[1,0]
	v_pk_mul_f32 v[64:65], v[64:65], v[198:199] op_sel_hi:[1,0]
	v_pk_mul_f32 v[46:47], v[46:47], v[198:199] op_sel_hi:[1,0]
	v_pk_mul_f32 v[44:45], v[44:45], v[198:199] op_sel_hi:[1,0]
	v_pk_mul_f32 v[42:43], v[42:43], v[198:199] op_sel_hi:[1,0]
	v_pk_mul_f32 v[40:41], v[40:41], v[198:199] op_sel_hi:[1,0]
	v_pk_mul_f32 v[38:39], v[38:39], v[198:199] op_sel_hi:[1,0]
	v_pk_mul_f32 v[36:37], v[36:37], v[198:199] op_sel_hi:[1,0]
	v_pk_mul_f32 v[34:35], v[34:35], v[198:199] op_sel_hi:[1,0]
	v_pk_mul_f32 v[32:33], v[32:33], v[198:199] op_sel_hi:[1,0]
	v_pk_mul_f32 v[30:31], v[30:31], v[198:199] op_sel_hi:[1,0]
	v_pk_mul_f32 v[28:29], v[28:29], v[198:199] op_sel_hi:[1,0]
	v_pk_mul_f32 v[26:27], v[26:27], v[198:199] op_sel_hi:[1,0]
	v_pk_mul_f32 v[24:25], v[24:25], v[198:199] op_sel_hi:[1,0]
	v_pk_mul_f32 v[22:23], v[22:23], v[198:199] op_sel_hi:[1,0]
	v_pk_mul_f32 v[20:21], v[20:21], v[198:199] op_sel_hi:[1,0]
	v_pk_mul_f32 v[18:19], v[18:19], v[198:199] op_sel_hi:[1,0]
	v_pk_mul_f32 v[16:17], v[16:17], v[198:199] op_sel_hi:[1,0]
	v_pk_mul_f32 v[14:15], v[14:15], v[198:199] op_sel_hi:[1,0]
	v_pk_mul_f32 v[12:13], v[12:13], v[198:199] op_sel_hi:[1,0]
	v_pk_mul_f32 v[10:11], v[10:11], v[198:199] op_sel_hi:[1,0]
	v_pk_mul_f32 v[8:9], v[8:9], v[198:199] op_sel_hi:[1,0]
	v_pk_mul_f32 v[6:7], v[6:7], v[198:199] op_sel_hi:[1,0]
	v_pk_mul_f32 v[4:5], v[4:5], v[198:199] op_sel_hi:[1,0]
	v_pk_mul_f32 v[2:3], v[2:3], v[198:199] op_sel_hi:[1,0]
	v_pk_mul_f32 v[0:1], v[0:1], v[198:199] op_sel_hi:[1,0]
	v_mul_f32_e32 v157, v157, v198

.LBB0_1892:
	s_setprio 1
	s_nop 7
	v_max_f32_e32 v153, v48, v49
	v_max3_f32 v153, v153, v50, v51
	v_max3_f32 v153, v153, v52, v53
	v_max3_f32 v153, v153, v54, v55
	v_max3_f32 v153, v153, v56, v57
	v_max3_f32 v153, v153, v58, v59
	v_max3_f32 v153, v153, v60, v61
	v_max3_f32 v153, v153, v62, v63
	v_mov_b32_e32 v155, v153
	s_nop 1
	v_permlane32_swap_b32_e32 v153, v155
	v_max_f32_e32 v153, v153, v155
	v_sub_f32_e32 v153, v153, v151
	v_cmp_lt_f32_e32 vcc, s25, v153
	s_cbranch_vccz .LBB0_1894
	v_max_f32_e32 v153, v153, v153
	v_max_f32_e32 v153, 0, v153
	v_exp_f32_e64 v198, -v153
	v_add_f32_e32 v151, v151, v153
	v_pk_mul_f32 v[78:79], v[78:79], v[198:199] op_sel_hi:[1,0]
	v_pk_mul_f32 v[76:77], v[76:77], v[198:199] op_sel_hi:[1,0]
	v_pk_mul_f32 v[74:75], v[74:75], v[198:199] op_sel_hi:[1,0]
	v_pk_mul_f32 v[72:73], v[72:73], v[198:199] op_sel_hi:[1,0]
	v_pk_mul_f32 v[70:71], v[70:71], v[198:199] op_sel_hi:[1,0]
	v_pk_mul_f32 v[68:69], v[68:69], v[198:199] op_sel_hi:[1,0]
	v_pk_mul_f32 v[66:67], v[66:67], v[198:199] op_sel_hi:[1,0]
	v_pk_mul_f32 v[64:65], v[64:65], v[198:199] op_sel_hi:[1,0]
	v_pk_mul_f32 v[46:47], v[46:47], v[198:199] op_sel_hi:[1,0]
	v_pk_mul_f32 v[44:45], v[44:45], v[198:199] op_sel_hi:[1,0]
	v_pk_mul_f32 v[42:43], v[42:43], v[198:199] op_sel_hi:[1,0]
	v_pk_mul_f32 v[40:41], v[40:41], v[198:199] op_sel_hi:[1,0]
	v_pk_mul_f32 v[38:39], v[38:39], v[198:199] op_sel_hi:[1,0]
	v_pk_mul_f32 v[36:37], v[36:37], v[198:199] op_sel_hi:[1,0]
	v_pk_mul_f32 v[34:35], v[34:35], v[198:199] op_sel_hi:[1,0]
	v_pk_mul_f32 v[32:33], v[32:33], v[198:199] op_sel_hi:[1,0]
	v_pk_mul_f32 v[30:31], v[30:31], v[198:199] op_sel_hi:[1,0]
	v_pk_mul_f32 v[28:29], v[28:29], v[198:199] op_sel_hi:[1,0]
	v_pk_mul_f32 v[26:27], v[26:27], v[198:199] op_sel_hi:[1,0]
	v_pk_mul_f32 v[24:25], v[24:25], v[198:199] op_sel_hi:[1,0]
	v_pk_mul_f32 v[22:23], v[22:23], v[198:199] op_sel_hi:[1,0]
	v_pk_mul_f32 v[20:21], v[20:21], v[198:199] op_sel_hi:[1,0]
	v_pk_mul_f32 v[18:19], v[18:19], v[198:199] op_sel_hi:[1,0]
	v_pk_mul_f32 v[16:17], v[16:17], v[198:199] op_sel_hi:[1,0]
	v_pk_mul_f32 v[14:15], v[14:15], v[198:199] op_sel_hi:[1,0]
	v_pk_mul_f32 v[12:13], v[12:13], v[198:199] op_sel_hi:[1,0]
	v_pk_mul_f32 v[10:11], v[10:11], v[198:199] op_sel_hi:[1,0]
	v_pk_mul_f32 v[8:9], v[8:9], v[198:199] op_sel_hi:[1,0]
	v_pk_mul_f32 v[6:7], v[6:7], v[198:199] op_sel_hi:[1,0]
	v_pk_mul_f32 v[4:5], v[4:5], v[198:199] op_sel_hi:[1,0]
	v_pk_mul_f32 v[2:3], v[2:3], v[198:199] op_sel_hi:[1,0]
	v_pk_mul_f32 v[0:1], v[0:1], v[198:199] op_sel_hi:[1,0]
	v_mul_f32_e32 v157, v157, v198
.LBB0_1894:
	v_add_u32_e32 v167, s27, v174
	v_add_u32_e32 v198, s27, v175
	v_sub_f32_e32 v48, v48, v151
	v_sub_f32_e32 v49, v49, v151
	v_sub_f32_e32 v50, v50, v151
	v_sub_f32_e32 v51, v51, v151
	v_sub_f32_e32 v52, v52, v151
	v_sub_f32_e32 v53, v53, v151
	v_sub_f32_e32 v54, v54, v151
	v_sub_f32_e32 v55, v55, v151
	v_add_u32_e32 v155, v167, v177
	v_exp_f32_e32 v48, v48
	v_exp_f32_e32 v49, v49
	v_exp_f32_e32 v50, v50
	v_exp_f32_e32 v51, v51
	v_exp_f32_e32 v52, v52
	v_exp_f32_e32 v53, v53
	v_exp_f32_e32 v54, v54
	v_exp_f32_e32 v55, v55
	v_add_u32_e32 v163, v198, v177
	ds_read_b64_tr_b16 v[204:205], v155 offset:24576
	ds_read_b64_tr_b16 v[206:207], v163 offset:26624
	v_add_u32_e32 v153, v167, v178
	v_add_u32_e32 v159, v198, v178
	ds_read_b64_tr_b16 v[208:209], v153 offset:24576
	ds_read_b64_tr_b16 v[210:211], v159 offset:26624
	ds_read_b64_tr_b16 v[214:215], v163 offset:30720
	ds_read_b64_tr_b16 v[212:213], v155 offset:28672
	v_cvt_pk_bf16_f32 v200, v48, v49
	v_cvt_pk_bf16_f32 v201, v50, v51
	v_cvt_pk_bf16_f32 v202, v52, v53
	v_cvt_pk_bf16_f32 v203, v54, v55
	v_add_u32_e32 v165, v167, v179
	v_add_u32_e32 v167, v167, v180
	s_waitcnt lgkmcnt(0)
	v_mfma_f32_32x32x16_bf16 v[64:79], v[204:207], v[200:203], v[64:79]
	v_add_u32_e32 v169, v198, v179
	ds_read_b64_tr_b16 v[204:205], v165 offset:24576
	ds_read_b64_tr_b16 v[206:207], v169 offset:26624
	ds_read_b64_tr_b16 v[218:219], v159 offset:30720
	ds_read_b64_tr_b16 v[216:217], v153 offset:28672
	v_add_u32_e32 v198, v198, v180
	v_add_f32_e32 v199, 0, v48
	v_sub_f32_e32 v56, v56, v151
	v_sub_f32_e32 v57, v57, v151
	v_sub_f32_e32 v58, v58, v151
	v_mfma_f32_32x32x16_bf16 v[32:47], v[208:211], v[200:203], v[32:47]
	ds_read_b64_tr_b16 v[208:209], v167 offset:24576
	ds_read_b64_tr_b16 v[210:211], v198 offset:26624
	ds_read_b64_tr_b16 v[226:227], v169 offset:30720
	ds_read_b64_tr_b16 v[224:225], v165 offset:28672
	v_sub_f32_e32 v59, v59, v151
	v_sub_f32_e32 v60, v60, v151
	v_sub_f32_e32 v61, v61, v151
	v_sub_f32_e32 v62, v62, v151
	v_sub_f32_e32 v63, v63, v151
	v_add_f32_e32 v199, v49, v199
	s_waitcnt lgkmcnt(0)
	v_mfma_f32_32x32x16_bf16 v[16:31], v[204:207], v[200:203], v[16:31]
	v_exp_f32_e32 v56, v56
	v_exp_f32_e32 v57, v57
	v_exp_f32_e32 v58, v58
	v_exp_f32_e32 v59, v59
	v_exp_f32_e32 v60, v60
	v_exp_f32_e32 v61, v61
	ds_read_b64_tr_b16 v[206:207], v198 offset:30720
	ds_read_b64_tr_b16 v[204:205], v167 offset:28672
	v_mfma_f32_32x32x16_bf16 v[0:15], v[208:211], v[200:203], v[0:15]
	v_exp_f32_e32 v62, v62
	v_exp_f32_e32 v63, v63
	v_add_f32_e32 v199, v50, v199
	v_add_f32_e32 v199, v51, v199
	v_add_f32_e32 v199, v52, v199
	v_add_f32_e32 v199, v53, v199
	v_cvt_pk_bf16_f32 v200, v56, v57
	v_cvt_pk_bf16_f32 v201, v58, v59
	v_cvt_pk_bf16_f32 v202, v60, v61
	v_cvt_pk_bf16_f32 v203, v62, v63
	v_add_f32_e32 v199, v54, v199
	v_add_f32_e32 v199, v55, v199
	v_mfma_f32_32x32x16_bf16 v[64:79], v[212:215], v[200:203], v[64:79]
	v_add_f32_e32 v199, v56, v199
	v_add_f32_e32 v199, v57, v199
	v_add_f32_e32 v199, v58, v199
	v_add_f32_e32 v199, v59, v199
	v_add_f32_e32 v199, v60, v199
	v_add_f32_e32 v199, v61, v199
	v_add_f32_e32 v199, v62, v199
	v_mfma_f32_32x32x16_bf16 v[32:47], v[216:219], v[200:203], v[32:47]
	v_add_f32_e32 v199, v63, v199
	v_add_f32_e32 v157, v157, v199
	v_mfma_f32_32x32x16_bf16 v[16:31], v[224:227], v[200:203], v[16:31]
	s_waitcnt lgkmcnt(0)
	v_mfma_f32_32x32x16_bf16 v[0:15], v[204:207], v[200:203], v[0:15]
	v_max_f32_e32 v200, v81, v81
	v_max_f32_e32 v201, v80, v80
	v_max_f32_e32 v200, v201, v200
	v_max3_f32 v200, v200, v82, v83
	v_max3_f32 v200, v200, v84, v85
	v_max3_f32 v200, v200, v86, v87
	v_max3_f32 v200, v200, v88, v89
	v_max3_f32 v200, v200, v90, v91
	v_max3_f32 v200, v200, v92, v93
	v_max3_f32 v200, v200, v94, v95
	v_mov_b32_e32 v199, v200
	s_nop 1
	v_permlane32_swap_b32_e32 v200, v199
	v_max_f32_e32 v199, v200, v199
	v_sub_f32_e32 v199, v199, v151
	v_cmp_lt_f32_e32 vcc, s25, v199
	s_cbranch_vccz .LBB0_1896
	v_max_f32_e32 v199, v199, v199
	v_max_f32_e32 v199, 0, v199
	v_exp_f32_e64 v200, -v199
	v_add_f32_e32 v151, v151, v199
	v_pk_mul_f32 v[78:79], v[78:79], v[200:201] op_sel_hi:[1,0]
	v_pk_mul_f32 v[76:77], v[76:77], v[200:201] op_sel_hi:[1,0]
	v_pk_mul_f32 v[74:75], v[74:75], v[200:201] op_sel_hi:[1,0]
	v_pk_mul_f32 v[72:73], v[72:73], v[200:201] op_sel_hi:[1,0]
	v_pk_mul_f32 v[70:71], v[70:71], v[200:201] op_sel_hi:[1,0]
	v_pk_mul_f32 v[68:69], v[68:69], v[200:201] op_sel_hi:[1,0]
	v_pk_mul_f32 v[66:67], v[66:67], v[200:201] op_sel_hi:[1,0]
	v_pk_mul_f32 v[64:65], v[64:65], v[200:201] op_sel_hi:[1,0]
	v_pk_mul_f32 v[46:47], v[46:47], v[200:201] op_sel_hi:[1,0]
	v_pk_mul_f32 v[44:45], v[44:45], v[200:201] op_sel_hi:[1,0]
	v_pk_mul_f32 v[42:43], v[42:43], v[200:201] op_sel_hi:[1,0]
	v_pk_mul_f32 v[40:41], v[40:41], v[200:201] op_sel_hi:[1,0]
	v_pk_mul_f32 v[38:39], v[38:39], v[200:201] op_sel_hi:[1,0]
	v_pk_mul_f32 v[36:37], v[36:37], v[200:201] op_sel_hi:[1,0]
	v_pk_mul_f32 v[34:35], v[34:35], v[200:201] op_sel_hi:[1,0]
	v_pk_mul_f32 v[32:33], v[32:33], v[200:201] op_sel_hi:[1,0]
	v_pk_mul_f32 v[30:31], v[30:31], v[200:201] op_sel_hi:[1,0]
	v_pk_mul_f32 v[28:29], v[28:29], v[200:201] op_sel_hi:[1,0]
	v_pk_mul_f32 v[26:27], v[26:27], v[200:201] op_sel_hi:[1,0]
	v_pk_mul_f32 v[24:25], v[24:25], v[200:201] op_sel_hi:[1,0]
	v_pk_mul_f32 v[22:23], v[22:23], v[200:201] op_sel_hi:[1,0]
	v_pk_mul_f32 v[20:21], v[20:21], v[200:201] op_sel_hi:[1,0]
	v_pk_mul_f32 v[18:19], v[18:19], v[200:201] op_sel_hi:[1,0]
	v_pk_mul_f32 v[16:17], v[16:17], v[200:201] op_sel_hi:[1,0]
	v_pk_mul_f32 v[14:15], v[14:15], v[200:201] op_sel_hi:[1,0]
	v_pk_mul_f32 v[12:13], v[12:13], v[200:201] op_sel_hi:[1,0]
	v_pk_mul_f32 v[10:11], v[10:11], v[200:201] op_sel_hi:[1,0]
	v_pk_mul_f32 v[8:9], v[8:9], v[200:201] op_sel_hi:[1,0]
	v_pk_mul_f32 v[6:7], v[6:7], v[200:201] op_sel_hi:[1,0]
	v_pk_mul_f32 v[4:5], v[4:5], v[200:201] op_sel_hi:[1,0]
	v_pk_mul_f32 v[2:3], v[2:3], v[200:201] op_sel_hi:[1,0]
	v_pk_mul_f32 v[0:1], v[0:1], v[200:201] op_sel_hi:[1,0]
	v_mul_f32_e32 v157, v157, v200

.LBB0_1926:
	s_setprio 1
	s_nop 7
	v_max_f32_e32 v153, v48, v49
	v_max3_f32 v153, v153, v50, v51
	v_max3_f32 v153, v153, v52, v53
	v_max3_f32 v153, v153, v54, v55
	v_max3_f32 v153, v153, v56, v57
	v_max3_f32 v153, v153, v58, v59
	v_max3_f32 v153, v153, v60, v61
	v_max3_f32 v153, v153, v62, v63
	v_mov_b32_e32 v155, v153
	s_nop 1
	v_permlane32_swap_b32_e32 v153, v155
	v_max_f32_e32 v153, v153, v155
	v_sub_f32_e32 v153, v153, v151
	v_cmp_lt_f32_e32 vcc, s26, v153
	s_cbranch_vccz .LBB0_1928
	v_max_f32_e32 v153, v153, v153
	v_max_f32_e32 v153, 0, v153
	v_exp_f32_e64 v198, -v153
	v_add_f32_e32 v151, v151, v153
	v_pk_mul_f32 v[78:79], v[78:79], v[198:199] op_sel_hi:[1,0]
	v_pk_mul_f32 v[76:77], v[76:77], v[198:199] op_sel_hi:[1,0]
	v_pk_mul_f32 v[74:75], v[74:75], v[198:199] op_sel_hi:[1,0]
	v_pk_mul_f32 v[72:73], v[72:73], v[198:199] op_sel_hi:[1,0]
	v_pk_mul_f32 v[70:71], v[70:71], v[198:199] op_sel_hi:[1,0]
	v_pk_mul_f32 v[68:69], v[68:69], v[198:199] op_sel_hi:[1,0]
	v_pk_mul_f32 v[66:67], v[66:67], v[198:199] op_sel_hi:[1,0]
	v_pk_mul_f32 v[64:65], v[64:65], v[198:199] op_sel_hi:[1,0]
	v_pk_mul_f32 v[46:47], v[46:47], v[198:199] op_sel_hi:[1,0]
	v_pk_mul_f32 v[44:45], v[44:45], v[198:199] op_sel_hi:[1,0]
	v_pk_mul_f32 v[42:43], v[42:43], v[198:199] op_sel_hi:[1,0]
	v_pk_mul_f32 v[40:41], v[40:41], v[198:199] op_sel_hi:[1,0]
	v_pk_mul_f32 v[38:39], v[38:39], v[198:199] op_sel_hi:[1,0]
	v_pk_mul_f32 v[36:37], v[36:37], v[198:199] op_sel_hi:[1,0]
	v_pk_mul_f32 v[34:35], v[34:35], v[198:199] op_sel_hi:[1,0]
	v_pk_mul_f32 v[32:33], v[32:33], v[198:199] op_sel_hi:[1,0]
	v_pk_mul_f32 v[30:31], v[30:31], v[198:199] op_sel_hi:[1,0]
	v_pk_mul_f32 v[28:29], v[28:29], v[198:199] op_sel_hi:[1,0]
	v_pk_mul_f32 v[26:27], v[26:27], v[198:199] op_sel_hi:[1,0]
	v_pk_mul_f32 v[24:25], v[24:25], v[198:199] op_sel_hi:[1,0]
	v_pk_mul_f32 v[22:23], v[22:23], v[198:199] op_sel_hi:[1,0]
	v_pk_mul_f32 v[20:21], v[20:21], v[198:199] op_sel_hi:[1,0]
	v_pk_mul_f32 v[18:19], v[18:19], v[198:199] op_sel_hi:[1,0]
	v_pk_mul_f32 v[16:17], v[16:17], v[198:199] op_sel_hi:[1,0]
	v_pk_mul_f32 v[14:15], v[14:15], v[198:199] op_sel_hi:[1,0]
	v_pk_mul_f32 v[12:13], v[12:13], v[198:199] op_sel_hi:[1,0]
	v_pk_mul_f32 v[10:11], v[10:11], v[198:199] op_sel_hi:[1,0]
	v_pk_mul_f32 v[8:9], v[8:9], v[198:199] op_sel_hi:[1,0]
	v_pk_mul_f32 v[6:7], v[6:7], v[198:199] op_sel_hi:[1,0]
	v_pk_mul_f32 v[4:5], v[4:5], v[198:199] op_sel_hi:[1,0]
	v_pk_mul_f32 v[2:3], v[2:3], v[198:199] op_sel_hi:[1,0]
	v_pk_mul_f32 v[0:1], v[0:1], v[198:199] op_sel_hi:[1,0]
	v_mul_f32_e32 v157, v157, v198
.LBB0_1928:
	v_add_u32_e32 v167, s27, v174
	v_add_u32_e32 v198, s27, v175
	v_sub_f32_e32 v48, v48, v151
	v_sub_f32_e32 v49, v49, v151
	v_sub_f32_e32 v50, v50, v151
	v_sub_f32_e32 v51, v51, v151
	v_sub_f32_e32 v52, v52, v151
	v_sub_f32_e32 v53, v53, v151
	v_sub_f32_e32 v54, v54, v151
	v_sub_f32_e32 v55, v55, v151
	v_add_u32_e32 v155, v167, v177
	v_exp_f32_e32 v48, v48
	v_exp_f32_e32 v49, v49
	v_exp_f32_e32 v50, v50
	v_exp_f32_e32 v51, v51
	v_exp_f32_e32 v52, v52
	v_exp_f32_e32 v53, v53
	v_exp_f32_e32 v54, v54
	v_exp_f32_e32 v55, v55
	v_add_u32_e32 v163, v198, v177
	ds_read_b64_tr_b16 v[204:205], v155 offset:24576
	ds_read_b64_tr_b16 v[206:207], v163 offset:26624
	v_add_u32_e32 v153, v167, v178
	v_add_u32_e32 v159, v198, v178
	ds_read_b64_tr_b16 v[208:209], v153 offset:24576
	ds_read_b64_tr_b16 v[210:211], v159 offset:26624
	ds_read_b64_tr_b16 v[214:215], v163 offset:30720
	ds_read_b64_tr_b16 v[212:213], v155 offset:28672
	v_cvt_pk_bf16_f32 v200, v48, v49
	v_cvt_pk_bf16_f32 v201, v50, v51
	v_cvt_pk_bf16_f32 v202, v52, v53
	v_cvt_pk_bf16_f32 v203, v54, v55
	v_add_u32_e32 v165, v167, v179
	v_add_u32_e32 v167, v167, v180
	s_waitcnt lgkmcnt(0)
	v_mfma_f32_32x32x16_bf16 v[64:79], v[204:207], v[200:203], v[64:79]
	v_add_u32_e32 v169, v198, v179
	ds_read_b64_tr_b16 v[204:205], v165 offset:24576
	ds_read_b64_tr_b16 v[206:207], v169 offset:26624
	ds_read_b64_tr_b16 v[218:219], v159 offset:30720
	ds_read_b64_tr_b16 v[216:217], v153 offset:28672
	v_add_u32_e32 v198, v198, v180
	v_add_f32_e32 v199, 0, v48
	v_sub_f32_e32 v56, v56, v151
	v_sub_f32_e32 v57, v57, v151
	v_sub_f32_e32 v58, v58, v151
	v_mfma_f32_32x32x16_bf16 v[32:47], v[208:211], v[200:203], v[32:47]
	ds_read_b64_tr_b16 v[208:209], v167 offset:24576
	ds_read_b64_tr_b16 v[210:211], v198 offset:26624
	ds_read_b64_tr_b16 v[226:227], v169 offset:30720
	ds_read_b64_tr_b16 v[224:225], v165 offset:28672
	v_sub_f32_e32 v59, v59, v151
	v_sub_f32_e32 v60, v60, v151
	v_sub_f32_e32 v61, v61, v151
	v_sub_f32_e32 v62, v62, v151
	v_sub_f32_e32 v63, v63, v151
	v_add_f32_e32 v199, v49, v199
	s_waitcnt lgkmcnt(0)
	v_mfma_f32_32x32x16_bf16 v[16:31], v[204:207], v[200:203], v[16:31]
	v_exp_f32_e32 v56, v56
	v_exp_f32_e32 v57, v57
	v_exp_f32_e32 v58, v58
	v_exp_f32_e32 v59, v59
	v_exp_f32_e32 v60, v60
	v_exp_f32_e32 v61, v61
	ds_read_b64_tr_b16 v[206:207], v198 offset:30720
	ds_read_b64_tr_b16 v[204:205], v167 offset:28672
	v_mfma_f32_32x32x16_bf16 v[0:15], v[208:211], v[200:203], v[0:15]
	v_exp_f32_e32 v62, v62
	v_exp_f32_e32 v63, v63
	v_add_f32_e32 v199, v50, v199
	v_add_f32_e32 v199, v51, v199
	v_add_f32_e32 v199, v52, v199
	v_add_f32_e32 v199, v53, v199
	v_cvt_pk_bf16_f32 v200, v56, v57
	v_cvt_pk_bf16_f32 v201, v58, v59
	v_cvt_pk_bf16_f32 v202, v60, v61
	v_cvt_pk_bf16_f32 v203, v62, v63
	v_add_f32_e32 v199, v54, v199
	v_add_f32_e32 v199, v55, v199
	v_mfma_f32_32x32x16_bf16 v[64:79], v[212:215], v[200:203], v[64:79]
	v_add_f32_e32 v199, v56, v199
	v_add_f32_e32 v199, v57, v199
	v_add_f32_e32 v199, v58, v199
	v_add_f32_e32 v199, v59, v199
	v_add_f32_e32 v199, v60, v199
	v_add_f32_e32 v199, v61, v199
	v_add_f32_e32 v199, v62, v199
	v_mfma_f32_32x32x16_bf16 v[32:47], v[216:219], v[200:203], v[32:47]
	v_add_f32_e32 v199, v63, v199
	v_add_f32_e32 v157, v157, v199
	v_mfma_f32_32x32x16_bf16 v[16:31], v[224:227], v[200:203], v[16:31]
	s_waitcnt lgkmcnt(0)
	v_mfma_f32_32x32x16_bf16 v[0:15], v[204:207], v[200:203], v[0:15]
	v_max_f32_e32 v200, v81, v81
	v_max_f32_e32 v201, v80, v80
	v_max_f32_e32 v200, v201, v200
	v_max3_f32 v200, v200, v82, v83
	v_max3_f32 v200, v200, v84, v85
	v_max3_f32 v200, v200, v86, v87
	v_max3_f32 v200, v200, v88, v89
	v_max3_f32 v200, v200, v90, v91
	v_max3_f32 v200, v200, v92, v93
	v_max3_f32 v200, v200, v94, v95
	v_mov_b32_e32 v199, v200
	s_nop 1
	v_permlane32_swap_b32_e32 v200, v199
	v_max_f32_e32 v199, v200, v199
	v_sub_f32_e32 v199, v199, v151
	v_cmp_lt_f32_e32 vcc, s26, v199
	s_cbranch_vccz .LBB0_1930
	v_max_f32_e32 v199, v199, v199
	v_max_f32_e32 v199, 0, v199
	v_exp_f32_e64 v200, -v199
	v_add_f32_e32 v151, v151, v199
	v_pk_mul_f32 v[78:79], v[78:79], v[200:201] op_sel_hi:[1,0]
	v_pk_mul_f32 v[76:77], v[76:77], v[200:201] op_sel_hi:[1,0]
	v_pk_mul_f32 v[74:75], v[74:75], v[200:201] op_sel_hi:[1,0]
	v_pk_mul_f32 v[72:73], v[72:73], v[200:201] op_sel_hi:[1,0]
	v_pk_mul_f32 v[70:71], v[70:71], v[200:201] op_sel_hi:[1,0]
	v_pk_mul_f32 v[68:69], v[68:69], v[200:201] op_sel_hi:[1,0]
	v_pk_mul_f32 v[66:67], v[66:67], v[200:201] op_sel_hi:[1,0]
	v_pk_mul_f32 v[64:65], v[64:65], v[200:201] op_sel_hi:[1,0]
	v_pk_mul_f32 v[46:47], v[46:47], v[200:201] op_sel_hi:[1,0]
	v_pk_mul_f32 v[44:45], v[44:45], v[200:201] op_sel_hi:[1,0]
	v_pk_mul_f32 v[42:43], v[42:43], v[200:201] op_sel_hi:[1,0]
	v_pk_mul_f32 v[40:41], v[40:41], v[200:201] op_sel_hi:[1,0]
	v_pk_mul_f32 v[38:39], v[38:39], v[200:201] op_sel_hi:[1,0]
	v_pk_mul_f32 v[36:37], v[36:37], v[200:201] op_sel_hi:[1,0]
	v_pk_mul_f32 v[34:35], v[34:35], v[200:201] op_sel_hi:[1,0]
	v_pk_mul_f32 v[32:33], v[32:33], v[200:201] op_sel_hi:[1,0]
	v_pk_mul_f32 v[30:31], v[30:31], v[200:201] op_sel_hi:[1,0]
	v_pk_mul_f32 v[28:29], v[28:29], v[200:201] op_sel_hi:[1,0]
	v_pk_mul_f32 v[26:27], v[26:27], v[200:201] op_sel_hi:[1,0]
	v_pk_mul_f32 v[24:25], v[24:25], v[200:201] op_sel_hi:[1,0]
	v_pk_mul_f32 v[22:23], v[22:23], v[200:201] op_sel_hi:[1,0]
	v_pk_mul_f32 v[20:21], v[20:21], v[200:201] op_sel_hi:[1,0]
	v_pk_mul_f32 v[18:19], v[18:19], v[200:201] op_sel_hi:[1,0]
	v_pk_mul_f32 v[16:17], v[16:17], v[200:201] op_sel_hi:[1,0]
	v_pk_mul_f32 v[14:15], v[14:15], v[200:201] op_sel_hi:[1,0]
	v_pk_mul_f32 v[12:13], v[12:13], v[200:201] op_sel_hi:[1,0]
	v_pk_mul_f32 v[10:11], v[10:11], v[200:201] op_sel_hi:[1,0]
	v_pk_mul_f32 v[8:9], v[8:9], v[200:201] op_sel_hi:[1,0]
	v_pk_mul_f32 v[6:7], v[6:7], v[200:201] op_sel_hi:[1,0]
	v_pk_mul_f32 v[4:5], v[4:5], v[200:201] op_sel_hi:[1,0]
	v_pk_mul_f32 v[2:3], v[2:3], v[200:201] op_sel_hi:[1,0]
	v_pk_mul_f32 v[0:1], v[0:1], v[200:201] op_sel_hi:[1,0]
	v_mul_f32_e32 v157, v157, v200

.LBB0_2047:
	s_nop 10
	v_max_f32_e32 v0, v48, v49
	v_max3_f32 v0, v0, v50, v51
	v_max3_f32 v0, v0, v52, v53
	v_max3_f32 v0, v0, v54, v55
	v_max3_f32 v0, v0, v56, v57
	v_max3_f32 v0, v0, v58, v59
	v_max3_f32 v0, v0, v60, v61
	v_max3_f32 v0, v0, v62, v63
	v_mov_b32_e32 v1, v0
	s_nop 1
	v_permlane32_swap_b32_e32 v0, v1
	v_max_f32_e32 v0, v0, v1
	s_cmp_lg_u64 exec, 0
	v_add_f32_e32 v0, 0, v0
	s_cselect_b64 vcc, -1, 0
	v_cndmask_b32_e32 v151, 0, v0, vcc
	v_sub_f32_e32 v0, v48, v151
	v_exp_f32_e32 v48, v0
	v_sub_f32_e32 v0, v49, v151
	v_exp_f32_e32 v49, v0
	v_sub_f32_e32 v0, v50, v151
	v_exp_f32_e32 v50, v0
	v_sub_f32_e32 v0, v51, v151
	v_exp_f32_e32 v51, v0
	v_sub_f32_e32 v0, v52, v151
	v_exp_f32_e32 v52, v0
	v_sub_f32_e32 v0, v53, v151
	v_exp_f32_e32 v53, v0
	v_sub_f32_e32 v0, v54, v151
	v_exp_f32_e32 v54, v0
	v_sub_f32_e32 v0, v55, v151
	v_exp_f32_e32 v55, v0
	v_sub_f32_e32 v0, v56, v151
	v_exp_f32_e32 v56, v0
	ds_read_b64_tr_b16 v[0:1], v183 offset:24576
	ds_read_b64_tr_b16 v[2:3], v185 offset:26624
	v_cvt_pk_bf16_f32 v4, v48, v49
	v_cvt_pk_bf16_f32 v5, v50, v51
	v_cvt_pk_bf16_f32 v6, v52, v53
	v_cvt_pk_bf16_f32 v7, v54, v55
	ds_read_b64_tr_b16 v[8:9], v182 offset:24576
	ds_read_b64_tr_b16 v[10:11], v184 offset:26624
	ds_read_b64_tr_b16 v[192:193], v185 offset:30720
	ds_read_b64_tr_b16 v[190:191], v183 offset:28672
	s_waitcnt lgkmcnt(0)
	v_mfma_f32_32x32x16_bf16 v[64:79], v[0:3], v[4:7], 0
	v_sub_f32_e32 v0, v57, v151
	v_exp_f32_e32 v57, v0
	ds_read_b64_tr_b16 v[0:1], v186 offset:24576
	ds_read_b64_tr_b16 v[2:3], v188 offset:26624
	ds_read_b64_tr_b16 v[200:201], v184 offset:30720
	ds_read_b64_tr_b16 v[198:199], v182 offset:28672
	v_sub_f32_e32 v12, v58, v151
	v_sub_f32_e32 v62, v62, v151
	v_sub_f32_e32 v63, v63, v151
	v_exp_f32_e32 v58, v12
	s_waitcnt lgkmcnt(0)
	v_mfma_f32_32x32x16_bf16 v[16:31], v[0:3], v[4:7], 0
	v_sub_f32_e32 v0, v60, v151
	v_exp_f32_e32 v60, v0
	v_sub_f32_e32 v0, v61, v151
	v_exp_f32_e32 v61, v0
	v_exp_f32_e32 v62, v62
	v_exp_f32_e32 v63, v63
	v_add_f32_e32 v156, 0, v48
	v_mfma_f32_32x32x16_bf16 v[32:47], v[8:11], v[4:7], 0
	v_sub_f32_e32 v8, v59, v151
	v_exp_f32_e32 v59, v8
	ds_read_b64_tr_b16 v[8:9], v187 offset:24576
	ds_read_b64_tr_b16 v[10:11], v189 offset:26624
	ds_read_b64_tr_b16 v[204:205], v188 offset:30720
	ds_read_b64_tr_b16 v[202:203], v186 offset:28672
	v_cvt_pk_bf16_f32 v210, v56, v57
	v_cvt_pk_bf16_f32 v212, v60, v61
	v_cvt_pk_bf16_f32 v211, v58, v59
	v_cvt_pk_bf16_f32 v213, v62, v63
	s_waitcnt lgkmcnt(0)
	v_mfma_f32_32x32x16_bf16 v[0:15], v[8:11], v[4:7], 0
	v_add_f32_e32 v156, v49, v156
	v_add_f32_e32 v156, v50, v156
	v_max_f32_e32 v157, v81, v81
	v_add_f32_e32 v156, v51, v156
	ds_read_b64_tr_b16 v[208:209], v189 offset:30720
	ds_read_b64_tr_b16 v[206:207], v187 offset:28672
	v_add_f32_e32 v156, v52, v156
	v_add_f32_e32 v156, v53, v156
	v_mfma_f32_32x32x16_bf16 v[64:79], v[190:193], v[210:213], v[64:79]
	v_max_f32_e32 v190, v80, v80
	v_max_f32_e32 v157, v190, v157
	v_max3_f32 v157, v157, v82, v83
	v_max3_f32 v157, v157, v84, v85
	v_add_f32_e32 v156, v54, v156
	v_max3_f32 v157, v157, v86, v87
	v_add_f32_e32 v156, v55, v156
	v_max3_f32 v157, v157, v88, v89
	v_add_f32_e32 v156, v56, v156
	v_max3_f32 v157, v157, v90, v91
	v_mfma_f32_32x32x16_bf16 v[32:47], v[198:201], v[210:213], v[32:47]
	v_add_f32_e32 v156, v57, v156
	v_max3_f32 v157, v157, v92, v93
	v_add_f32_e32 v156, v58, v156
	v_max3_f32 v157, v157, v94, v95
	v_add_f32_e32 v156, v59, v156
	v_mov_b32_e32 v190, v157
	v_add_f32_e32 v156, v60, v156
	v_mfma_f32_32x32x16_bf16 v[16:31], v[202:205], v[210:213], v[16:31]
	v_permlane32_swap_b32_e32 v157, v190
	v_add_f32_e32 v156, v61, v156
	v_max_f32_e32 v190, v190, v190
	v_max_f32_e32 v157, v157, v157
	v_add_f32_e32 v156, v62, v156
	v_max_f32_e32 v157, v157, v190
	s_waitcnt lgkmcnt(0)
	v_mfma_f32_32x32x16_bf16 v[0:15], v[206:209], v[210:213], v[0:15]
	v_add_f32_e32 v156, v63, v156
	v_sub_f32_e32 v157, v157, v151
	s_mov_b32 s2, 0x41000000
	v_add_f32_e32 v156, 0, v156
	v_cmp_lt_f32_e32 vcc, s2, v157
	s_cbranch_vccz .LBB0_2049
	v_max_f32_e32 v157, v157, v157
	v_max_f32_e32 v157, 0, v157
	v_exp_f32_e64 v190, -v157
	v_add_f32_e32 v151, v151, v157
	v_pk_mul_f32 v[78:79], v[78:79], v[190:191] op_sel_hi:[1,0]
	v_pk_mul_f32 v[76:77], v[76:77], v[190:191] op_sel_hi:[1,0]
	v_pk_mul_f32 v[74:75], v[74:75], v[190:191] op_sel_hi:[1,0]
	v_pk_mul_f32 v[72:73], v[72:73], v[190:191] op_sel_hi:[1,0]
	v_pk_mul_f32 v[70:71], v[70:71], v[190:191] op_sel_hi:[1,0]
	v_pk_mul_f32 v[68:69], v[68:69], v[190:191] op_sel_hi:[1,0]
	v_pk_mul_f32 v[66:67], v[66:67], v[190:191] op_sel_hi:[1,0]
	v_pk_mul_f32 v[64:65], v[64:65], v[190:191] op_sel_hi:[1,0]
	v_pk_mul_f32 v[46:47], v[46:47], v[190:191] op_sel_hi:[1,0]
	v_pk_mul_f32 v[44:45], v[44:45], v[190:191] op_sel_hi:[1,0]
	v_pk_mul_f32 v[42:43], v[42:43], v[190:191] op_sel_hi:[1,0]
	v_pk_mul_f32 v[40:41], v[40:41], v[190:191] op_sel_hi:[1,0]
	v_pk_mul_f32 v[38:39], v[38:39], v[190:191] op_sel_hi:[1,0]
	v_pk_mul_f32 v[36:37], v[36:37], v[190:191] op_sel_hi:[1,0]
	v_pk_mul_f32 v[34:35], v[34:35], v[190:191] op_sel_hi:[1,0]
	v_pk_mul_f32 v[32:33], v[32:33], v[190:191] op_sel_hi:[1,0]
	v_pk_mul_f32 v[30:31], v[30:31], v[190:191] op_sel_hi:[1,0]
	v_pk_mul_f32 v[28:29], v[28:29], v[190:191] op_sel_hi:[1,0]
	v_pk_mul_f32 v[26:27], v[26:27], v[190:191] op_sel_hi:[1,0]
	v_pk_mul_f32 v[24:25], v[24:25], v[190:191] op_sel_hi:[1,0]
	v_pk_mul_f32 v[22:23], v[22:23], v[190:191] op_sel_hi:[1,0]
	v_pk_mul_f32 v[20:21], v[20:21], v[190:191] op_sel_hi:[1,0]
	v_pk_mul_f32 v[18:19], v[18:19], v[190:191] op_sel_hi:[1,0]
	v_pk_mul_f32 v[16:17], v[16:17], v[190:191] op_sel_hi:[1,0]
	v_pk_mul_f32 v[14:15], v[14:15], v[190:191] op_sel_hi:[1,0]
	v_pk_mul_f32 v[12:13], v[12:13], v[190:191] op_sel_hi:[1,0]
	v_pk_mul_f32 v[10:11], v[10:11], v[190:191] op_sel_hi:[1,0]
	v_pk_mul_f32 v[8:9], v[8:9], v[190:191] op_sel_hi:[1,0]
	v_pk_mul_f32 v[6:7], v[6:7], v[190:191] op_sel_hi:[1,0]
	v_pk_mul_f32 v[4:5], v[4:5], v[190:191] op_sel_hi:[1,0]
	v_pk_mul_f32 v[2:3], v[2:3], v[190:191] op_sel_hi:[1,0]
	v_pk_mul_f32 v[0:1], v[0:1], v[190:191] op_sel_hi:[1,0]
	v_mul_f32_e32 v156, v156, v190

.LBB0_2062:
	s_setprio 1
	s_nop 7
	v_max_f32_e32 v153, v48, v49
	v_max3_f32 v153, v153, v50, v51
	v_max3_f32 v153, v153, v52, v53
	v_max3_f32 v153, v153, v54, v55
	v_max3_f32 v153, v153, v56, v57
	v_max3_f32 v153, v153, v58, v59
	v_max3_f32 v153, v153, v60, v61
	v_max3_f32 v153, v153, v62, v63
	v_mov_b32_e32 v155, v153
	s_nop 1
	v_permlane32_swap_b32_e32 v153, v155
	v_max_f32_e32 v153, v153, v155
	v_sub_f32_e32 v153, v153, v151
	v_cmp_lt_f32_e32 vcc, s20, v153
	s_cbranch_vccz .LBB0_2064
	v_max_f32_e32 v153, v153, v153
	v_max_f32_e32 v153, 0, v153
	v_exp_f32_e64 v168, -v153
	v_add_f32_e32 v151, v151, v153
	v_pk_mul_f32 v[78:79], v[78:79], v[168:169] op_sel_hi:[1,0]
	v_pk_mul_f32 v[76:77], v[76:77], v[168:169] op_sel_hi:[1,0]
	v_pk_mul_f32 v[74:75], v[74:75], v[168:169] op_sel_hi:[1,0]
	v_pk_mul_f32 v[72:73], v[72:73], v[168:169] op_sel_hi:[1,0]
	v_pk_mul_f32 v[70:71], v[70:71], v[168:169] op_sel_hi:[1,0]
	v_pk_mul_f32 v[68:69], v[68:69], v[168:169] op_sel_hi:[1,0]
	v_pk_mul_f32 v[66:67], v[66:67], v[168:169] op_sel_hi:[1,0]
	v_pk_mul_f32 v[64:65], v[64:65], v[168:169] op_sel_hi:[1,0]
	v_pk_mul_f32 v[46:47], v[46:47], v[168:169] op_sel_hi:[1,0]
	v_pk_mul_f32 v[44:45], v[44:45], v[168:169] op_sel_hi:[1,0]
	v_pk_mul_f32 v[42:43], v[42:43], v[168:169] op_sel_hi:[1,0]
	v_pk_mul_f32 v[40:41], v[40:41], v[168:169] op_sel_hi:[1,0]
	v_pk_mul_f32 v[38:39], v[38:39], v[168:169] op_sel_hi:[1,0]
	v_pk_mul_f32 v[36:37], v[36:37], v[168:169] op_sel_hi:[1,0]
	v_pk_mul_f32 v[34:35], v[34:35], v[168:169] op_sel_hi:[1,0]
	v_pk_mul_f32 v[32:33], v[32:33], v[168:169] op_sel_hi:[1,0]
	v_pk_mul_f32 v[30:31], v[30:31], v[168:169] op_sel_hi:[1,0]
	v_pk_mul_f32 v[28:29], v[28:29], v[168:169] op_sel_hi:[1,0]
	v_pk_mul_f32 v[26:27], v[26:27], v[168:169] op_sel_hi:[1,0]
	v_pk_mul_f32 v[24:25], v[24:25], v[168:169] op_sel_hi:[1,0]
	v_pk_mul_f32 v[22:23], v[22:23], v[168:169] op_sel_hi:[1,0]
	v_pk_mul_f32 v[20:21], v[20:21], v[168:169] op_sel_hi:[1,0]
	v_pk_mul_f32 v[18:19], v[18:19], v[168:169] op_sel_hi:[1,0]
	v_pk_mul_f32 v[16:17], v[16:17], v[168:169] op_sel_hi:[1,0]
	v_pk_mul_f32 v[14:15], v[14:15], v[168:169] op_sel_hi:[1,0]
	v_pk_mul_f32 v[12:13], v[12:13], v[168:169] op_sel_hi:[1,0]
	v_pk_mul_f32 v[10:11], v[10:11], v[168:169] op_sel_hi:[1,0]
	v_pk_mul_f32 v[8:9], v[8:9], v[168:169] op_sel_hi:[1,0]
	v_pk_mul_f32 v[6:7], v[6:7], v[168:169] op_sel_hi:[1,0]
	v_pk_mul_f32 v[4:5], v[4:5], v[168:169] op_sel_hi:[1,0]
	v_pk_mul_f32 v[2:3], v[2:3], v[168:169] op_sel_hi:[1,0]
	v_pk_mul_f32 v[0:1], v[0:1], v[168:169] op_sel_hi:[1,0]
	v_mul_f32_e32 v159, v159, v168
.LBB0_2064:
	v_add_u32_e32 v167, s21, v174
	v_add_u32_e32 v169, s21, v175
	v_sub_f32_e32 v48, v48, v151
	v_sub_f32_e32 v49, v49, v151
	v_sub_f32_e32 v50, v50, v151
	v_sub_f32_e32 v51, v51, v151
	v_sub_f32_e32 v52, v52, v151
	v_sub_f32_e32 v53, v53, v151
	v_sub_f32_e32 v54, v54, v151
	v_sub_f32_e32 v55, v55, v151
	v_add_u32_e32 v155, v167, v177
	v_exp_f32_e32 v48, v48
	v_exp_f32_e32 v49, v49
	v_exp_f32_e32 v50, v50
	v_exp_f32_e32 v51, v51
	v_exp_f32_e32 v52, v52
	v_exp_f32_e32 v53, v53
	v_exp_f32_e32 v54, v54
	v_exp_f32_e32 v55, v55
	v_add_u32_e32 v163, v169, v177
	ds_read_b64_tr_b16 v[186:187], v155 offset:24576
	ds_read_b64_tr_b16 v[188:189], v163 offset:26624
	v_add_u32_e32 v153, v167, v178
	v_add_u32_e32 v161, v169, v178
	ds_read_b64_tr_b16 v[190:191], v153 offset:24576
	ds_read_b64_tr_b16 v[192:193], v161 offset:26624
	ds_read_b64_tr_b16 v[200:201], v163 offset:30720
	ds_read_b64_tr_b16 v[198:199], v155 offset:28672
	v_cvt_pk_bf16_f32 v182, v48, v49
	v_cvt_pk_bf16_f32 v183, v50, v51
	v_cvt_pk_bf16_f32 v184, v52, v53
	v_cvt_pk_bf16_f32 v185, v54, v55
	v_add_u32_e32 v165, v167, v179
	v_add_u32_e32 v167, v167, v180
	s_waitcnt lgkmcnt(0)
	v_mfma_f32_32x32x16_bf16 v[64:79], v[186:189], v[182:185], v[64:79]
	v_add_u32_e32 v168, v169, v179
	ds_read_b64_tr_b16 v[186:187], v165 offset:24576
	ds_read_b64_tr_b16 v[188:189], v168 offset:26624
	ds_read_b64_tr_b16 v[204:205], v161 offset:30720
	ds_read_b64_tr_b16 v[202:203], v153 offset:28672
	v_add_u32_e32 v169, v169, v180
	v_sub_f32_e32 v56, v56, v151
	v_sub_f32_e32 v57, v57, v151
	v_sub_f32_e32 v58, v58, v151
	v_sub_f32_e32 v59, v59, v151
	v_mfma_f32_32x32x16_bf16 v[32:47], v[190:193], v[182:185], v[32:47]
	ds_read_b64_tr_b16 v[190:191], v167 offset:24576
	ds_read_b64_tr_b16 v[192:193], v169 offset:26624
	ds_read_b64_tr_b16 v[208:209], v168 offset:30720
	ds_read_b64_tr_b16 v[206:207], v165 offset:28672
	v_sub_f32_e32 v60, v60, v151
	v_sub_f32_e32 v61, v61, v151
	v_sub_f32_e32 v62, v62, v151
	v_sub_f32_e32 v63, v63, v151
	v_exp_f32_e32 v56, v56
	v_exp_f32_e32 v57, v57
	s_waitcnt lgkmcnt(0)
	v_mfma_f32_32x32x16_bf16 v[16:31], v[186:189], v[182:185], v[16:31]
	v_exp_f32_e32 v58, v58
	v_exp_f32_e32 v59, v59
	v_exp_f32_e32 v60, v60
	v_exp_f32_e32 v61, v61
	ds_read_b64_tr_b16 v[188:189], v169 offset:30720
	ds_read_b64_tr_b16 v[186:187], v167 offset:28672
	v_exp_f32_e32 v62, v62
	v_exp_f32_e32 v63, v63
	v_mfma_f32_32x32x16_bf16 v[0:15], v[190:193], v[182:185], v[0:15]
	v_add_f32_e32 v190, 0, v48
	v_cvt_pk_bf16_f32 v182, v56, v57
	v_cvt_pk_bf16_f32 v183, v58, v59
	v_cvt_pk_bf16_f32 v184, v60, v61
	v_cvt_pk_bf16_f32 v185, v62, v63
	v_add_f32_e32 v190, v49, v190
	v_add_f32_e32 v190, v50, v190
	v_mfma_f32_32x32x16_bf16 v[64:79], v[198:201], v[182:185], v[64:79]
	v_add_f32_e32 v190, v51, v190
	v_add_f32_e32 v190, v52, v190
	v_add_f32_e32 v190, v53, v190
	v_add_f32_e32 v190, v54, v190
	v_add_f32_e32 v190, v55, v190
	v_add_f32_e32 v190, v56, v190
	v_add_f32_e32 v190, v57, v190
	v_mfma_f32_32x32x16_bf16 v[32:47], v[202:205], v[182:185], v[32:47]
	v_add_f32_e32 v190, v58, v190
	v_add_f32_e32 v190, v59, v190
	v_add_f32_e32 v190, v60, v190
	v_add_f32_e32 v190, v61, v190
	v_add_f32_e32 v190, v62, v190
	v_add_f32_e32 v190, v63, v190
	v_add_f32_e32 v159, v159, v190
	v_mfma_f32_32x32x16_bf16 v[16:31], v[206:209], v[182:185], v[16:31]
	s_waitcnt lgkmcnt(0)
	v_mfma_f32_32x32x16_bf16 v[0:15], v[186:189], v[182:185], v[0:15]
	v_max_f32_e32 v182, v80, v81
	v_max3_f32 v182, v182, v82, v83
	v_max3_f32 v182, v182, v84, v85
	v_max3_f32 v182, v182, v86, v87
	v_max3_f32 v182, v182, v88, v89
	v_max3_f32 v182, v182, v90, v91
	v_max3_f32 v182, v182, v92, v93
	v_max3_f32 v182, v182, v94, v95
	v_mov_b32_e32 v183, v182
	s_nop 1
	v_permlane32_swap_b32_e32 v182, v183
	v_max_f32_e32 v182, v182, v183
	v_sub_f32_e32 v182, v182, v151
	v_cmp_lt_f32_e32 vcc, s20, v182
	s_cbranch_vccz .LBB0_2066
	v_max_f32_e32 v182, v182, v182
	v_max_f32_e32 v183, 0, v182
	v_exp_f32_e64 v182, -v183
	v_add_f32_e32 v151, v151, v183
	v_pk_mul_f32 v[78:79], v[78:79], v[182:183] op_sel_hi:[1,0]
	v_pk_mul_f32 v[76:77], v[76:77], v[182:183] op_sel_hi:[1,0]
	v_pk_mul_f32 v[74:75], v[74:75], v[182:183] op_sel_hi:[1,0]
	v_pk_mul_f32 v[72:73], v[72:73], v[182:183] op_sel_hi:[1,0]
	v_pk_mul_f32 v[70:71], v[70:71], v[182:183] op_sel_hi:[1,0]
	v_pk_mul_f32 v[68:69], v[68:69], v[182:183] op_sel_hi:[1,0]
	v_pk_mul_f32 v[66:67], v[66:67], v[182:183] op_sel_hi:[1,0]
	v_pk_mul_f32 v[64:65], v[64:65], v[182:183] op_sel_hi:[1,0]
	v_pk_mul_f32 v[46:47], v[46:47], v[182:183] op_sel_hi:[1,0]
	v_pk_mul_f32 v[44:45], v[44:45], v[182:183] op_sel_hi:[1,0]
	v_pk_mul_f32 v[42:43], v[42:43], v[182:183] op_sel_hi:[1,0]
	v_pk_mul_f32 v[40:41], v[40:41], v[182:183] op_sel_hi:[1,0]
	v_pk_mul_f32 v[38:39], v[38:39], v[182:183] op_sel_hi:[1,0]
	v_pk_mul_f32 v[36:37], v[36:37], v[182:183] op_sel_hi:[1,0]
	v_pk_mul_f32 v[34:35], v[34:35], v[182:183] op_sel_hi:[1,0]
	v_pk_mul_f32 v[32:33], v[32:33], v[182:183] op_sel_hi:[1,0]
	v_pk_mul_f32 v[30:31], v[30:31], v[182:183] op_sel_hi:[1,0]
	v_pk_mul_f32 v[28:29], v[28:29], v[182:183] op_sel_hi:[1,0]
	v_pk_mul_f32 v[26:27], v[26:27], v[182:183] op_sel_hi:[1,0]
	v_pk_mul_f32 v[24:25], v[24:25], v[182:183] op_sel_hi:[1,0]
	v_pk_mul_f32 v[22:23], v[22:23], v[182:183] op_sel_hi:[1,0]
	v_pk_mul_f32 v[20:21], v[20:21], v[182:183] op_sel_hi:[1,0]
	v_pk_mul_f32 v[18:19], v[18:19], v[182:183] op_sel_hi:[1,0]
	v_pk_mul_f32 v[16:17], v[16:17], v[182:183] op_sel_hi:[1,0]
	v_pk_mul_f32 v[14:15], v[14:15], v[182:183] op_sel_hi:[1,0]
	v_pk_mul_f32 v[12:13], v[12:13], v[182:183] op_sel_hi:[1,0]
	v_pk_mul_f32 v[10:11], v[10:11], v[182:183] op_sel_hi:[1,0]
	v_pk_mul_f32 v[8:9], v[8:9], v[182:183] op_sel_hi:[1,0]
	v_pk_mul_f32 v[6:7], v[6:7], v[182:183] op_sel_hi:[1,0]
	v_pk_mul_f32 v[4:5], v[4:5], v[182:183] op_sel_hi:[1,0]
	v_pk_mul_f32 v[2:3], v[2:3], v[182:183] op_sel_hi:[1,0]
	v_pk_mul_f32 v[0:1], v[0:1], v[182:183] op_sel_hi:[1,0]
	v_mul_f32_e32 v159, v159, v182
